# GEMM K loops: no lgkmcnt(0) drain in front of the two inner barriers (next-step fragment reads stay in flight across the barrier; counted waits at their consumers)
# speedup vs baseline: 1.0086x; 1.0044x over previous
; #define G_HALF(pl, ql, ps, qs, kt_) { const int k4_ = min((kt_) + 4, nk - 1); \
;         SB G_LOAD(pl, ql, k4_) F_LOAD(fa1, fb1, cur, 1) SB G_MFMA(fa0, fb0) SB G_STORE(ps, qs, wr) F_LOAD(fa0, fb0, nxt, 0) SB G_MFMA(fa1, fb1) SB \
;         __syncthreads(); { const int t_ = cur; cur = nxt; nxt = wr; wr = t_; } }
; #define G_HALF(pl, ql, ps, qs, kt_) { const int k4_ = min((kt_) + 4, nk - 1); \
;         SB R_BURST1(fb0, fb1, cur, 1, pl, ql, k4_, ps, qs, wr) R_BURST2(fb1, fb0, nxt, 0, ps, qs, wr) \
;         __syncthreads(); { const int t_ = cur; cur = nxt; nxt = wr; wr = t_; } }
; #define G_HALF(pl, ql, ps, qs, kt_) { const int k4_ = min((kt_) + 4, nk - 1); \
;         SB R_BURST1(fb0, fb1, cur, 1, pl, ql, k4_, ps, qs, wr) R_BURST2(fb1, fb0, nxt, 0, ps, qs, wr) \
;         __syncthreads(); { const int t_ = cur; cur = nxt; nxt = wr; wr = t_; } }
;     ...
; #pragma unroll 1
;     for (; kt + 3 <= nk; kt += 3) {
;         G_HALF(p1, q1, p2, q2, kt)
;         G_HALF(p2, q2, p0, q0, kt + 1)
;         G_HALF(p0, q0, p1, q1, kt + 2)
;     }
.LBB0_218:
	s_waitcnt lgkmcnt(1)
	s_nop 0
	v_mfma_f32_32x32x16_bf16 v[112:127], v[144:147], v[184:187], v[112:127]
	ds_read_b128 v[220:223], v204 offset:22560
	s_waitcnt vmcnt(7)
	ds_write_b128 v196, v[172:175]
	s_waitcnt lgkmcnt(2)
	v_mfma_f32_32x32x16_bf16 v[48:63], v[144:147], v[128:131], v[48:63]
	ds_read_b128 v[172:175], v211 offset:2080
	global_load_dwordx4 v[144:147], v250, s[98:99] offset:256
	v_mfma_f32_32x32x16_bf16 v[96:111], v[140:143], v[184:187], v[96:111]
	ds_read_b128 v[224:227], v204 offset:25120
	s_waitcnt vmcnt(6)
	ds_write_b128 v195, v[180:183]
	v_mfma_f32_32x32x16_bf16 v[32:47], v[140:143], v[128:131], v[32:47]
	ds_read_b128 v[180:183], v211 offset:4640
	global_load_dwordx4 v[140:143], v251, s[98:99] offset:256
	v_mfma_f32_32x32x16_bf16 v[80:95], v[136:139], v[184:187], v[80:95]
	s_waitcnt vmcnt(5)
	ds_write_b128 v193, v[168:171]
	v_mfma_f32_32x32x16_bf16 v[16:31], v[136:139], v[128:131], v[16:31]
	ds_read_b128 v[168:171], v211 offset:7200
	global_load_dwordx4 v[136:139], v250, s[100:101] offset:256
	v_mfma_f32_32x32x16_bf16 v[64:79], v[132:135], v[184:187], v[64:79]
	s_waitcnt vmcnt(4)
	ds_write_b128 v192, v[164:167]
	v_mfma_f32_32x32x16_bf16 v[0:15], v[132:135], v[128:131], v[0:15]
	ds_read_b128 v[132:135], v211 offset:9760
	global_load_dwordx4 v[128:131], v251, s[100:101] offset:256
	s_waitcnt lgkmcnt(7)
	v_mfma_f32_32x32x16_bf16 v[112:127], v[172:175], v[220:223], v[112:127]
	ds_read_b128 v[164:167], v204 offset:63488
	s_waitcnt lgkmcnt(7)
	v_mfma_f32_32x32x16_bf16 v[48:63], v[172:175], v[224:227], v[48:63]
	ds_read_b128 v[172:175], v211 offset:43008
	s_waitcnt lgkmcnt(6)
	v_mfma_f32_32x32x16_bf16 v[96:111], v[180:183], v[220:223], v[96:111]
	ds_read_b128 v[184:187], v205 offset:43520
	v_mfma_f32_32x32x16_bf16 v[32:47], v[180:183], v[224:227], v[32:47]
	ds_read_b128 v[180:183], v211 offset:45568
	s_waitcnt lgkmcnt(6)
	v_mfma_f32_32x32x16_bf16 v[80:95], v[168:171], v[220:223], v[80:95]
	v_mfma_f32_32x32x16_bf16 v[16:31], v[168:171], v[224:227], v[16:31]
	ds_read_b128 v[168:171], v211 offset:48128
	s_waitcnt lgkmcnt(5)
	v_mfma_f32_32x32x16_bf16 v[64:79], v[132:135], v[220:223], v[64:79]
	v_mfma_f32_32x32x16_bf16 v[0:15], v[132:135], v[224:227], v[0:15]
	ds_read_b128 v[132:135], v211 offset:50688
	s_barrier
	s_waitcnt lgkmcnt(4)
	v_mfma_f32_32x32x16_bf16 v[112:127], v[172:175], v[164:167], v[112:127]
	ds_read_b128 v[220:223], v204 offset:63520
	ds_write_b128 v210, v[160:163] offset:2048
	s_waitcnt lgkmcnt(5)
	v_mfma_f32_32x32x16_bf16 v[48:63], v[172:175], v[184:187], v[48:63]
	global_load_dwordx4 v[172:175], v250, s[98:99] offset:320
	ds_read_b128 v[160:163], v211 offset:43040
	s_waitcnt lgkmcnt(5)
	v_mfma_f32_32x32x16_bf16 v[96:111], v[180:183], v[164:167], v[96:111]
	ds_read_b128 v[224:227], v205 offset:43552
	ds_write_b128 v210, v[156:159] offset:12288
	v_mfma_f32_32x32x16_bf16 v[32:47], v[180:183], v[184:187], v[32:47]
	global_load_dwordx4 v[180:183], v251, s[98:99] offset:320
	ds_read_b128 v[156:159], v211 offset:45600
	s_waitcnt lgkmcnt(7)
	v_mfma_f32_32x32x16_bf16 v[80:95], v[168:171], v[164:167], v[80:95]
	ds_write_b128 v210, v[148:151] offset:22528
	v_mfma_f32_32x32x16_bf16 v[16:31], v[168:171], v[184:187], v[16:31]
	global_load_dwordx4 v[168:171], v250, s[100:101] offset:320
	ds_read_b128 v[148:151], v211 offset:48160
	s_waitcnt lgkmcnt(8)
	v_mfma_f32_32x32x16_bf16 v[64:79], v[132:135], v[164:167], v[64:79]
	s_waitcnt vmcnt(7)
	ds_write_b128 v210, v[152:155] offset:32768
	v_mfma_f32_32x32x16_bf16 v[0:15], v[132:135], v[184:187], v[0:15]
	global_load_dwordx4 v[164:167], v251, s[100:101] offset:320
	ds_read_b128 v[132:135], v211 offset:50720
	s_waitcnt lgkmcnt(7)
	v_mfma_f32_32x32x16_bf16 v[112:127], v[160:163], v[220:223], v[112:127]
	ds_read_b128 v[152:155], v201
	s_waitcnt lgkmcnt(7)
	v_mfma_f32_32x32x16_bf16 v[48:63], v[160:163], v[224:227], v[48:63]
	ds_read_b128 v[160:163], v197
	s_waitcnt lgkmcnt(6)
	v_mfma_f32_32x32x16_bf16 v[96:111], v[156:159], v[220:223], v[96:111]
	ds_read_b128 v[184:187], v202
	v_mfma_f32_32x32x16_bf16 v[32:47], v[156:159], v[224:227], v[32:47]
	ds_read_b128 v[156:159], v198
	s_waitcnt lgkmcnt(6)
	v_mfma_f32_32x32x16_bf16 v[80:95], v[148:151], v[220:223], v[80:95]
	v_mfma_f32_32x32x16_bf16 v[16:31], v[148:151], v[224:227], v[16:31]
	ds_read_b128 v[148:151], v199
	s_waitcnt lgkmcnt(5)
	v_mfma_f32_32x32x16_bf16 v[64:79], v[132:135], v[220:223], v[64:79]
	v_mfma_f32_32x32x16_bf16 v[0:15], v[132:135], v[224:227], v[0:15]
	ds_read_b128 v[132:135], v200
	s_barrier
; #define G_LOAD(pr, qr, kt_) if (MODE != 1) { _Pragma("unroll") for (int r = 0; r < NP; ++r) pr[r] = *(const u32x4*)(pp + (size_t)(r * 128) * ldp + (kt_) * BK); \
;                               _Pragma("unroll") for (int r = 0; r < NQ; ++r) qr[r] = *(const u32x4*)(qp + (size_t)(r * 128) * ldq + (kt_) * BK); }
; #define G_STORE(pr, qr, so_) { unsigned char* w_ = wP + (so_); \
;                               _Pragma("unroll") for (int r = 0; r < NP; ++r) *(u32x4*)(w_ + r * 128 * LROW) = pr[r]; \
;                               _Pragma("unroll") for (int r = 0; r < NQ; ++r) *(u32x4*)(w_ + BI * LROW + r * 128 * LROW) = qr[r]; }
; #define F_LOAD(fa, fb, so_, ks_) { _Pragma("unroll") for (int it = 0; it < WI; ++it) fa[it] = *(const bf16x8*)(rP + (so_) + it * 32 * LROW + (ks_) * 32); \
;                                   _Pragma("unroll") for (int jt = 0; jt < 2; ++jt) fb[jt] = *(const bf16x8*)(rQ + (so_) + jt * 32 * LROW + (ks_) * 32); }
; #define G_LOAD(pr, qr, kt_) if (MODE != 1) { _Pragma("unroll") for (int r = 0; r < NP; ++r) pr[r] = *(const u32x4*)(pp + (size_t)(r * 128) * ldp + (kt_) * BK); \
;                               _Pragma("unroll") for (int r = 0; r < NQ; ++r) qr[r] = *(const u32x4*)(qp + (size_t)(r * 128) * ldq + (kt_) * BK); }
;     ...
;     if (MODE == 1) {
; #pragma unroll
;         for (int r = 0; r < NP; ++r) { p0[r] = *(const u32x4*)(pp + (size_t)(r * 128) * ldp); p1[r] = p0[r]; p2[r] = p0[r]; }
; #pragma unroll
;         for (int r = 0; r < NQ; ++r) { q0[r] = *(const u32x4*)(qp + (size_t)(r * 128) * ldq); q1[r] = q0[r]; q2[r] = q0[r]; }
;     }
;     G_LOAD(p0, q0, 0)
;     G_LOAD(p1, q1, 1)
;     G_LOAD(p2, q2, 2)
;     G_STORE(p0, q0, 0)
;     G_LOAD(p0, q0, 3)
;     G_STORE(p1, q1, STAGE)
;     __syncthreads();
;     F_LOAD(fa0, fb0, 0, 0)
;     int cur = 0, nxt = STAGE, wr = 2 * STAGE;
;     int kt = 0;
; #pragma unroll 1
;     for (; kt + 3 <= nk; kt += 3) {
;         G_HALF(p1, q1, p2, q2, kt)
;         G_HALF(p2, q2, p0, q0, kt + 1)
;         G_HALF(p0, q0, p1, q1, kt + 2)
;     }
;     if (kt < nk) G_HALF(p1, q1, p2, q2, kt)
;     if (kt + 1 < nk) G_HALF(p2, q2, p0, q0, kt + 1)
	s_waitcnt lgkmcnt(4)
	v_mfma_f32_32x32x16_bf16 v[112:127], v[160:163], v[152:155], v[112:127]
	ds_read_b128 v[220:223], v203
	s_waitcnt vmcnt(7)
	ds_write_b128 v210, v[144:147] offset:43008
	s_waitcnt lgkmcnt(5)
	v_mfma_f32_32x32x16_bf16 v[48:63], v[160:163], v[184:187], v[48:63]
	global_load_dwordx4 v[160:163], v250, s[98:99] offset:384
	ds_read_b128 v[144:147], v206
	s_waitcnt lgkmcnt(5)
	v_mfma_f32_32x32x16_bf16 v[96:111], v[156:159], v[152:155], v[96:111]
	ds_read_b128 v[224:227], v207
	s_waitcnt vmcnt(7)
	ds_write_b128 v210, v[140:143] offset:53248
	v_mfma_f32_32x32x16_bf16 v[32:47], v[156:159], v[184:187], v[32:47]
	global_load_dwordx4 v[156:159], v251, s[98:99] offset:384
	ds_read_b128 v[140:143], v216
	s_waitcnt lgkmcnt(7)
	v_mfma_f32_32x32x16_bf16 v[80:95], v[148:151], v[152:155], v[80:95]
	s_waitcnt vmcnt(7)
	ds_write_b128 v210, v[136:139] offset:63488
	v_mfma_f32_32x32x16_bf16 v[16:31], v[148:151], v[184:187], v[16:31]
	global_load_dwordx4 v[148:151], v250, s[100:101] offset:384
	ds_read_b128 v[136:139], v217
	s_waitcnt lgkmcnt(8)
	v_mfma_f32_32x32x16_bf16 v[64:79], v[132:135], v[152:155], v[64:79]
	s_waitcnt vmcnt(7)
	ds_write_b128 v194, v[128:131]
	v_mfma_f32_32x32x16_bf16 v[0:15], v[132:135], v[184:187], v[0:15]
	ds_read_b128 v[132:135], v218
	global_load_dwordx4 v[152:155], v251, s[100:101] offset:384
	s_waitcnt lgkmcnt(7)
	v_mfma_f32_32x32x16_bf16 v[112:127], v[144:147], v[220:223], v[112:127]
	ds_read_b128 v[184:187], v204 offset:22528
	s_waitcnt lgkmcnt(7)
	v_mfma_f32_32x32x16_bf16 v[48:63], v[144:147], v[224:227], v[48:63]
	ds_read_b128 v[144:147], v211 offset:2048
	s_waitcnt lgkmcnt(6)
	v_mfma_f32_32x32x16_bf16 v[96:111], v[140:143], v[220:223], v[96:111]
	ds_read_b128 v[128:131], v204 offset:25088
	v_mfma_f32_32x32x16_bf16 v[32:47], v[140:143], v[224:227], v[32:47]
	ds_read_b128 v[140:143], v211 offset:4608
	s_waitcnt lgkmcnt(6)
	v_mfma_f32_32x32x16_bf16 v[80:95], v[136:139], v[220:223], v[80:95]
	v_mfma_f32_32x32x16_bf16 v[16:31], v[136:139], v[224:227], v[16:31]
	ds_read_b128 v[136:139], v211 offset:7168
	s_waitcnt lgkmcnt(5)
	v_mfma_f32_32x32x16_bf16 v[64:79], v[132:135], v[220:223], v[64:79]
	v_mfma_f32_32x32x16_bf16 v[0:15], v[132:135], v[224:227], v[0:15]
	ds_read_b128 v[132:135], v211 offset:9728
	s_add_i32 s5, s5, 3
	v_add_u32_e32 v250, 0xc0, v250
	s_cmp_lt_u32 s5, 30
	v_add_u32_e32 v251, 0xc0, v251
	s_waitcnt lgkmcnt(0)
	s_barrier
	s_cbranch_scc1 .LBB0_218
	s_add_i32 s5, s8, 0xfffff700
	v_mfma_f32_32x32x16_bf16 v[112:127], v[144:147], v[184:187], v[112:127]
	ds_read_b128 v[200:203], v204 offset:22560
	s_waitcnt vmcnt(7)
	ds_write_b128 v196, v[172:175]
	ds_read_b128 v[172:175], v211 offset:2080
	v_mfma_f32_32x32x16_bf16 v[96:111], v[140:143], v[184:187], v[96:111]
	ds_read_b128 v[176:179], v204 offset:25120
	s_waitcnt vmcnt(6)
	ds_write_b128 v195, v[180:183]
	ds_read_b128 v[180:183], v211 offset:4640
	v_mfma_f32_32x32x16_bf16 v[80:95], v[136:139], v[184:187], v[80:95]
	s_waitcnt vmcnt(5)
	ds_write_b128 v193, v[168:171]
	ds_read_b128 v[168:171], v211 offset:7200
	v_mfma_f32_32x32x16_bf16 v[64:79], v[132:135], v[184:187], v[64:79]
	s_waitcnt vmcnt(4)
	ds_write_b128 v192, v[164:167]
	ds_read_b128 v[164:167], v211 offset:9760
	s_waitcnt lgkmcnt(7)
	v_mfma_f32_32x32x16_bf16 v[112:127], v[172:175], v[200:203], v[112:127]
	ds_read_b128 v[216:219], v204 offset:63488
	ds_read_b128 v[184:187], v211 offset:43008
	s_waitcnt lgkmcnt(6)
	v_mfma_f32_32x32x16_bf16 v[96:111], v[180:183], v[200:203], v[96:111]
	ds_read_b128 v[188:191], v205 offset:43520
	ds_read_b128 v[192:195], v211 offset:45568
	s_waitcnt lgkmcnt(6)
	v_mfma_f32_32x32x16_bf16 v[80:95], v[168:171], v[200:203], v[80:95]
	ds_read_b128 v[196:199], v211 offset:48128
	s_waitcnt lgkmcnt(5)
	v_mfma_f32_32x32x16_bf16 v[64:79], v[164:167], v[200:203], v[64:79]
	ds_read_b128 v[200:203], v211 offset:50688
	s_waitcnt lgkmcnt(0)
	s_barrier
	v_mfma_f32_32x32x16_bf16 v[112:127], v[184:187], v[216:219], v[112:127]
	ds_read_b128 v[220:223], v204 offset:63520
	s_waitcnt vmcnt(3)
	ds_write_b128 v210, v[160:163] offset:2048
	ds_read_b128 v[160:163], v211 offset:43040
	v_mfma_f32_32x32x16_bf16 v[96:111], v[192:195], v[216:219], v[96:111]
	ds_read_b128 v[204:207], v205 offset:43552
	s_waitcnt vmcnt(2)
	ds_write_b128 v210, v[156:159] offset:12288
	ds_read_b128 v[156:159], v211 offset:45600
	v_mfma_f32_32x32x16_bf16 v[80:95], v[196:199], v[216:219], v[80:95]
	s_waitcnt vmcnt(1)
	ds_write_b128 v210, v[148:151] offset:22528
	ds_read_b128 v[148:151], v211 offset:48160
	v_mfma_f32_32x32x16_bf16 v[64:79], v[200:203], v[216:219], v[64:79]
	s_waitcnt vmcnt(0)
	ds_write_b128 v210, v[152:155] offset:32768
	ds_read_b128 v[152:155], v211 offset:50720
	s_waitcnt lgkmcnt(7)
	v_mfma_f32_32x32x16_bf16 v[112:127], v[160:163], v[220:223], v[112:127]
	s_waitcnt lgkmcnt(4)
	v_mfma_f32_32x32x16_bf16 v[96:111], v[156:159], v[220:223], v[96:111]
	s_waitcnt lgkmcnt(2)
	v_mfma_f32_32x32x16_bf16 v[80:95], v[148:151], v[220:223], v[80:95]
	s_waitcnt lgkmcnt(0)
	v_mfma_f32_32x32x16_bf16 v[64:79], v[152:155], v[220:223], v[64:79]
	v_mov_b32_e32 v216, v212
	s_barrier
; DI u32x2 pk4(float a, float b, float c, float d) { u32x2 r; r.x = pk2(a, b); r.y = pk2(c, d); return r; }
; template <int WI, int WGJ, class GetF, class FinF>
; DI void staged_rows(unsigned char* lds, int tid, GetF get, FinF fin) {
;     ...
;     const int lane = tid & 63, wid = tid >> 6, wi = wid / WGJ, wj = wid % WGJ, h = lane >> 5, ln = lane & 31;
; #pragma unroll
;     for (int jt = 0; jt < 2; ++jt) {
;         unsigned char* wrow = lds + (wj * 32 + ln) * RS + (wi * WI * 32 + 4 * h) * 2;
; #pragma unroll
;         for (int it = 0; it < WI; ++it)
; #pragma unroll
;             for (int g = 0; g < 4; ++g) *(u32x2*)(wrow + (it * 32 + 8 * g) * 2) = get(it, jt, g);
;         __syncthreads();
; template <int MODE>
; DI void phase1(const Params& p, unsigned char* smem, int tid) {
;     ...
;             const int lane = te & 63, wid = te >> 6, wi = wid >> 2, h = lane >> 5; (void)lane;
;             bf16_t* fvt = (bf16_t*)(ws + OFF_FVT);
;             staged_rows<4, 4>(lds, te,
;                 [&](int it, int jt, int g) { const f32x4 rs = *(const f32x4*)(rstd + tt * 256 + wi * 128 + it * 32 + 8 * g + 4 * h);
;                     return pk4(acc[it][jt][4 * g] * rs[0], acc[it][jt][4 * g + 1] * rs[1], acc[it][jt][4 * g + 2] * rs[2], acc[it][jt][4 * g + 3] * rs[3]); },
	s_lshl_b32 s10, s4, 8
	v_ashrrev_i32_e32 v208, 6, v216
	v_lshrrev_b32_e32 v210, 30, v208
	v_add_u32_e32 v210, v208, v210
	v_and_b32_e32 v211, 0x7ffffc, v210
	v_sub_u32_e32 v208, v208, v211
	v_and_b32_e32 v211, 31, v216
	v_lshl_or_b32 v208, v208, 5, v211
	v_lshlrev_b32_e32 v210, 6, v210
	v_mul_lo_u32 v208, v208, s50
	v_and_b32_e32 v210, 0xffffff00, v210
	v_lshrrev_b32_e32 v211, 2, v216
	v_and_b32_e32 v211, 8, v211
	v_add3_u32 v208, 0, v208, v210
	s_ashr_i32 s11, s10, 31
	v_add_u32_e32 v217, v208, v211
	s_lshl_b64 s[12:13], s[10:11], 2
	v_ashrrev_i32_e32 v208, 1, v216
	s_add_u32 s12, s40, s12
	v_and_b32_e32 v210, 0xffffff80, v208
	s_addc_u32 s13, s41, s13
	v_ashrrev_i32_e32 v211, 31, v210
	v_lshrrev_b32_e32 v208, 1, v216
	v_lshl_add_u64 v[210:211], v[210:211], 2, s[12:13]
	v_and_b32_e32 v208, 16, v208
	v_lshl_add_u64 v[210:211], v[210:211], 0, v[208:209]
	global_load_dwordx4 v[222:225], v[210:211], off
	global_load_dwordx4 v[226:229], v[210:211], off offset:32
	global_load_dwordx4 v[230:233], v[210:211], off offset:64
	global_load_dwordx4 v[234:237], v[210:211], off offset:96
	global_load_dwordx4 v[238:241], v[210:211], off offset:128
	global_load_dwordx4 v[242:245], v[210:211], off offset:160
	global_load_dwordx4 v[248:251], v[210:211], off offset:192
	global_load_dwordx4 v[252:255], v[210:211], off offset:224
	s_mov_b32 s9, 0
	s_waitcnt vmcnt(7)
	v_pk_mul_f32 v[112:113], v[112:113], v[222:223]
	v_pk_mul_f32 v[114:115], v[114:115], v[224:225]
	v_cvt_pk_bf16_f32 v218, v112, v113
	v_cvt_pk_bf16_f32 v219, v114, v115
	s_waitcnt vmcnt(6)
	v_pk_mul_f32 v[112:113], v[116:117], v[226:227]
	v_pk_mul_f32 v[114:115], v[118:119], v[228:229]
	v_cvt_pk_bf16_f32 v116, v112, v113
	v_cvt_pk_bf16_f32 v117, v114, v115
	v_add_u32_e32 v112, 0x800, v217
	ds_write2_b64 v112, v[218:219], v[116:117] offset1:2
	s_waitcnt vmcnt(5)
	v_pk_mul_f32 v[114:115], v[120:121], v[230:231]
	v_pk_mul_f32 v[116:117], v[122:123], v[232:233]
	v_cvt_pk_bf16_f32 v118, v114, v115
	v_cvt_pk_bf16_f32 v119, v116, v117
	s_waitcnt vmcnt(4)
	v_pk_mul_f32 v[114:115], v[124:125], v[234:235]
	v_pk_mul_f32 v[116:117], v[126:127], v[236:237]
	v_cvt_pk_bf16_f32 v114, v114, v115
	v_cvt_pk_bf16_f32 v115, v116, v117
	ds_write2_b64 v112, v[118:119], v[114:115] offset0:4 offset1:6
	s_waitcnt vmcnt(3)
	v_pk_mul_f32 v[96:97], v[96:97], v[238:239]
	v_pk_mul_f32 v[98:99], v[98:99], v[240:241]
	v_cvt_pk_bf16_f32 v114, v96, v97
	v_cvt_pk_bf16_f32 v115, v98, v99
	s_waitcnt vmcnt(2)
	v_pk_mul_f32 v[96:97], v[100:101], v[242:243]
	v_pk_mul_f32 v[98:99], v[102:103], v[244:245]
	v_cvt_pk_bf16_f32 v96, v96, v97
	v_cvt_pk_bf16_f32 v97, v98, v99
	ds_write2_b64 v112, v[114:115], v[96:97] offset0:8 offset1:10
	s_waitcnt vmcnt(1)
	v_pk_mul_f32 v[96:97], v[104:105], v[248:249]
	v_pk_mul_f32 v[98:99], v[106:107], v[250:251]
	v_cvt_pk_bf16_f32 v100, v96, v97
	v_cvt_pk_bf16_f32 v101, v98, v99
	s_waitcnt vmcnt(0)
	v_pk_mul_f32 v[96:97], v[108:109], v[252:253]
	v_pk_mul_f32 v[98:99], v[110:111], v[254:255]
	v_cvt_pk_bf16_f32 v96, v96, v97
	v_cvt_pk_bf16_f32 v97, v98, v99
	ds_write2_b64 v112, v[100:101], v[96:97] offset0:12 offset1:14
	global_load_dwordx4 v[222:225], v[210:211], off offset:256
	global_load_dwordx4 v[226:229], v[210:211], off offset:288
	global_load_dwordx4 v[230:233], v[210:211], off offset:320
	global_load_dwordx4 v[234:237], v[210:211], off offset:352
	global_load_dwordx4 v[238:241], v[210:211], off offset:384
	global_load_dwordx4 v[242:245], v[210:211], off offset:416
	global_load_dwordx4 v[248:251], v[210:211], off offset:448
	global_load_dwordx4 v[252:255], v[210:211], off offset:480
	s_waitcnt vmcnt(7)
	v_pk_mul_f32 v[80:81], v[80:81], v[222:223]
	v_pk_mul_f32 v[82:83], v[82:83], v[224:225]
	v_cvt_pk_bf16_f32 v96, v80, v81
	v_cvt_pk_bf16_f32 v97, v82, v83
	s_waitcnt vmcnt(6)
	v_pk_mul_f32 v[80:81], v[84:85], v[226:227]
	v_pk_mul_f32 v[82:83], v[86:87], v[228:229]
	v_cvt_pk_bf16_f32 v80, v80, v81
	v_cvt_pk_bf16_f32 v81, v82, v83
	ds_write2_b64 v112, v[96:97], v[80:81] offset0:16 offset1:18
	s_waitcnt vmcnt(5)
	v_pk_mul_f32 v[80:81], v[88:89], v[230:231]
	v_pk_mul_f32 v[82:83], v[90:91], v[232:233]
	v_cvt_pk_bf16_f32 v84, v80, v81
	v_cvt_pk_bf16_f32 v85, v82, v83
	s_waitcnt vmcnt(4)
	v_pk_mul_f32 v[80:81], v[92:93], v[234:235]
	v_pk_mul_f32 v[82:83], v[94:95], v[236:237]
	v_cvt_pk_bf16_f32 v80, v80, v81
	v_cvt_pk_bf16_f32 v81, v82, v83
	ds_write2_b64 v112, v[84:85], v[80:81] offset0:20 offset1:22
	s_waitcnt vmcnt(3)
	v_pk_mul_f32 v[64:65], v[64:65], v[238:239]
	v_pk_mul_f32 v[66:67], v[66:67], v[240:241]
	v_cvt_pk_bf16_f32 v80, v64, v65
	v_cvt_pk_bf16_f32 v81, v66, v67
	s_waitcnt vmcnt(2)
	v_pk_mul_f32 v[64:65], v[68:69], v[242:243]
	v_pk_mul_f32 v[66:67], v[70:71], v[244:245]
	v_cvt_pk_bf16_f32 v64, v64, v65
	v_cvt_pk_bf16_f32 v65, v66, v67
	ds_write2_b64 v112, v[80:81], v[64:65] offset0:24 offset1:26
	s_waitcnt vmcnt(1)
	v_pk_mul_f32 v[64:65], v[72:73], v[248:249]
	v_pk_mul_f32 v[66:67], v[74:75], v[250:251]
	v_cvt_pk_bf16_f32 v68, v64, v65
	v_cvt_pk_bf16_f32 v69, v66, v67
	s_waitcnt vmcnt(0)
	v_pk_mul_f32 v[64:65], v[76:77], v[252:253]
	v_pk_mul_f32 v[66:67], v[78:79], v[254:255]
	v_cvt_pk_bf16_f32 v64, v64, v65
	v_cvt_pk_bf16_f32 v65, v66, v67
	ds_write2_b64 v112, v[68:69], v[64:65] offset0:28 offset1:30
	s_waitcnt lgkmcnt(0)
	s_barrier
	s_branch .LBB0_221

; #define G_LOAD(pr, qr, kt_) if (MODE != 1) { _Pragma("unroll") for (int r = 0; r < NP; ++r) pr[r] = *(const u32x4*)(pp + (size_t)(r * 128) * ldp + (kt_) * BK); \
;                               _Pragma("unroll") for (int r = 0; r < NQ; ++r) qr[r] = *(const u32x4*)(qp + (size_t)(r * 128) * ldq + (kt_) * BK); }
; #define G_STORE(pr, qr, so_) { unsigned char* w_ = wP + (so_); \
;                               _Pragma("unroll") for (int r = 0; r < NP; ++r) *(u32x4*)(w_ + r * 128 * LROW) = pr[r]; \
;                               _Pragma("unroll") for (int r = 0; r < NQ; ++r) *(u32x4*)(w_ + BI * LROW + r * 128 * LROW) = qr[r]; }
; #define F_LOAD(fa, fb, so_, ks_) { _Pragma("unroll") for (int it = 0; it < WI; ++it) fa[it] = *(const bf16x8*)(rP + (so_) + it * 32 * LROW + (ks_) * 32); \
;                                   _Pragma("unroll") for (int jt = 0; jt < 2; ++jt) fb[jt] = *(const bf16x8*)(rQ + (so_) + jt * 32 * LROW + (ks_) * 32); }
; #define G_LOAD(pr, qr, kt_) if (MODE != 1) { _Pragma("unroll") for (int r = 0; r < NP; ++r) pr[r] = *(const u32x4*)(pp + (size_t)(r * 128) * ldp + (kt_) * BK); \
;                               _Pragma("unroll") for (int r = 0; r < NQ; ++r) qr[r] = *(const u32x4*)(qp + (size_t)(r * 128) * ldq + (kt_) * BK); }
; #define G_STORE(pr, qr, so_) { unsigned char* w_ = wP + (so_); \
;                               _Pragma("unroll") for (int r = 0; r < NP; ++r) *(u32x4*)(w_ + r * 128 * LROW) = pr[r]; \
;                               _Pragma("unroll") for (int r = 0; r < NQ; ++r) *(u32x4*)(w_ + BI * LROW + r * 128 * LROW) = qr[r]; }
;     ...
;     if (MODE == 1) {
; #pragma unroll
;         for (int r = 0; r < NP; ++r) { p0[r] = *(const u32x4*)(pp + (size_t)(r * 128) * ldp); p1[r] = p0[r]; p2[r] = p0[r]; }
; #pragma unroll
;         for (int r = 0; r < NQ; ++r) { q0[r] = *(const u32x4*)(qp + (size_t)(r * 128) * ldq); q1[r] = q0[r]; q2[r] = q0[r]; }
;     }
;     G_LOAD(p0, q0, 0)
;     G_LOAD(p1, q1, 1)
;     G_LOAD(p2, q2, 2)
;     G_STORE(p0, q0, 0)
;     G_LOAD(p0, q0, 3)
;     G_STORE(p1, q1, STAGE)
;     __syncthreads();
;     F_LOAD(fa0, fb0, 0, 0)
;     int cur = 0, nxt = STAGE, wr = 2 * STAGE;
;     int kt = 0;
; #pragma unroll 1
;     for (; kt + 3 <= nk; kt += 3) {
;         G_HALF(p1, q1, p2, q2, kt)
;         G_HALF(p2, q2, p0, q0, kt + 1)
;         G_HALF(p0, q0, p1, q1, kt + 2)
;     }
.LBB0_230:
	s_waitcnt lgkmcnt(1)
	v_mfma_f32_32x32x16_bf16 v[112:127], v[180:183], v[160:163], v[112:127]
	ds_read_b128 v[220:223], v194 offset:22560
	s_waitcnt vmcnt(7)
	ds_write_b128 v200, v[156:159]
	s_waitcnt lgkmcnt(2)
	v_mfma_f32_32x32x16_bf16 v[48:63], v[180:183], v[164:167], v[48:63]
	global_load_dwordx4 v[180:183], v250, s[98:99] offset:256
	ds_read_b128 v[156:159], v193 offset:2080
	v_mfma_f32_32x32x16_bf16 v[96:111], v[176:179], v[160:163], v[96:111]
	ds_read_b128 v[224:227], v194 offset:25120
	s_waitcnt vmcnt(6)
	ds_write_b128 v199, v[152:155]
	v_mfma_f32_32x32x16_bf16 v[32:47], v[176:179], v[164:167], v[32:47]
	global_load_dwordx4 v[176:179], v251, s[98:99] offset:256
	ds_read_b128 v[152:155], v193 offset:4640
	v_mfma_f32_32x32x16_bf16 v[80:95], v[172:175], v[160:163], v[80:95]
	s_waitcnt vmcnt(5)
	ds_write_b128 v198, v[148:151]
	v_mfma_f32_32x32x16_bf16 v[16:31], v[172:175], v[164:167], v[16:31]
	global_load_dwordx4 v[172:175], v250, s[100:101] offset:256
	ds_read_b128 v[148:151], v193 offset:7200
	v_mfma_f32_32x32x16_bf16 v[64:79], v[168:171], v[160:163], v[64:79]
	s_waitcnt vmcnt(4)
	ds_write_b128 v197, v[144:147]
	v_mfma_f32_32x32x16_bf16 v[0:15], v[168:171], v[164:167], v[0:15]
	global_load_dwordx4 v[160:163], v251, s[100:101] offset:256
	ds_read_b128 v[144:147], v193 offset:9760
	s_waitcnt lgkmcnt(7)
	v_mfma_f32_32x32x16_bf16 v[112:127], v[156:159], v[220:223], v[112:127]
	ds_read_b128 v[164:167], v194 offset:63488
	s_waitcnt lgkmcnt(7)
	v_mfma_f32_32x32x16_bf16 v[48:63], v[156:159], v[224:227], v[48:63]
	ds_read_b128 v[156:159], v193 offset:43008
	s_waitcnt lgkmcnt(6)
	v_mfma_f32_32x32x16_bf16 v[96:111], v[152:155], v[220:223], v[96:111]
	ds_read_b128 v[168:171], v196 offset:43520
	v_mfma_f32_32x32x16_bf16 v[32:47], v[152:155], v[224:227], v[32:47]
	ds_read_b128 v[152:155], v193 offset:45568
	s_waitcnt lgkmcnt(6)
	v_mfma_f32_32x32x16_bf16 v[80:95], v[148:151], v[220:223], v[80:95]
	v_mfma_f32_32x32x16_bf16 v[16:31], v[148:151], v[224:227], v[16:31]
	ds_read_b128 v[148:151], v193 offset:48128
	s_waitcnt lgkmcnt(5)
	v_mfma_f32_32x32x16_bf16 v[64:79], v[144:147], v[220:223], v[64:79]
	v_mfma_f32_32x32x16_bf16 v[0:15], v[144:147], v[224:227], v[0:15]
	ds_read_b128 v[144:147], v193 offset:50688
	s_barrier
	s_waitcnt lgkmcnt(4)
	v_mfma_f32_32x32x16_bf16 v[112:127], v[156:159], v[164:167], v[112:127]
	ds_read_b128 v[220:223], v194 offset:63520
	ds_write_b128 v192, v[140:143] offset:2048
	s_waitcnt lgkmcnt(5)
	v_mfma_f32_32x32x16_bf16 v[48:63], v[156:159], v[168:171], v[48:63]
	global_load_dwordx4 v[156:159], v250, s[98:99] offset:320
	ds_read_b128 v[140:143], v193 offset:43040
	s_waitcnt lgkmcnt(5)
	v_mfma_f32_32x32x16_bf16 v[96:111], v[152:155], v[164:167], v[96:111]
	ds_read_b128 v[224:227], v196 offset:43552
	ds_write_b128 v192, v[136:139] offset:12288
	v_mfma_f32_32x32x16_bf16 v[32:47], v[152:155], v[168:171], v[32:47]
	global_load_dwordx4 v[152:155], v251, s[98:99] offset:320
	ds_read_b128 v[136:139], v193 offset:45600
	s_waitcnt lgkmcnt(7)
	v_mfma_f32_32x32x16_bf16 v[80:95], v[148:151], v[164:167], v[80:95]
	ds_write_b128 v192, v[132:135] offset:22528
	v_mfma_f32_32x32x16_bf16 v[16:31], v[148:151], v[168:171], v[16:31]
	global_load_dwordx4 v[148:151], v250, s[100:101] offset:320
	ds_read_b128 v[132:135], v193 offset:48160
	s_waitcnt lgkmcnt(8)
	v_mfma_f32_32x32x16_bf16 v[64:79], v[144:147], v[164:167], v[64:79]
	s_waitcnt vmcnt(7)
	ds_write_b128 v192, v[128:131] offset:32768
	v_mfma_f32_32x32x16_bf16 v[0:15], v[144:147], v[168:171], v[0:15]
	global_load_dwordx4 v[144:147], v251, s[100:101] offset:320
	ds_read_b128 v[128:131], v193 offset:50720
	s_waitcnt lgkmcnt(7)
	v_mfma_f32_32x32x16_bf16 v[112:127], v[140:143], v[220:223], v[112:127]
	ds_read_b128 v[164:167], v202
	s_waitcnt lgkmcnt(7)
	v_mfma_f32_32x32x16_bf16 v[48:63], v[140:143], v[224:227], v[48:63]
	ds_read_b128 v[140:143], v201
	s_waitcnt lgkmcnt(6)
	v_mfma_f32_32x32x16_bf16 v[96:111], v[136:139], v[220:223], v[96:111]
	ds_read_b128 v[168:171], v203
	v_mfma_f32_32x32x16_bf16 v[32:47], v[136:139], v[224:227], v[32:47]
	ds_read_b128 v[136:139], v204
	s_waitcnt lgkmcnt(6)
	v_mfma_f32_32x32x16_bf16 v[80:95], v[132:135], v[220:223], v[80:95]
	v_mfma_f32_32x32x16_bf16 v[16:31], v[132:135], v[224:227], v[16:31]
	ds_read_b128 v[132:135], v205
	s_waitcnt lgkmcnt(5)
	v_mfma_f32_32x32x16_bf16 v[64:79], v[128:131], v[220:223], v[64:79]
	v_mfma_f32_32x32x16_bf16 v[0:15], v[128:131], v[224:227], v[0:15]
	ds_read_b128 v[128:131], v206
	s_barrier
; #define G_LOAD(pr, qr, kt_) if (MODE != 1) { _Pragma("unroll") for (int r = 0; r < NP; ++r) pr[r] = *(const u32x4*)(pp + (size_t)(r * 128) * ldp + (kt_) * BK); \
;                               _Pragma("unroll") for (int r = 0; r < NQ; ++r) qr[r] = *(const u32x4*)(qp + (size_t)(r * 128) * ldq + (kt_) * BK); }
; #define G_STORE(pr, qr, so_) { unsigned char* w_ = wP + (so_); \
;                               _Pragma("unroll") for (int r = 0; r < NP; ++r) *(u32x4*)(w_ + r * 128 * LROW) = pr[r]; \
;                               _Pragma("unroll") for (int r = 0; r < NQ; ++r) *(u32x4*)(w_ + BI * LROW + r * 128 * LROW) = qr[r]; }
; #define F_LOAD(fa, fb, so_, ks_) { _Pragma("unroll") for (int it = 0; it < WI; ++it) fa[it] = *(const bf16x8*)(rP + (so_) + it * 32 * LROW + (ks_) * 32); \
;                                   _Pragma("unroll") for (int jt = 0; jt < 2; ++jt) fb[jt] = *(const bf16x8*)(rQ + (so_) + jt * 32 * LROW + (ks_) * 32); }
; #define G_LOAD(pr, qr, kt_) if (MODE != 1) { _Pragma("unroll") for (int r = 0; r < NP; ++r) pr[r] = *(const u32x4*)(pp + (size_t)(r * 128) * ldp + (kt_) * BK); \
;                               _Pragma("unroll") for (int r = 0; r < NQ; ++r) qr[r] = *(const u32x4*)(qp + (size_t)(r * 128) * ldq + (kt_) * BK); }
;     ...
;     if (MODE == 1) {
; #pragma unroll
;         for (int r = 0; r < NP; ++r) { p0[r] = *(const u32x4*)(pp + (size_t)(r * 128) * ldp); p1[r] = p0[r]; p2[r] = p0[r]; }
; #pragma unroll
;         for (int r = 0; r < NQ; ++r) { q0[r] = *(const u32x4*)(qp + (size_t)(r * 128) * ldq); q1[r] = q0[r]; q2[r] = q0[r]; }
;     }
;     G_LOAD(p0, q0, 0)
;     G_LOAD(p1, q1, 1)
;     G_LOAD(p2, q2, 2)
;     G_STORE(p0, q0, 0)
;     G_LOAD(p0, q0, 3)
;     G_STORE(p1, q1, STAGE)
;     __syncthreads();
;     F_LOAD(fa0, fb0, 0, 0)
;     int cur = 0, nxt = STAGE, wr = 2 * STAGE;
;     int kt = 0;
; #pragma unroll 1
;     for (; kt + 3 <= nk; kt += 3) {
;         G_HALF(p1, q1, p2, q2, kt)
;         G_HALF(p2, q2, p0, q0, kt + 1)
;         G_HALF(p0, q0, p1, q1, kt + 2)
;     }
;     if (kt < nk) G_HALF(p1, q1, p2, q2, kt)
;     if (kt + 1 < nk) G_HALF(p2, q2, p0, q0, kt + 1)
	s_waitcnt lgkmcnt(4)
	v_mfma_f32_32x32x16_bf16 v[112:127], v[140:143], v[164:167], v[112:127]
	ds_read_b128 v[220:223], v207
	s_waitcnt vmcnt(7)
	ds_write_b128 v192, v[180:183] offset:43008
	s_waitcnt lgkmcnt(5)
	v_mfma_f32_32x32x16_bf16 v[48:63], v[140:143], v[168:171], v[48:63]
	global_load_dwordx4 v[140:143], v250, s[98:99] offset:384
	ds_read_b128 v[180:183], v210
	s_waitcnt lgkmcnt(5)
	v_mfma_f32_32x32x16_bf16 v[96:111], v[136:139], v[164:167], v[96:111]
	ds_read_b128 v[224:227], v211
	s_waitcnt vmcnt(7)
	ds_write_b128 v192, v[176:179] offset:53248
	v_mfma_f32_32x32x16_bf16 v[32:47], v[136:139], v[168:171], v[32:47]
	ds_read_b128 v[176:179], v216
	global_load_dwordx4 v[136:139], v251, s[98:99] offset:384
	s_waitcnt lgkmcnt(7)
	v_mfma_f32_32x32x16_bf16 v[80:95], v[132:135], v[164:167], v[80:95]
	s_waitcnt vmcnt(7)
	ds_write_b128 v192, v[172:175] offset:63488
	v_mfma_f32_32x32x16_bf16 v[16:31], v[132:135], v[168:171], v[16:31]
	global_load_dwordx4 v[132:135], v250, s[100:101] offset:384
	ds_read_b128 v[172:175], v217
	s_waitcnt lgkmcnt(8)
	v_mfma_f32_32x32x16_bf16 v[64:79], v[128:131], v[164:167], v[64:79]
	s_waitcnt vmcnt(7)
	ds_write_b128 v195, v[160:163]
	v_mfma_f32_32x32x16_bf16 v[0:15], v[128:131], v[168:171], v[0:15]
	ds_read_b128 v[168:171], v218
	global_load_dwordx4 v[128:131], v251, s[100:101] offset:384
	s_waitcnt lgkmcnt(7)
	v_mfma_f32_32x32x16_bf16 v[112:127], v[180:183], v[220:223], v[112:127]
	ds_read_b128 v[160:163], v194 offset:22528
	s_waitcnt lgkmcnt(7)
	v_mfma_f32_32x32x16_bf16 v[48:63], v[180:183], v[224:227], v[48:63]
	ds_read_b128 v[180:183], v193 offset:2048
	s_waitcnt lgkmcnt(6)
	v_mfma_f32_32x32x16_bf16 v[96:111], v[176:179], v[220:223], v[96:111]
	ds_read_b128 v[164:167], v194 offset:25088
	v_mfma_f32_32x32x16_bf16 v[32:47], v[176:179], v[224:227], v[32:47]
	ds_read_b128 v[176:179], v193 offset:4608
	s_waitcnt lgkmcnt(6)
	v_mfma_f32_32x32x16_bf16 v[80:95], v[172:175], v[220:223], v[80:95]
	v_mfma_f32_32x32x16_bf16 v[16:31], v[172:175], v[224:227], v[16:31]
	ds_read_b128 v[172:175], v193 offset:7168
	s_waitcnt lgkmcnt(5)
	v_mfma_f32_32x32x16_bf16 v[64:79], v[168:171], v[220:223], v[64:79]
	v_mfma_f32_32x32x16_bf16 v[0:15], v[168:171], v[224:227], v[0:15]
	ds_read_b128 v[168:171], v193 offset:9728
	s_add_i32 s5, s5, 3
	v_add_u32_e32 v250, 0xc0, v250
	s_cmp_lt_u32 s5, 30
	v_add_u32_e32 v251, 0xc0, v251
	s_waitcnt lgkmcnt(0)
	s_barrier
	s_cbranch_scc1 .LBB0_230
	v_mfma_f32_32x32x16_bf16 v[112:127], v[180:183], v[160:163], v[112:127]
	ds_read_b128 v[184:187], v194 offset:22560
	s_waitcnt vmcnt(7)
	ds_write_b128 v200, v[156:159]
	v_mfma_f32_32x32x16_bf16 v[48:63], v[180:183], v[164:167], v[48:63]
	ds_read_b128 v[156:159], v193 offset:2080
	v_mfma_f32_32x32x16_bf16 v[96:111], v[176:179], v[160:163], v[96:111]
	ds_read_b128 v[180:183], v194 offset:25120
	s_waitcnt vmcnt(6)
	ds_write_b128 v199, v[152:155]
	v_mfma_f32_32x32x16_bf16 v[32:47], v[176:179], v[164:167], v[32:47]
	ds_read_b128 v[152:155], v193 offset:4640
	v_mfma_f32_32x32x16_bf16 v[80:95], v[172:175], v[160:163], v[80:95]
	s_waitcnt vmcnt(5)
	ds_write_b128 v198, v[148:151]
	v_mfma_f32_32x32x16_bf16 v[16:31], v[172:175], v[164:167], v[16:31]
	ds_read_b128 v[148:151], v193 offset:7200
	v_mfma_f32_32x32x16_bf16 v[64:79], v[168:171], v[160:163], v[64:79]
	s_waitcnt vmcnt(4)
	ds_write_b128 v197, v[144:147]
	v_mfma_f32_32x32x16_bf16 v[0:15], v[168:171], v[164:167], v[0:15]
	ds_read_b128 v[144:147], v193 offset:9760
	s_waitcnt lgkmcnt(7)
	v_mfma_f32_32x32x16_bf16 v[112:127], v[156:159], v[184:187], v[112:127]
	ds_read_b128 v[160:163], v194 offset:63488
	s_waitcnt lgkmcnt(7)
	v_mfma_f32_32x32x16_bf16 v[48:63], v[156:159], v[180:183], v[48:63]
	ds_read_b128 v[156:159], v193 offset:43008
	s_waitcnt lgkmcnt(6)
	v_mfma_f32_32x32x16_bf16 v[96:111], v[152:155], v[184:187], v[96:111]
	ds_read_b128 v[164:167], v196 offset:43520
	v_mfma_f32_32x32x16_bf16 v[32:47], v[152:155], v[180:183], v[32:47]
	ds_read_b128 v[152:155], v193 offset:45568
	s_waitcnt lgkmcnt(6)
	v_mfma_f32_32x32x16_bf16 v[80:95], v[148:151], v[184:187], v[80:95]
	v_mfma_f32_32x32x16_bf16 v[16:31], v[148:151], v[180:183], v[16:31]
	ds_read_b128 v[148:151], v193 offset:48128
	s_waitcnt lgkmcnt(5)
	v_mfma_f32_32x32x16_bf16 v[64:79], v[144:147], v[184:187], v[64:79]
	v_mfma_f32_32x32x16_bf16 v[0:15], v[144:147], v[180:183], v[0:15]
	ds_read_b128 v[144:147], v193 offset:50688
	s_waitcnt lgkmcnt(0)
	s_barrier
	v_mfma_f32_32x32x16_bf16 v[112:127], v[156:159], v[160:163], v[112:127]
	ds_read_b128 v[168:171], v194 offset:63520
	s_waitcnt vmcnt(3)
	ds_write_b128 v192, v[140:143] offset:2048
	v_mfma_f32_32x32x16_bf16 v[48:63], v[156:159], v[164:167], v[48:63]
	ds_read_b128 v[140:143], v193 offset:43040
	v_mfma_f32_32x32x16_bf16 v[96:111], v[152:155], v[160:163], v[96:111]
	ds_read_b128 v[156:159], v196 offset:43552
	s_waitcnt vmcnt(2)
	ds_write_b128 v192, v[136:139] offset:12288
	v_mfma_f32_32x32x16_bf16 v[32:47], v[152:155], v[164:167], v[32:47]
	ds_read_b128 v[136:139], v193 offset:45600
	v_mfma_f32_32x32x16_bf16 v[80:95], v[148:151], v[160:163], v[80:95]
	s_waitcnt vmcnt(1)
	ds_write_b128 v192, v[132:135] offset:22528
	v_mfma_f32_32x32x16_bf16 v[16:31], v[148:151], v[164:167], v[16:31]
	ds_read_b128 v[132:135], v193 offset:48160
	v_mfma_f32_32x32x16_bf16 v[64:79], v[144:147], v[160:163], v[64:79]
	s_waitcnt vmcnt(0)
	ds_write_b128 v192, v[128:131] offset:32768
	v_mfma_f32_32x32x16_bf16 v[0:15], v[144:147], v[164:167], v[0:15]
	ds_read_b128 v[128:131], v193 offset:50720
	s_waitcnt lgkmcnt(7)
	v_mfma_f32_32x32x16_bf16 v[112:127], v[140:143], v[168:171], v[112:127]
	s_waitcnt lgkmcnt(6)
	v_mfma_f32_32x32x16_bf16 v[48:63], v[140:143], v[156:159], v[48:63]
	s_waitcnt lgkmcnt(4)
	v_mfma_f32_32x32x16_bf16 v[96:111], v[136:139], v[168:171], v[96:111]
	v_mfma_f32_32x32x16_bf16 v[32:47], v[136:139], v[156:159], v[32:47]
	s_waitcnt lgkmcnt(2)
	v_mfma_f32_32x32x16_bf16 v[80:95], v[132:135], v[168:171], v[80:95]
	v_mfma_f32_32x32x16_bf16 v[16:31], v[132:135], v[156:159], v[16:31]
	s_waitcnt lgkmcnt(0)
	v_mfma_f32_32x32x16_bf16 v[64:79], v[128:131], v[168:171], v[64:79]
	v_mfma_f32_32x32x16_bf16 v[0:15], v[128:131], v[156:159], v[0:15]
	v_mov_b32_e32 v195, v212
	s_barrier
; template <int MODE>
; DI void phase1(const Params& p, unsigned char* smem, int tid) {
;     ...
;             for (int jt = 0; jt < 2; ++jt) {
;                 const int t = tt * 256 + wj * 64 + jt * 32 + ln;
;                 const float rs = rstd[t];
;                 if (wi == 0) {
;                     float sq = 0.f;
; #pragma unroll
;                     for (int it = 0; it < 4; ++it)
; #pragma unroll
;                         for (int r = 0; r < 16; ++r) { const float v = acc[it][jt][r] * rs; sq += v * v; }
;                     { const auto sw = __builtin_amdgcn_permlane32_swap(__float_as_uint(sq), __float_as_uint(sq), false, false);
;                       sq = __uint_as_float(sw[0]) + __uint_as_float(sw[1]); }
;                     if (h == 0) ((float*)(ws + OFF_RKV))[t] = 1.0f / sqrtf(sq * (1.0f / 128) + EPS);
;                 }
	s_lshl_b32 s92, s4, 8
	v_and_b32_e32 v196, 0xc0, v195
	v_and_b32_e32 v198, 31, v195
	v_or3_b32 v128, v196, s92, v198
	v_bfe_u32 v197, v195, 5, 1
	s_mov_b64 s[4:5], -1
	s_andn2_b64 vcc, exec, s[6:7]
	v_ashrrev_i32_e32 v129, 31, v128
	s_cbranch_vccnz .LBB0_367
	v_lshl_add_u64 v[130:131], v[128:129], 2, s[40:41]
	global_load_dword v134, v[130:131], off
	s_movk_i32 s4, 0x100
	v_cmp_gt_u32_e64 s[6:7], s4, v195
	v_cmp_eq_u32_e64 s[4:5], 0, v197
	s_and_saveexec_b64 s[10:11], s[6:7]
	s_cbranch_execz .LBB0_235
	s_waitcnt vmcnt(0)
	v_mul_f32_e32 v130, v113, v134
	v_mul_f32_e32 v131, v112, v134
	v_mul_f32_e32 v130, v130, v130
	v_fmac_f32_e32 v130, v131, v131
	v_mul_f32_e32 v131, v114, v134
	v_fmac_f32_e32 v130, v131, v131
	v_mul_f32_e32 v131, v115, v134
	v_fmac_f32_e32 v130, v131, v131
	v_mul_f32_e32 v131, v116, v134
	v_fmac_f32_e32 v130, v131, v131
	v_mul_f32_e32 v131, v117, v134
	v_fmac_f32_e32 v130, v131, v131
	v_mul_f32_e32 v131, v118, v134
	v_fmac_f32_e32 v130, v131, v131
	v_mul_f32_e32 v131, v119, v134
	v_fmac_f32_e32 v130, v131, v131
	v_mul_f32_e32 v131, v120, v134
	v_fmac_f32_e32 v130, v131, v131
	v_mul_f32_e32 v131, v121, v134
	v_fmac_f32_e32 v130, v131, v131
	v_mul_f32_e32 v131, v122, v134
	v_fmac_f32_e32 v130, v131, v131
	v_mul_f32_e32 v131, v123, v134
	v_fmac_f32_e32 v130, v131, v131
	v_mul_f32_e32 v131, v124, v134
	v_fmac_f32_e32 v130, v131, v131
	v_mul_f32_e32 v131, v125, v134
	v_fmac_f32_e32 v130, v131, v131
	v_mul_f32_e32 v131, v126, v134
	v_fmac_f32_e32 v130, v131, v131
	v_mul_f32_e32 v131, v127, v134
	v_fmac_f32_e32 v130, v131, v131
	v_mul_f32_e32 v131, v96, v134
	v_fmac_f32_e32 v130, v131, v131
	v_mul_f32_e32 v131, v97, v134
	v_fmac_f32_e32 v130, v131, v131
	v_mul_f32_e32 v131, v98, v134
	v_fmac_f32_e32 v130, v131, v131
	v_mul_f32_e32 v131, v99, v134
	v_fmac_f32_e32 v130, v131, v131
	v_mul_f32_e32 v131, v100, v134
	v_fmac_f32_e32 v130, v131, v131
	v_mul_f32_e32 v131, v101, v134
	v_fmac_f32_e32 v130, v131, v131
	v_mul_f32_e32 v131, v102, v134
	v_fmac_f32_e32 v130, v131, v131
	v_mul_f32_e32 v131, v103, v134
	v_fmac_f32_e32 v130, v131, v131
	v_mul_f32_e32 v131, v104, v134
	v_fmac_f32_e32 v130, v131, v131
	v_mul_f32_e32 v131, v105, v134
	v_fmac_f32_e32 v130, v131, v131
	v_mul_f32_e32 v131, v106, v134
	v_fmac_f32_e32 v130, v131, v131
	v_mul_f32_e32 v131, v107, v134
	v_fmac_f32_e32 v130, v131, v131
	v_mul_f32_e32 v131, v108, v134
	v_fmac_f32_e32 v130, v131, v131
	v_mul_f32_e32 v131, v109, v134
	v_fmac_f32_e32 v130, v131, v131
	v_mul_f32_e32 v131, v110, v134
	v_fmac_f32_e32 v130, v131, v131
	v_mul_f32_e32 v131, v111, v134
	v_fmac_f32_e32 v130, v131, v131
	v_mul_f32_e32 v131, v80, v134
	v_fmac_f32_e32 v130, v131, v131
	v_mul_f32_e32 v131, v81, v134
	v_fmac_f32_e32 v130, v131, v131
	v_mul_f32_e32 v131, v82, v134
	v_fmac_f32_e32 v130, v131, v131
	v_mul_f32_e32 v131, v83, v134
	v_fmac_f32_e32 v130, v131, v131
	v_mul_f32_e32 v131, v84, v134
	v_fmac_f32_e32 v130, v131, v131
	v_mul_f32_e32 v131, v85, v134
	v_fmac_f32_e32 v130, v131, v131
	v_mul_f32_e32 v131, v86, v134
	v_fmac_f32_e32 v130, v131, v131
	v_mul_f32_e32 v131, v87, v134
	v_fmac_f32_e32 v130, v131, v131
	v_mul_f32_e32 v131, v88, v134
	v_fmac_f32_e32 v130, v131, v131
	v_mul_f32_e32 v131, v89, v134
	v_fmac_f32_e32 v130, v131, v131
	v_mul_f32_e32 v131, v90, v134
	v_fmac_f32_e32 v130, v131, v131
	v_mul_f32_e32 v131, v91, v134
	v_fmac_f32_e32 v130, v131, v131
	v_mul_f32_e32 v131, v92, v134
	v_fmac_f32_e32 v130, v131, v131
	v_mul_f32_e32 v131, v93, v134
	v_fmac_f32_e32 v130, v131, v131
	v_mul_f32_e32 v131, v94, v134
	v_fmac_f32_e32 v130, v131, v131
	v_mul_f32_e32 v131, v95, v134
	v_fmac_f32_e32 v130, v131, v131
	v_mul_f32_e32 v131, v64, v134
	v_fmac_f32_e32 v130, v131, v131
	v_mul_f32_e32 v131, v65, v134
	v_fmac_f32_e32 v130, v131, v131
	v_mul_f32_e32 v131, v66, v134
	v_fmac_f32_e32 v130, v131, v131
	v_mul_f32_e32 v131, v67, v134
	v_fmac_f32_e32 v130, v131, v131
	v_mul_f32_e32 v131, v68, v134
	v_fmac_f32_e32 v130, v131, v131
	v_mul_f32_e32 v131, v69, v134
	v_fmac_f32_e32 v130, v131, v131
	v_mul_f32_e32 v131, v70, v134
	v_fmac_f32_e32 v130, v131, v131
	v_mul_f32_e32 v131, v71, v134
	v_fmac_f32_e32 v130, v131, v131
	v_mul_f32_e32 v131, v72, v134
	v_fmac_f32_e32 v130, v131, v131
	v_mul_f32_e32 v131, v73, v134
	v_fmac_f32_e32 v130, v131, v131
	v_mul_f32_e32 v131, v74, v134
	v_fmac_f32_e32 v130, v131, v131
	v_mul_f32_e32 v131, v75, v134
	v_fmac_f32_e32 v130, v131, v131
	v_mul_f32_e32 v131, v76, v134
	v_fmac_f32_e32 v130, v131, v131
	v_mul_f32_e32 v131, v77, v134
	v_fmac_f32_e32 v130, v131, v131
	v_mul_f32_e32 v131, v78, v134
	v_fmac_f32_e32 v130, v131, v131
	v_mul_f32_e32 v131, v79, v134
	v_fmac_f32_e32 v130, v131, v131
	v_mov_b32_e32 v131, v130
	s_nop 1
	v_permlane32_swap_b32_e32 v130, v131
	s_and_b64 exec, exec, s[4:5]
	s_cbranch_execz .LBB0_235
	v_add_f32_e32 v130, v130, v131
	v_fmamk_f32 v130, v130, 0x3c000000, v213
	s_mov_b32 s8, 0xf800000
	v_mul_f32_e32 v131, 0x4f800000, v130
	v_cmp_gt_f32_e32 vcc, s8, v130
	s_nop 1
	v_cndmask_b32_e32 v130, v130, v131, vcc
	v_sqrt_f32_e32 v131, v130
	s_nop 0
	v_add_u32_e32 v132, -1, v131
	v_fma_f32 v135, -v132, v131, v130
	v_add_u32_e32 v133, 1, v131
	v_cmp_ge_f32_e64 s[8:9], 0, v135
	s_nop 1
	v_cndmask_b32_e64 v132, v131, v132, s[8:9]
	v_fma_f32 v131, -v133, v131, v130
	v_cmp_lt_f32_e64 s[8:9], 0, v131
	s_nop 1
	v_cndmask_b32_e64 v131, v132, v133, s[8:9]
	v_mul_f32_e32 v132, 0x37800000, v131
	v_cndmask_b32_e32 v131, v131, v132, vcc
	v_cmp_class_f32_e32 vcc, v130, v214
	s_nop 1
	v_cndmask_b32_e32 v130, v131, v130, vcc
	v_div_scale_f32 v131, s[8:9], v130, v130, 1.0
	v_rcp_f32_e32 v132, v131
	v_readlane_b32 s8, v247, 11
	v_readlane_b32 s9, v247, 12
	v_fma_f32 v133, -v131, v132, 1.0
	v_fmac_f32_e32 v132, v133, v132
	v_div_scale_f32 v133, vcc, 1.0, v130, 1.0
	v_mul_f32_e32 v135, v133, v132
	v_fma_f32 v136, -v131, v135, v133
	v_fmac_f32_e32 v135, v136, v132
	v_fma_f32 v131, -v131, v135, v133
	v_div_fmas_f32 v131, v131, v132, v135
	v_div_fixup_f32 v132, v131, v130, 1.0
	v_lshl_add_u64 v[130:131], v[128:129], 2, s[8:9]
	global_store_dword v[130:131], v132, off

; #define G_HALF(pl, ql, ps, qs, kt_) { const int k4_ = min((kt_) + 4, nk - 1); \
;         SB G_LOAD(pl, ql, k4_) F_LOAD(fa1, fb1, cur, 1) SB G_MFMA(fa0, fb0) SB G_STORE(ps, qs, wr) F_LOAD(fa0, fb0, nxt, 0) SB G_MFMA(fa1, fb1) SB \
;         __syncthreads(); { const int t_ = cur; cur = nxt; nxt = wr; wr = t_; } }
; #define G_HALF(pl, ql, ps, qs, kt_) { const int k4_ = min((kt_) + 4, nk - 1); \
;         SB R_BURST1(fb0, fb1, cur, 1, pl, ql, k4_, ps, qs, wr) R_BURST2(fb1, fb0, nxt, 0, ps, qs, wr) \
;         __syncthreads(); { const int t_ = cur; cur = nxt; nxt = wr; wr = t_; } }
; #define G_HALF(pl, ql, ps, qs, kt_) { const int k4_ = min((kt_) + 4, nk - 1); \
;         SB R_BURST1(fb0, fb1, cur, 1, pl, ql, k4_, ps, qs, wr) R_BURST2(fb1, fb0, nxt, 0, ps, qs, wr) \
;         __syncthreads(); { const int t_ = cur; cur = nxt; nxt = wr; wr = t_; } }
;     ...
; #pragma unroll 1
;     for (; kt + 3 <= nk - 4; kt += 3) {
;         G_HALF(p1, q1, p2, q2, kt)
;         G_HALF(p2, q2, p0, q0, kt + 1)
;         G_HALF(p0, q0, p1, q1, kt + 2)
;     }
.LBB0_921:
	s_waitcnt lgkmcnt(1)
	s_nop 0
	v_mfma_f32_32x32x16_bf16 v[112:127], v[160:163], v[172:175], v[112:127]
	v_lshl_add_u64 v[228:229], v[190:191], 0, v[184:185]
	v_lshl_add_u64 v[230:231], v[196:197], 0, v[184:185]
	ds_read_b128 v[220:223], v201 offset:22560
	s_waitcnt vmcnt(7)
	ds_write_b128 v219, v[132:135]
	s_waitcnt lgkmcnt(2)
	v_mfma_f32_32x32x16_bf16 v[48:63], v[160:163], v[176:179], v[48:63]
	global_load_dwordx4 v[160:163], v[230:231], off offset:256
	ds_read_b128 v[132:135], v199 offset:2080
	v_mfma_f32_32x32x16_bf16 v[96:111], v[164:167], v[172:175], v[96:111]
	ds_read_b128 v[224:227], v201 offset:25120
	s_waitcnt vmcnt(7)
	ds_write_b128 v218, v[128:131]
	v_mfma_f32_32x32x16_bf16 v[32:47], v[164:167], v[176:179], v[32:47]
	v_add_co_u32_e32 v232, vcc, s29, v230
	ds_read_b128 v[128:131], v199 offset:4640
	s_nop 0
	v_addc_co_u32_e32 v233, vcc, 0, v231, vcc
	global_load_dwordx4 v[164:167], v[232:233], off offset:256
	v_mfma_f32_32x32x16_bf16 v[80:95], v[168:171], v[172:175], v[80:95]
	s_waitcnt vmcnt(7)
	ds_write_b128 v217, v[136:139]
	v_mfma_f32_32x32x16_bf16 v[16:31], v[168:171], v[176:179], v[16:31]
	global_load_dwordx4 v[168:171], v[228:229], off offset:256
	ds_read_b128 v[136:139], v199 offset:7200
	v_mfma_f32_32x32x16_bf16 v[64:79], v[180:183], v[172:175], v[64:79]
	s_waitcnt vmcnt(7)
	ds_write_b128 v216, v[140:143]
	v_mfma_f32_32x32x16_bf16 v[0:15], v[180:183], v[176:179], v[0:15]
	v_add_co_u32_e32 v234, vcc, s29, v228
	ds_read_b128 v[140:143], v199 offset:9760
	s_nop 0
	v_addc_co_u32_e32 v235, vcc, 0, v229, vcc
	global_load_dwordx4 v[172:175], v[234:235], off offset:256
	s_waitcnt lgkmcnt(7)
	v_mfma_f32_32x32x16_bf16 v[112:127], v[132:135], v[220:223], v[112:127]
	ds_read_b128 v[176:179], v201 offset:63488
	s_waitcnt lgkmcnt(7)
	v_mfma_f32_32x32x16_bf16 v[48:63], v[132:135], v[224:227], v[48:63]
	ds_read_b128 v[132:135], v199 offset:43008
	s_waitcnt lgkmcnt(6)
	v_mfma_f32_32x32x16_bf16 v[96:111], v[128:131], v[220:223], v[96:111]
	ds_read_b128 v[180:183], v200 offset:43520
	v_mfma_f32_32x32x16_bf16 v[32:47], v[128:131], v[224:227], v[32:47]
	ds_read_b128 v[128:131], v199 offset:45568
	s_waitcnt lgkmcnt(6)
	v_mfma_f32_32x32x16_bf16 v[80:95], v[136:139], v[220:223], v[80:95]
	v_mfma_f32_32x32x16_bf16 v[16:31], v[136:139], v[224:227], v[16:31]
	ds_read_b128 v[136:139], v199 offset:48128
	s_waitcnt lgkmcnt(5)
	v_mfma_f32_32x32x16_bf16 v[64:79], v[140:143], v[220:223], v[64:79]
	v_mfma_f32_32x32x16_bf16 v[0:15], v[140:143], v[224:227], v[0:15]
	ds_read_b128 v[140:143], v199 offset:50688
	s_barrier
	s_waitcnt lgkmcnt(4)
	v_mfma_f32_32x32x16_bf16 v[112:127], v[132:135], v[176:179], v[112:127]
	ds_read_b128 v[220:223], v201 offset:63520
	s_waitcnt vmcnt(7)
	ds_write_b128 v202, v[144:147] offset:2048
	s_waitcnt lgkmcnt(5)
	v_mfma_f32_32x32x16_bf16 v[48:63], v[132:135], v[180:183], v[48:63]
	global_load_dwordx4 v[132:135], v[230:231], off offset:320
	ds_read_b128 v[144:147], v199 offset:43040
	s_waitcnt lgkmcnt(5)
	v_mfma_f32_32x32x16_bf16 v[96:111], v[128:131], v[176:179], v[96:111]
	ds_read_b128 v[224:227], v200 offset:43552
	s_waitcnt vmcnt(7)
	ds_write_b128 v202, v[152:155] offset:12288
	v_mfma_f32_32x32x16_bf16 v[32:47], v[128:131], v[180:183], v[32:47]
	global_load_dwordx4 v[128:131], v[232:233], off offset:320
	ds_read_b128 v[152:155], v199 offset:45600
	s_waitcnt lgkmcnt(7)
	v_mfma_f32_32x32x16_bf16 v[80:95], v[136:139], v[176:179], v[80:95]
	s_waitcnt vmcnt(7)
	ds_write_b128 v202, v[148:151] offset:22528
	v_mfma_f32_32x32x16_bf16 v[16:31], v[136:139], v[180:183], v[16:31]
	global_load_dwordx4 v[136:139], v[228:229], off offset:320
	ds_read_b128 v[148:151], v199 offset:48160
	s_waitcnt lgkmcnt(8)
	v_mfma_f32_32x32x16_bf16 v[64:79], v[140:143], v[176:179], v[64:79]
	s_waitcnt vmcnt(7)
	ds_write_b128 v202, v[156:159] offset:32768
	v_mfma_f32_32x32x16_bf16 v[0:15], v[140:143], v[180:183], v[0:15]
	global_load_dwordx4 v[140:143], v[234:235], off offset:320
	ds_read_b128 v[156:159], v199 offset:50720
	s_waitcnt lgkmcnt(7)
	v_mfma_f32_32x32x16_bf16 v[112:127], v[144:147], v[220:223], v[112:127]
	ds_read_b128 v[176:179], v215
	s_waitcnt lgkmcnt(7)
	v_mfma_f32_32x32x16_bf16 v[48:63], v[144:147], v[224:227], v[48:63]
	ds_read_b128 v[144:147], v214
	s_waitcnt lgkmcnt(6)
	v_mfma_f32_32x32x16_bf16 v[96:111], v[152:155], v[220:223], v[96:111]
	ds_read_b128 v[180:183], v213
	v_mfma_f32_32x32x16_bf16 v[32:47], v[152:155], v[224:227], v[32:47]
	ds_read_b128 v[152:155], v212
	s_waitcnt lgkmcnt(6)
	v_mfma_f32_32x32x16_bf16 v[80:95], v[148:151], v[220:223], v[80:95]
	v_mfma_f32_32x32x16_bf16 v[16:31], v[148:151], v[224:227], v[16:31]
	ds_read_b128 v[148:151], v211
	s_waitcnt lgkmcnt(5)
	v_mfma_f32_32x32x16_bf16 v[64:79], v[156:159], v[220:223], v[64:79]
	v_mfma_f32_32x32x16_bf16 v[0:15], v[156:159], v[224:227], v[0:15]
	ds_read_b128 v[156:159], v210
	s_barrier
; #define G_HALF(pl, ql, ps, qs, kt_) { const int k4_ = min((kt_) + 4, nk - 1); \
;         SB G_LOAD(pl, ql, k4_) F_LOAD(fa1, fb1, cur, 1) SB G_MFMA(fa0, fb0) SB G_STORE(ps, qs, wr) F_LOAD(fa0, fb0, nxt, 0) SB G_MFMA(fa1, fb1) SB \
;         __syncthreads(); { const int t_ = cur; cur = nxt; nxt = wr; wr = t_; } }
; #define G_HALF(pl, ql, ps, qs, kt_) { const int k4_ = min((kt_) + 4, nk - 1); \
;         SB R_BURST1(fb0, fb1, cur, 1, pl, ql, k4_, ps, qs, wr) R_BURST2(fb1, fb0, nxt, 0, ps, qs, wr) \
;         __syncthreads(); { const int t_ = cur; cur = nxt; nxt = wr; wr = t_; } }
; #define G_HALF(pl, ql, ps, qs, kt_) { const int k4_ = min((kt_) + 4, nk - 1); \
;         SB R_BURST1(fb0, fb1, cur, 1, pl, ql, k4_, ps, qs, wr) R_BURST2(fb1, fb0, nxt, 0, ps, qs, wr) \
;         __syncthreads(); { const int t_ = cur; cur = nxt; nxt = wr; wr = t_; } }
;     ...
; #pragma unroll 1
;     for (; kt + 3 <= nk - 4; kt += 3) {
;         G_HALF(p1, q1, p2, q2, kt)
;         G_HALF(p2, q2, p0, q0, kt + 1)
;         G_HALF(p0, q0, p1, q1, kt + 2)
;     }
;     G_HALF(p1, q1, p2, q2, nk - 5)
	s_waitcnt lgkmcnt(4)
	v_mfma_f32_32x32x16_bf16 v[112:127], v[144:147], v[176:179], v[112:127]
	ds_read_b128 v[220:223], v209
	s_waitcnt vmcnt(7)
	ds_write_b128 v202, v[160:163] offset:43008
	s_waitcnt lgkmcnt(5)
	v_mfma_f32_32x32x16_bf16 v[48:63], v[144:147], v[180:183], v[48:63]
	global_load_dwordx4 v[144:147], v[230:231], off offset:384
	ds_read_b128 v[160:163], v208
	s_waitcnt lgkmcnt(5)
	v_mfma_f32_32x32x16_bf16 v[96:111], v[152:155], v[176:179], v[96:111]
	ds_read_b128 v[224:227], v207
	s_waitcnt vmcnt(7)
	ds_write_b128 v202, v[164:167] offset:53248
	v_mfma_f32_32x32x16_bf16 v[32:47], v[152:155], v[180:183], v[32:47]
	global_load_dwordx4 v[152:155], v[232:233], off offset:384
	ds_read_b128 v[164:167], v206
	s_waitcnt lgkmcnt(7)
	v_mfma_f32_32x32x16_bf16 v[80:95], v[148:151], v[176:179], v[80:95]
	s_waitcnt vmcnt(7)
	ds_write_b128 v202, v[168:171] offset:63488
	v_mfma_f32_32x32x16_bf16 v[16:31], v[148:151], v[180:183], v[16:31]
	global_load_dwordx4 v[148:151], v[228:229], off offset:384
	ds_read_b128 v[168:171], v205
	s_waitcnt lgkmcnt(8)
	v_mfma_f32_32x32x16_bf16 v[64:79], v[156:159], v[176:179], v[64:79]
	s_waitcnt vmcnt(7)
	ds_write_b128 v203, v[172:175]
	v_mfma_f32_32x32x16_bf16 v[0:15], v[156:159], v[180:183], v[0:15]
	global_load_dwordx4 v[156:159], v[234:235], off offset:384
	ds_read_b128 v[180:183], v204
	s_waitcnt lgkmcnt(7)
	v_mfma_f32_32x32x16_bf16 v[112:127], v[160:163], v[220:223], v[112:127]
	ds_read_b128 v[172:175], v201 offset:22528
	s_waitcnt lgkmcnt(7)
	v_mfma_f32_32x32x16_bf16 v[48:63], v[160:163], v[224:227], v[48:63]
	ds_read_b128 v[160:163], v199 offset:2048
	s_waitcnt lgkmcnt(6)
	v_mfma_f32_32x32x16_bf16 v[96:111], v[164:167], v[220:223], v[96:111]
	ds_read_b128 v[176:179], v201 offset:25088
	v_mfma_f32_32x32x16_bf16 v[32:47], v[164:167], v[224:227], v[32:47]
	ds_read_b128 v[164:167], v199 offset:4608
	s_waitcnt lgkmcnt(6)
	v_mfma_f32_32x32x16_bf16 v[80:95], v[168:171], v[220:223], v[80:95]
	v_mfma_f32_32x32x16_bf16 v[16:31], v[168:171], v[224:227], v[16:31]
	ds_read_b128 v[168:171], v199 offset:7168
	s_waitcnt lgkmcnt(5)
	v_mfma_f32_32x32x16_bf16 v[64:79], v[180:183], v[220:223], v[64:79]
	v_mfma_f32_32x32x16_bf16 v[0:15], v[180:183], v[224:227], v[0:15]
	ds_read_b128 v[180:183], v199 offset:9728
	s_add_i32 s20, s20, 3
	v_lshl_add_u64 v[196:197], v[196:197], 0, s[18:19]
	s_cmp_lt_u32 s20, 26
	v_lshl_add_u64 v[190:191], v[190:191], 0, s[18:19]
	s_waitcnt lgkmcnt(0)
	s_barrier
	s_cbranch_scc1 .LBB0_921
	v_mfma_f32_32x32x16_bf16 v[112:127], v[160:163], v[172:175], v[112:127]
	ds_read_b128 v[220:223], v201 offset:22560
	s_waitcnt vmcnt(7)
	ds_write_b128 v219, v[132:135]
	v_mfma_f32_32x32x16_bf16 v[48:63], v[160:163], v[176:179], v[48:63]
	global_load_dwordx4 v[160:163], v[194:195], off offset:1984
	ds_read_b128 v[194:197], v199 offset:2080
	v_mfma_f32_32x32x16_bf16 v[96:111], v[164:167], v[172:175], v[96:111]
	ds_read_b128 v[224:227], v201 offset:25120
	s_waitcnt vmcnt(7)
	ds_write_b128 v218, v[128:131]
	v_mfma_f32_32x32x16_bf16 v[32:47], v[164:167], v[176:179], v[32:47]
	global_load_dwordx4 v[164:167], v[192:193], off offset:1984
	ds_read_b128 v[190:193], v199 offset:4640
	v_mfma_f32_32x32x16_bf16 v[80:95], v[168:171], v[172:175], v[80:95]
	s_waitcnt vmcnt(7)
	ds_write_b128 v217, v[136:139]
	v_mfma_f32_32x32x16_bf16 v[16:31], v[168:171], v[176:179], v[16:31]
	global_load_dwordx4 v[168:171], v[188:189], off offset:1984
	ds_read_b128 v[228:231], v199 offset:7200
	v_mfma_f32_32x32x16_bf16 v[64:79], v[180:183], v[172:175], v[64:79]
	s_waitcnt vmcnt(7)
	ds_write_b128 v216, v[140:143]
	v_mfma_f32_32x32x16_bf16 v[0:15], v[180:183], v[176:179], v[0:15]
	global_load_dwordx4 v[172:175], v[186:187], off offset:1984
	ds_read_b128 v[176:179], v199 offset:9760
	s_waitcnt lgkmcnt(7)
	v_mfma_f32_32x32x16_bf16 v[112:127], v[194:197], v[220:223], v[112:127]
	ds_read_b128 v[180:183], v201 offset:63488
	s_waitcnt lgkmcnt(7)
	v_mfma_f32_32x32x16_bf16 v[48:63], v[194:197], v[224:227], v[48:63]
	ds_read_b128 v[186:189], v199 offset:43008
	s_waitcnt lgkmcnt(6)
	v_mfma_f32_32x32x16_bf16 v[96:111], v[190:193], v[220:223], v[96:111]
	ds_read_b128 v[194:197], v200 offset:43520
	v_mfma_f32_32x32x16_bf16 v[32:47], v[190:193], v[224:227], v[32:47]
	ds_read_b128 v[190:193], v199 offset:45568
	s_waitcnt lgkmcnt(6)
	v_mfma_f32_32x32x16_bf16 v[80:95], v[228:231], v[220:223], v[80:95]
	v_mfma_f32_32x32x16_bf16 v[16:31], v[228:231], v[224:227], v[16:31]
	ds_read_b128 v[216:219], v199 offset:48128
	s_waitcnt lgkmcnt(5)
	v_mfma_f32_32x32x16_bf16 v[64:79], v[176:179], v[220:223], v[64:79]
	v_mfma_f32_32x32x16_bf16 v[0:15], v[176:179], v[224:227], v[0:15]
	ds_read_b128 v[176:179], v199 offset:50688
	s_waitcnt lgkmcnt(0)
	s_barrier
; #define G_HALF_NL(ps, qs, kt_) { SB R_BURST1S(fb0, fb1, cur, 1, ps, qs, wr) R_BURST2(fb1, fb0, nxt, 0, ps, qs, wr) \
;         __syncthreads(); { const int t_ = cur; cur = nxt; nxt = wr; wr = t_; } }
;     ...
;     G_HALF_NL(p0, q0, nk - 4)
;     G_HALF_NL(p1, q1, nk - 3)
	v_mfma_f32_32x32x16_bf16 v[112:127], v[186:189], v[180:183], v[112:127]
	ds_read_b128 v[220:223], v201 offset:63520
	s_waitcnt vmcnt(7)
	ds_write_b128 v202, v[144:147] offset:2048
	v_mfma_f32_32x32x16_bf16 v[48:63], v[186:189], v[194:197], v[48:63]
	ds_read_b128 v[186:189], v199 offset:43040
	v_mfma_f32_32x32x16_bf16 v[96:111], v[190:193], v[180:183], v[96:111]
	ds_read_b128 v[224:227], v200 offset:43552
	s_waitcnt vmcnt(6)
	ds_write_b128 v202, v[152:155] offset:12288
	v_mfma_f32_32x32x16_bf16 v[32:47], v[190:193], v[194:197], v[32:47]
	ds_read_b128 v[190:193], v199 offset:45600
	v_mfma_f32_32x32x16_bf16 v[80:95], v[216:219], v[180:183], v[80:95]
	s_waitcnt vmcnt(5)
	ds_write_b128 v202, v[148:151] offset:22528
	v_mfma_f32_32x32x16_bf16 v[16:31], v[216:219], v[194:197], v[16:31]
	ds_read_b128 v[216:219], v199 offset:48160
	v_mfma_f32_32x32x16_bf16 v[64:79], v[176:179], v[180:183], v[64:79]
	s_waitcnt vmcnt(4)
	ds_write_b128 v202, v[156:159] offset:32768
	v_mfma_f32_32x32x16_bf16 v[0:15], v[176:179], v[194:197], v[0:15]
	ds_read_b128 v[176:179], v199 offset:50720
	s_waitcnt lgkmcnt(7)
	v_mfma_f32_32x32x16_bf16 v[112:127], v[186:189], v[220:223], v[112:127]
	ds_read_b128 v[180:183], v215
	s_waitcnt lgkmcnt(7)
	v_mfma_f32_32x32x16_bf16 v[48:63], v[186:189], v[224:227], v[48:63]
	ds_read_b128 v[186:189], v214
	s_waitcnt lgkmcnt(6)
	v_mfma_f32_32x32x16_bf16 v[96:111], v[190:193], v[220:223], v[96:111]
	ds_read_b128 v[194:197], v213
	v_mfma_f32_32x32x16_bf16 v[32:47], v[190:193], v[224:227], v[32:47]
	ds_read_b128 v[190:193], v212
	s_waitcnt lgkmcnt(6)
	v_mfma_f32_32x32x16_bf16 v[80:95], v[216:219], v[220:223], v[80:95]
	v_mfma_f32_32x32x16_bf16 v[16:31], v[216:219], v[224:227], v[16:31]
	ds_read_b128 v[212:215], v211
	s_waitcnt lgkmcnt(5)
	v_mfma_f32_32x32x16_bf16 v[64:79], v[176:179], v[220:223], v[64:79]
	v_mfma_f32_32x32x16_bf16 v[0:15], v[176:179], v[224:227], v[0:15]
	ds_read_b128 v[176:179], v210
	s_waitcnt lgkmcnt(0)
	s_barrier
	v_mfma_f32_32x32x16_bf16 v[112:127], v[186:189], v[180:183], v[112:127]
	ds_read_b128 v[216:219], v209
	s_waitcnt vmcnt(3)
	ds_write_b128 v202, v[160:163] offset:43008
	v_mfma_f32_32x32x16_bf16 v[48:63], v[186:189], v[194:197], v[48:63]
	ds_read_b128 v[186:189], v208
	v_mfma_f32_32x32x16_bf16 v[96:111], v[190:193], v[180:183], v[96:111]
	ds_read_b128 v[208:211], v207
	s_waitcnt vmcnt(2)
	ds_write_b128 v202, v[164:167] offset:53248
	v_mfma_f32_32x32x16_bf16 v[32:47], v[190:193], v[194:197], v[32:47]
	ds_read_b128 v[190:193], v206
	v_mfma_f32_32x32x16_bf16 v[80:95], v[212:215], v[180:183], v[80:95]
	s_waitcnt vmcnt(1)
	ds_write_b128 v202, v[168:171] offset:63488
	v_mfma_f32_32x32x16_bf16 v[16:31], v[212:215], v[194:197], v[16:31]
	ds_read_b128 v[212:215], v205
	v_mfma_f32_32x32x16_bf16 v[64:79], v[176:179], v[180:183], v[64:79]
	s_waitcnt vmcnt(0)
	ds_write_b128 v203, v[172:175]
	v_mfma_f32_32x32x16_bf16 v[0:15], v[176:179], v[194:197], v[0:15]
	ds_read_b128 v[176:179], v204
	s_waitcnt lgkmcnt(7)
	v_mfma_f32_32x32x16_bf16 v[112:127], v[186:189], v[216:219], v[112:127]
	ds_read_b128 v[180:183], v201 offset:22528
	s_waitcnt lgkmcnt(7)
	v_mfma_f32_32x32x16_bf16 v[48:63], v[186:189], v[208:211], v[48:63]
	ds_read_b128 v[186:189], v199 offset:2048
	s_waitcnt lgkmcnt(6)
	v_mfma_f32_32x32x16_bf16 v[96:111], v[190:193], v[216:219], v[96:111]
	ds_read_b128 v[194:197], v201 offset:25088
	v_mfma_f32_32x32x16_bf16 v[32:47], v[190:193], v[208:211], v[32:47]
	ds_read_b128 v[190:193], v199 offset:4608
	s_waitcnt lgkmcnt(6)
	v_mfma_f32_32x32x16_bf16 v[80:95], v[212:215], v[216:219], v[80:95]
	v_mfma_f32_32x32x16_bf16 v[16:31], v[212:215], v[208:211], v[16:31]
	ds_read_b128 v[202:205], v199 offset:7168
	s_waitcnt lgkmcnt(5)
	v_mfma_f32_32x32x16_bf16 v[64:79], v[176:179], v[216:219], v[64:79]
	v_mfma_f32_32x32x16_bf16 v[0:15], v[176:179], v[208:211], v[0:15]
	ds_read_b128 v[176:179], v199 offset:9728
	s_waitcnt lgkmcnt(0)
	s_barrier
; DI int real_tile_row256(int tt) { return (tt >> 4) * L + NMETA + (tt & 15) * 256; }
; DI void phase3b(const Params& p, unsigned char* smem, int tid) {
;     ...
;     auto tile_ptrs = [&](int rb, const bf16_t*& P, const bf16_t*& Q) __attribute__((always_inline)) -> bool {
;         const int idp = rb + xcd * (per_round >> 3) + cu;
;         if (rb >= 16 * 64 || idp >= 16 * 64) return false;
;         const int half = idp >> 9, i9 = idp & 511, f = (i9 & 31) >> 2, tt = (i9 >> 5) * 4 + (i9 & 3);
;         P = (const bf16_t*)(ws + (half == 0 ? OFF_WZ : OFF_WG)) + (size_t)f * 256 * 1024;
;         Q = hb + (size_t)real_tile_row256(tt) * 1024;
;         return true;
	v_mfma_f32_32x32x16_bf16 v[112:127], v[186:189], v[180:183], v[112:127]
	ds_read_b128 v[206:209], v201 offset:22560
	v_mfma_f32_32x32x16_bf16 v[48:63], v[186:189], v[194:197], v[48:63]
	ds_read_b128 v[186:189], v199 offset:2080
	v_mfma_f32_32x32x16_bf16 v[96:111], v[190:193], v[180:183], v[96:111]
	ds_read_b128 v[210:213], v201 offset:25120
	v_mfma_f32_32x32x16_bf16 v[32:47], v[190:193], v[194:197], v[32:47]
	ds_read_b128 v[190:193], v199 offset:4640
	v_mfma_f32_32x32x16_bf16 v[80:95], v[202:205], v[180:183], v[80:95]
	v_mfma_f32_32x32x16_bf16 v[16:31], v[202:205], v[194:197], v[16:31]
	ds_read_b128 v[202:205], v199 offset:7200
	v_mfma_f32_32x32x16_bf16 v[64:79], v[176:179], v[180:183], v[64:79]
	v_mfma_f32_32x32x16_bf16 v[0:15], v[176:179], v[194:197], v[0:15]
	ds_read_b128 v[176:179], v199 offset:9760
	s_waitcnt lgkmcnt(4)
	v_mfma_f32_32x32x16_bf16 v[112:127], v[186:189], v[206:209], v[112:127]
	ds_read_b128 v[180:183], v201 offset:63488
	s_waitcnt lgkmcnt(4)
	v_mfma_f32_32x32x16_bf16 v[48:63], v[186:189], v[210:213], v[48:63]
	ds_read_b128 v[186:189], v199 offset:43008
	s_waitcnt lgkmcnt(4)
	v_mfma_f32_32x32x16_bf16 v[96:111], v[190:193], v[206:209], v[96:111]
	ds_read_b128 v[194:197], v200 offset:43520
	v_mfma_f32_32x32x16_bf16 v[32:47], v[190:193], v[210:213], v[32:47]
	ds_read_b128 v[190:193], v199 offset:45568
	s_waitcnt lgkmcnt(5)
	v_mfma_f32_32x32x16_bf16 v[80:95], v[202:205], v[206:209], v[80:95]
	v_mfma_f32_32x32x16_bf16 v[16:31], v[202:205], v[210:213], v[16:31]
	ds_read_b128 v[202:205], v199 offset:48128
	s_waitcnt lgkmcnt(5)
	v_mfma_f32_32x32x16_bf16 v[64:79], v[176:179], v[206:209], v[64:79]
	v_mfma_f32_32x32x16_bf16 v[0:15], v[176:179], v[210:213], v[0:15]
	ds_read_b128 v[176:179], v199 offset:50688
	s_waitcnt lgkmcnt(0)
	s_barrier
	v_mfma_f32_32x32x16_bf16 v[112:127], v[186:189], v[180:183], v[112:127]
	ds_read_b128 v[206:209], v201 offset:63520
	v_mfma_f32_32x32x16_bf16 v[48:63], v[186:189], v[194:197], v[48:63]
	ds_read_b128 v[186:189], v199 offset:43040
	v_mfma_f32_32x32x16_bf16 v[96:111], v[190:193], v[180:183], v[96:111]
	ds_read_b128 v[210:213], v200 offset:43552
	v_mfma_f32_32x32x16_bf16 v[32:47], v[190:193], v[194:197], v[32:47]
	ds_read_b128 v[190:193], v199 offset:45600
	v_mfma_f32_32x32x16_bf16 v[80:95], v[202:205], v[180:183], v[80:95]
	v_mfma_f32_32x32x16_bf16 v[16:31], v[202:205], v[194:197], v[16:31]
	ds_read_b128 v[200:203], v199 offset:48160
	v_mfma_f32_32x32x16_bf16 v[64:79], v[176:179], v[180:183], v[64:79]
	v_mfma_f32_32x32x16_bf16 v[0:15], v[176:179], v[194:197], v[0:15]
	ds_read_b128 v[176:179], v199 offset:50720
	s_waitcnt lgkmcnt(4)
	v_mfma_f32_32x32x16_bf16 v[112:127], v[186:189], v[206:209], v[112:127]
	s_waitcnt lgkmcnt(3)
	v_mfma_f32_32x32x16_bf16 v[48:63], v[186:189], v[210:213], v[48:63]
	s_waitcnt lgkmcnt(2)
	v_mfma_f32_32x32x16_bf16 v[96:111], v[190:193], v[206:209], v[96:111]
	v_mfma_f32_32x32x16_bf16 v[32:47], v[190:193], v[210:213], v[32:47]
	s_waitcnt lgkmcnt(1)
	v_mfma_f32_32x32x16_bf16 v[80:95], v[200:203], v[206:209], v[80:95]
	v_mfma_f32_32x32x16_bf16 v[16:31], v[200:203], v[210:213], v[16:31]
	s_waitcnt lgkmcnt(0)
	v_mfma_f32_32x32x16_bf16 v[64:79], v[176:179], v[206:209], v[64:79]
	v_mfma_f32_32x32x16_bf16 v[0:15], v[176:179], v[210:213], v[0:15]
	s_add_i32 s38, s14, s2
	s_add_i32 s22, s38, s17
	s_max_i32 s23, s38, s22
	s_cmpk_lt_i32 s23, 0x400
	s_cselect_b64 s[20:21], -1, 0
	s_cmpk_gt_i32 s23, 0x3ff
	s_barrier
	s_cbranch_scc1 .LBB0_924
	s_lshr_b32 s8, s22, 3
	s_and_b32 s6, s8, 60
	s_and_b32 s7, s22, 3
	s_or_b32 s9, s6, s7
	s_cmpk_lt_u32 s22, 0x200
	s_cselect_b32 s6, s28, 0xdcfc00
	s_add_u32 s6, s56, s6
	s_addc_u32 s7, s57, 0
	s_lshl_b32 s22, s22, 17
	s_and_b32 s22, s22, 0x380000
	s_add_u32 s6, s6, s22
	s_addc_u32 s7, s7, 0
	s_bfe_u32 s8, s8, 0x20004
	s_lshl_b32 s9, s9, 8
	s_mulk_i32 s8, 0x1010
	s_and_b32 s9, s9, 0xf00
	s_add_i32 s8, s8, s9
	s_lshl_b32 s8, s8, 11
	s_add_i32 s8, s8, 0x8000
	s_add_u32 s8, s3, s8
	s_addc_u32 s9, s16, 0

; #define G_LOAD(pr, qr, kt_) if (MODE != 1) { _Pragma("unroll") for (int r = 0; r < NP; ++r) pr[r] = *(const u32x4*)(pp + (size_t)(r * 128) * ldp + (kt_) * BK); \
;                               _Pragma("unroll") for (int r = 0; r < NQ; ++r) qr[r] = *(const u32x4*)(qp + (size_t)(r * 128) * ldq + (kt_) * BK); }
; #define G_STORE(pr, qr, so_) { unsigned char* w_ = wP + (so_); \
;                               _Pragma("unroll") for (int r = 0; r < NP; ++r) *(u32x4*)(w_ + r * 128 * LROW) = pr[r]; \
;                               _Pragma("unroll") for (int r = 0; r < NQ; ++r) *(u32x4*)(w_ + BI * LROW + r * 128 * LROW) = qr[r]; }
; #define F_LOAD(fa, fb, so_, ks_) { _Pragma("unroll") for (int it = 0; it < WI; ++it) fa[it] = *(const bf16x8*)(rP + (so_) + it * 32 * LROW + (ks_) * 32); \
;                                   _Pragma("unroll") for (int jt = 0; jt < 2; ++jt) fb[jt] = *(const bf16x8*)(rQ + (so_) + jt * 32 * LROW + (ks_) * 32); }
; #define G_LOAD(pr, qr, kt_) if (MODE != 1) { _Pragma("unroll") for (int r = 0; r < NP; ++r) pr[r] = *(const u32x4*)(pp + (size_t)(r * 128) * ldp + (kt_) * BK); \
;                               _Pragma("unroll") for (int r = 0; r < NQ; ++r) qr[r] = *(const u32x4*)(qp + (size_t)(r * 128) * ldq + (kt_) * BK); }
; #define G_STORE(pr, qr, so_) { unsigned char* w_ = wP + (so_); \
;                               _Pragma("unroll") for (int r = 0; r < NP; ++r) *(u32x4*)(w_ + r * 128 * LROW) = pr[r]; \
;                               _Pragma("unroll") for (int r = 0; r < NQ; ++r) *(u32x4*)(w_ + BI * LROW + r * 128 * LROW) = qr[r]; }
;     ...
;     if (MODE == 1) {
; #pragma unroll
;         for (int r = 0; r < NP; ++r) { p0[r] = *(const u32x4*)(pp + (size_t)(r * 128) * ldp); p1[r] = p0[r]; p2[r] = p0[r]; }
; #pragma unroll
;         for (int r = 0; r < NQ; ++r) { q0[r] = *(const u32x4*)(qp + (size_t)(r * 128) * ldq); q1[r] = q0[r]; q2[r] = q0[r]; }
;     }
;     G_LOAD(p0, q0, 0)
;     G_LOAD(p1, q1, 1)
;     G_LOAD(p2, q2, 2)
;     G_STORE(p0, q0, 0)
;     G_LOAD(p0, q0, 3)
;     G_STORE(p1, q1, STAGE)
;     __syncthreads();
;     F_LOAD(fa0, fb0, 0, 0)
;     int cur = 0, nxt = STAGE, wr = 2 * STAGE;
;     int kt = 0;
; #pragma unroll 1
;     for (; kt + 3 <= nk; kt += 3) {
;         G_HALF(p1, q1, p2, q2, kt)
;         G_HALF(p2, q2, p0, q0, kt + 1)
;         G_HALF(p0, q0, p1, q1, kt + 2)
;     }
.LBB0_993:
	s_waitcnt lgkmcnt(1)
	s_nop 0
	v_mfma_f32_32x32x16_bf16 v[112:127], v[180:183], v[160:163], v[112:127]
	ds_read_b128 v[216:219], v195 offset:22560
	s_waitcnt vmcnt(7)
	ds_write_b128 v200, v[156:159]
	s_waitcnt lgkmcnt(2)
	v_mfma_f32_32x32x16_bf16 v[0:15], v[180:183], v[164:167], v[0:15]
	global_load_dwordx4 v[180:183], v250, s[98:99] offset:256
	ds_read_b128 v[156:159], v193 offset:2080
	v_mfma_f32_32x32x16_bf16 v[96:111], v[176:179], v[160:163], v[96:111]
	ds_read_b128 v[222:225], v195 offset:25120
	s_waitcnt vmcnt(6)
	ds_write_b128 v199, v[152:155]
	v_mfma_f32_32x32x16_bf16 v[32:47], v[176:179], v[164:167], v[32:47]
	global_load_dwordx4 v[176:179], v251, s[98:99] offset:256
	ds_read_b128 v[152:155], v193 offset:4640
	v_mfma_f32_32x32x16_bf16 v[80:95], v[172:175], v[160:163], v[80:95]
	s_waitcnt vmcnt(5)
	ds_write_b128 v196, v[148:151]
	v_mfma_f32_32x32x16_bf16 v[48:63], v[172:175], v[164:167], v[48:63]
	global_load_dwordx4 v[172:175], v250, s[100:101] offset:256
	ds_read_b128 v[148:151], v193 offset:7200
	v_mfma_f32_32x32x16_bf16 v[64:79], v[168:171], v[160:163], v[64:79]
	s_waitcnt vmcnt(4)
	ds_write_b128 v198, v[144:147]
	v_mfma_f32_32x32x16_bf16 v[16:31], v[168:171], v[164:167], v[16:31]
	global_load_dwordx4 v[160:163], v251, s[100:101] offset:256
	ds_read_b128 v[144:147], v193 offset:9760
	s_waitcnt lgkmcnt(7)
	v_mfma_f32_32x32x16_bf16 v[112:127], v[156:159], v[216:219], v[112:127]
	ds_read_b128 v[164:167], v195 offset:63488
	s_waitcnt lgkmcnt(7)
	v_mfma_f32_32x32x16_bf16 v[0:15], v[156:159], v[222:225], v[0:15]
	ds_read_b128 v[156:159], v193 offset:43008
	s_waitcnt lgkmcnt(6)
	v_mfma_f32_32x32x16_bf16 v[96:111], v[152:155], v[216:219], v[96:111]
	ds_read_b128 v[168:171], v194 offset:43520
	v_mfma_f32_32x32x16_bf16 v[32:47], v[152:155], v[222:225], v[32:47]
	ds_read_b128 v[152:155], v193 offset:45568
	s_waitcnt lgkmcnt(6)
	v_mfma_f32_32x32x16_bf16 v[80:95], v[148:151], v[216:219], v[80:95]
	v_mfma_f32_32x32x16_bf16 v[48:63], v[148:151], v[222:225], v[48:63]
	ds_read_b128 v[148:151], v193 offset:48128
	s_waitcnt lgkmcnt(5)
	v_mfma_f32_32x32x16_bf16 v[64:79], v[144:147], v[216:219], v[64:79]
	v_mfma_f32_32x32x16_bf16 v[16:31], v[144:147], v[222:225], v[16:31]
	ds_read_b128 v[144:147], v193 offset:50688
	s_barrier
	s_min_u32 s6, s11, 26
	s_waitcnt lgkmcnt(4)
	v_mfma_f32_32x32x16_bf16 v[112:127], v[156:159], v[164:167], v[112:127]
	ds_read_b128 v[216:219], v195 offset:63520
	ds_write_b128 v192, v[140:143] offset:2048
	s_waitcnt lgkmcnt(5)
	v_mfma_f32_32x32x16_bf16 v[0:15], v[156:159], v[168:171], v[0:15]
	global_load_dwordx4 v[156:159], v250, s[98:99] offset:320
	ds_read_b128 v[140:143], v193 offset:43040
	s_waitcnt lgkmcnt(5)
	v_mfma_f32_32x32x16_bf16 v[96:111], v[152:155], v[164:167], v[96:111]
	ds_read_b128 v[222:225], v194 offset:43552
	ds_write_b128 v192, v[136:139] offset:12288
	v_mfma_f32_32x32x16_bf16 v[32:47], v[152:155], v[168:171], v[32:47]
	global_load_dwordx4 v[152:155], v251, s[98:99] offset:320
	ds_read_b128 v[136:139], v193 offset:45600
	s_waitcnt lgkmcnt(7)
	v_mfma_f32_32x32x16_bf16 v[80:95], v[148:151], v[164:167], v[80:95]
	ds_write_b128 v192, v[132:135] offset:22528
	v_mfma_f32_32x32x16_bf16 v[48:63], v[148:151], v[168:171], v[48:63]
	global_load_dwordx4 v[148:151], v250, s[100:101] offset:320
	ds_read_b128 v[132:135], v193 offset:48160
	s_waitcnt lgkmcnt(8)
	v_mfma_f32_32x32x16_bf16 v[64:79], v[144:147], v[164:167], v[64:79]
	s_waitcnt vmcnt(7)
	ds_write_b128 v192, v[128:131] offset:32768
	v_mfma_f32_32x32x16_bf16 v[16:31], v[144:147], v[168:171], v[16:31]
	global_load_dwordx4 v[144:147], v251, s[100:101] offset:320
	ds_read_b128 v[128:131], v193 offset:50720
	s_waitcnt lgkmcnt(7)
	v_mfma_f32_32x32x16_bf16 v[112:127], v[140:143], v[216:219], v[112:127]
	ds_read_b128 v[164:167], v202
	s_waitcnt lgkmcnt(7)
	v_mfma_f32_32x32x16_bf16 v[0:15], v[140:143], v[222:225], v[0:15]
	ds_read_b128 v[140:143], v201
	s_waitcnt lgkmcnt(6)
	v_mfma_f32_32x32x16_bf16 v[96:111], v[136:139], v[216:219], v[96:111]
	ds_read_b128 v[168:171], v203
	v_mfma_f32_32x32x16_bf16 v[32:47], v[136:139], v[222:225], v[32:47]
	ds_read_b128 v[136:139], v204
	s_waitcnt lgkmcnt(6)
	v_mfma_f32_32x32x16_bf16 v[80:95], v[132:135], v[216:219], v[80:95]
	v_mfma_f32_32x32x16_bf16 v[48:63], v[132:135], v[222:225], v[48:63]
	ds_read_b128 v[132:135], v205
	s_waitcnt lgkmcnt(5)
	v_mfma_f32_32x32x16_bf16 v[64:79], v[128:131], v[216:219], v[64:79]
	v_mfma_f32_32x32x16_bf16 v[16:31], v[128:131], v[222:225], v[16:31]
	ds_read_b128 v[128:131], v206
	s_barrier
; #define G_LOAD(pr, qr, kt_) if (MODE != 1) { _Pragma("unroll") for (int r = 0; r < NP; ++r) pr[r] = *(const u32x4*)(pp + (size_t)(r * 128) * ldp + (kt_) * BK); \
;                               _Pragma("unroll") for (int r = 0; r < NQ; ++r) qr[r] = *(const u32x4*)(qp + (size_t)(r * 128) * ldq + (kt_) * BK); }
; #define G_STORE(pr, qr, so_) { unsigned char* w_ = wP + (so_); \
;                               _Pragma("unroll") for (int r = 0; r < NP; ++r) *(u32x4*)(w_ + r * 128 * LROW) = pr[r]; \
;                               _Pragma("unroll") for (int r = 0; r < NQ; ++r) *(u32x4*)(w_ + BI * LROW + r * 128 * LROW) = qr[r]; }
; #define F_LOAD(fa, fb, so_, ks_) { _Pragma("unroll") for (int it = 0; it < WI; ++it) fa[it] = *(const bf16x8*)(rP + (so_) + it * 32 * LROW + (ks_) * 32); \
;                                   _Pragma("unroll") for (int jt = 0; jt < 2; ++jt) fb[jt] = *(const bf16x8*)(rQ + (so_) + jt * 32 * LROW + (ks_) * 32); }
; #define G_LOAD(pr, qr, kt_) if (MODE != 1) { _Pragma("unroll") for (int r = 0; r < NP; ++r) pr[r] = *(const u32x4*)(pp + (size_t)(r * 128) * ldp + (kt_) * BK); \
;                               _Pragma("unroll") for (int r = 0; r < NQ; ++r) qr[r] = *(const u32x4*)(qp + (size_t)(r * 128) * ldq + (kt_) * BK); }
;     ...
;     if (MODE == 1) {
; #pragma unroll
;         for (int r = 0; r < NP; ++r) { p0[r] = *(const u32x4*)(pp + (size_t)(r * 128) * ldp); p1[r] = p0[r]; p2[r] = p0[r]; }
; #pragma unroll
;         for (int r = 0; r < NQ; ++r) { q0[r] = *(const u32x4*)(qp + (size_t)(r * 128) * ldq); q1[r] = q0[r]; q2[r] = q0[r]; }
;     }
;     G_LOAD(p0, q0, 0)
;     G_LOAD(p1, q1, 1)
;     G_LOAD(p2, q2, 2)
;     G_STORE(p0, q0, 0)
;     G_LOAD(p0, q0, 3)
;     G_STORE(p1, q1, STAGE)
;     __syncthreads();
;     F_LOAD(fa0, fb0, 0, 0)
;     int cur = 0, nxt = STAGE, wr = 2 * STAGE;
;     int kt = 0;
; #pragma unroll 1
;     for (; kt + 3 <= nk; kt += 3) {
;         G_HALF(p1, q1, p2, q2, kt)
;         G_HALF(p2, q2, p0, q0, kt + 1)
;         G_HALF(p0, q0, p1, q1, kt + 2)
;     }
;     if (kt < nk) G_HALF(p1, q1, p2, q2, kt)
;     if (kt + 1 < nk) G_HALF(p2, q2, p0, q0, kt + 1)
	s_min_u32 s6, s11, 25
	s_waitcnt lgkmcnt(4)
	v_mfma_f32_32x32x16_bf16 v[112:127], v[140:143], v[164:167], v[112:127]
	ds_read_b128 v[216:219], v207
	s_waitcnt vmcnt(7)
	ds_write_b128 v192, v[180:183] offset:43008
	s_waitcnt lgkmcnt(5)
	v_mfma_f32_32x32x16_bf16 v[0:15], v[140:143], v[168:171], v[0:15]
	global_load_dwordx4 v[140:143], v250, s[98:99] offset:384
	ds_read_b128 v[180:183], v208
	s_waitcnt lgkmcnt(5)
	v_mfma_f32_32x32x16_bf16 v[96:111], v[136:139], v[164:167], v[96:111]
	ds_read_b128 v[222:225], v209
	s_waitcnt vmcnt(7)
	ds_write_b128 v192, v[176:179] offset:53248
	v_mfma_f32_32x32x16_bf16 v[32:47], v[136:139], v[168:171], v[32:47]
	ds_read_b128 v[176:179], v210
	global_load_dwordx4 v[136:139], v251, s[98:99] offset:384
	s_waitcnt lgkmcnt(7)
	v_mfma_f32_32x32x16_bf16 v[80:95], v[132:135], v[164:167], v[80:95]
	s_waitcnt vmcnt(7)
	ds_write_b128 v192, v[172:175] offset:63488
	v_mfma_f32_32x32x16_bf16 v[48:63], v[132:135], v[168:171], v[48:63]
	global_load_dwordx4 v[132:135], v250, s[100:101] offset:384
	ds_read_b128 v[172:175], v211
	s_waitcnt lgkmcnt(8)
	v_mfma_f32_32x32x16_bf16 v[64:79], v[128:131], v[164:167], v[64:79]
	s_waitcnt vmcnt(7)
	ds_write_b128 v197, v[160:163]
	v_mfma_f32_32x32x16_bf16 v[16:31], v[128:131], v[168:171], v[16:31]
	ds_read_b128 v[168:171], v214
	global_load_dwordx4 v[128:131], v251, s[100:101] offset:384
	s_waitcnt lgkmcnt(7)
	v_mfma_f32_32x32x16_bf16 v[112:127], v[180:183], v[216:219], v[112:127]
	ds_read_b128 v[160:163], v195 offset:22528
	s_waitcnt lgkmcnt(7)
	v_mfma_f32_32x32x16_bf16 v[0:15], v[180:183], v[222:225], v[0:15]
	ds_read_b128 v[180:183], v193 offset:2048
	s_waitcnt lgkmcnt(6)
	v_mfma_f32_32x32x16_bf16 v[96:111], v[176:179], v[216:219], v[96:111]
	ds_read_b128 v[164:167], v195 offset:25088
	v_mfma_f32_32x32x16_bf16 v[32:47], v[176:179], v[222:225], v[32:47]
	ds_read_b128 v[176:179], v193 offset:4608
	s_waitcnt lgkmcnt(6)
	v_mfma_f32_32x32x16_bf16 v[80:95], v[172:175], v[216:219], v[80:95]
	v_mfma_f32_32x32x16_bf16 v[48:63], v[172:175], v[222:225], v[48:63]
	ds_read_b128 v[172:175], v193 offset:7168
	s_waitcnt lgkmcnt(5)
	v_mfma_f32_32x32x16_bf16 v[64:79], v[168:171], v[216:219], v[64:79]
	v_mfma_f32_32x32x16_bf16 v[16:31], v[168:171], v[222:225], v[16:31]
	ds_read_b128 v[168:171], v193 offset:9728
	s_add_i32 s11, s11, 3
	v_add_u32_e32 v250, 0xc0, v250
	s_cmp_lt_u32 s11, 30
	v_add_u32_e32 v251, 0xc0, v251
	s_waitcnt lgkmcnt(0)
	s_barrier
	s_cbranch_scc1 .LBB0_993
	v_mfma_f32_32x32x16_bf16 v[112:127], v[180:183], v[160:163], v[112:127]
	ds_read_b128 v[184:187], v195 offset:22560
	s_waitcnt vmcnt(7)
	ds_write_b128 v200, v[156:159]
	v_mfma_f32_32x32x16_bf16 v[0:15], v[180:183], v[164:167], v[0:15]
	ds_read_b128 v[156:159], v193 offset:2080
	v_mfma_f32_32x32x16_bf16 v[96:111], v[176:179], v[160:163], v[96:111]
	ds_read_b128 v[180:183], v195 offset:25120
	s_waitcnt vmcnt(6)
	ds_write_b128 v199, v[152:155]
	v_mfma_f32_32x32x16_bf16 v[32:47], v[176:179], v[164:167], v[32:47]
	ds_read_b128 v[152:155], v193 offset:4640
	v_mfma_f32_32x32x16_bf16 v[80:95], v[172:175], v[160:163], v[80:95]
	s_waitcnt vmcnt(5)
	ds_write_b128 v196, v[148:151]
	v_mfma_f32_32x32x16_bf16 v[48:63], v[172:175], v[164:167], v[48:63]
	ds_read_b128 v[148:151], v193 offset:7200
	v_mfma_f32_32x32x16_bf16 v[64:79], v[168:171], v[160:163], v[64:79]
	s_waitcnt vmcnt(4)
	ds_write_b128 v198, v[144:147]
	v_mfma_f32_32x32x16_bf16 v[16:31], v[168:171], v[164:167], v[16:31]
	ds_read_b128 v[144:147], v193 offset:9760
	s_waitcnt lgkmcnt(7)
	v_mfma_f32_32x32x16_bf16 v[112:127], v[156:159], v[184:187], v[112:127]
	ds_read_b128 v[160:163], v195 offset:63488
	s_waitcnt lgkmcnt(7)
	v_mfma_f32_32x32x16_bf16 v[0:15], v[156:159], v[180:183], v[0:15]
	ds_read_b128 v[156:159], v193 offset:43008
	s_waitcnt lgkmcnt(6)
	v_mfma_f32_32x32x16_bf16 v[96:111], v[152:155], v[184:187], v[96:111]
	ds_read_b128 v[164:167], v194 offset:43520
	v_mfma_f32_32x32x16_bf16 v[32:47], v[152:155], v[180:183], v[32:47]
	ds_read_b128 v[152:155], v193 offset:45568
	s_waitcnt lgkmcnt(6)
	v_mfma_f32_32x32x16_bf16 v[80:95], v[148:151], v[184:187], v[80:95]
	v_mfma_f32_32x32x16_bf16 v[48:63], v[148:151], v[180:183], v[48:63]
	ds_read_b128 v[148:151], v193 offset:48128
	s_waitcnt lgkmcnt(5)
	v_mfma_f32_32x32x16_bf16 v[64:79], v[144:147], v[184:187], v[64:79]
	v_mfma_f32_32x32x16_bf16 v[16:31], v[144:147], v[180:183], v[16:31]
	ds_read_b128 v[144:147], v193 offset:50688
	s_waitcnt lgkmcnt(0)
	s_barrier
	v_mfma_f32_32x32x16_bf16 v[112:127], v[156:159], v[160:163], v[112:127]
	ds_read_b128 v[168:171], v195 offset:63520
	s_waitcnt vmcnt(3)
	ds_write_b128 v192, v[140:143] offset:2048
	v_mfma_f32_32x32x16_bf16 v[0:15], v[156:159], v[164:167], v[0:15]
	ds_read_b128 v[140:143], v193 offset:43040
	v_mfma_f32_32x32x16_bf16 v[96:111], v[152:155], v[160:163], v[96:111]
	ds_read_b128 v[156:159], v194 offset:43552
	s_waitcnt vmcnt(2)
	ds_write_b128 v192, v[136:139] offset:12288
	v_mfma_f32_32x32x16_bf16 v[32:47], v[152:155], v[164:167], v[32:47]
	ds_read_b128 v[136:139], v193 offset:45600
	v_mfma_f32_32x32x16_bf16 v[80:95], v[148:151], v[160:163], v[80:95]
	s_waitcnt vmcnt(1)
	ds_write_b128 v192, v[132:135] offset:22528
	v_mfma_f32_32x32x16_bf16 v[48:63], v[148:151], v[164:167], v[48:63]
	ds_read_b128 v[132:135], v193 offset:48160
	v_mfma_f32_32x32x16_bf16 v[64:79], v[144:147], v[160:163], v[64:79]
	s_waitcnt vmcnt(0)
	ds_write_b128 v192, v[128:131] offset:32768
	v_mfma_f32_32x32x16_bf16 v[16:31], v[144:147], v[164:167], v[16:31]
	ds_read_b128 v[128:131], v193 offset:50720
	s_waitcnt lgkmcnt(7)
	v_mfma_f32_32x32x16_bf16 v[112:127], v[140:143], v[168:171], v[112:127]
	s_waitcnt lgkmcnt(6)
	v_mfma_f32_32x32x16_bf16 v[0:15], v[140:143], v[156:159], v[0:15]
	s_waitcnt lgkmcnt(4)
	v_mfma_f32_32x32x16_bf16 v[96:111], v[136:139], v[168:171], v[96:111]
	v_mfma_f32_32x32x16_bf16 v[32:47], v[136:139], v[156:159], v[32:47]
	s_waitcnt lgkmcnt(2)
	v_mfma_f32_32x32x16_bf16 v[80:95], v[132:135], v[168:171], v[80:95]
	v_mfma_f32_32x32x16_bf16 v[48:63], v[132:135], v[156:159], v[48:63]
	s_waitcnt lgkmcnt(0)
	v_mfma_f32_32x32x16_bf16 v[64:79], v[128:131], v[168:171], v[64:79]
	v_mfma_f32_32x32x16_bf16 v[16:31], v[128:131], v[156:159], v[16:31]
	s_lshl_b32 s6, s53, 6
	s_add_i32 s14, s6, s14
	v_mov_b32_e32 v130, v220
	s_ashr_i32 s15, s14, 31
	s_barrier
; DI float bf_lo(unsigned u) { return __uint_as_float(u << 16); }
; DI float bf_hi(unsigned u) { return __uint_as_float(u & 0xffff0000u); }
; DI void phase4(const Params& p, unsigned char* smem, int tid) {
;     ...
;             int te = tid; asm volatile("" : "+v"(te));
;             const unsigned char* ga = ws + OFF_G + ((size_t)(f * 64 + tt) * 8 + (te >> 6)) * 16384 + (te & 63) * 16;
;             const unsigned char* gb = ga + (size_t)4 * 64 * 8 * 16384;
; #pragma unroll
;             for (int it = 0; it < 4; ++it)
; #pragma unroll
;                 for (int jt = 0; jt < 2; ++jt)
; #pragma unroll
;                     for (int gp = 0; gp < 2; ++gp) {
;                         const u32x4 a4 = *(const u32x4*)(ga + ((it * 2 + jt) * 2 + gp) * 1024), b4 = *(const u32x4*)(gb + ((it * 2 + jt) * 2 + gp) * 1024);
; #pragma unroll
;                         for (int e = 0; e < 4; ++e) {
;                             acc[it][jt][8 * gp + 2 * e] *= bf_lo(a4[e]) * __builtin_amdgcn_rcpf(fmaxf(bf_lo(b4[e]), 8.6736174e-19f));
;                             acc[it][jt][8 * gp + 2 * e + 1] *= bf_hi(a4[e]) * __builtin_amdgcn_rcpf(fmaxf(bf_hi(b4[e]), 8.6736174e-19f));
;                         }
;                     }
	s_lshl_b64 s[58:59], s[14:15], 17
	v_ashrrev_i32_e32 v128, 6, v130
	v_ashrrev_i32_e32 v129, 31, v128
	s_add_u32 s58, s24, s58
	v_lshlrev_b64 v[128:129], 14, v[128:129]
	s_addc_u32 s59, s25, s59
	v_lshlrev_b32_e32 v130, 4, v130
	v_lshl_add_u64 v[128:129], s[58:59], 0, v[128:129]
	v_and_b32_e32 v212, 0x3f0, v130
	v_lshl_add_u64 v[152:153], v[128:129], 0, v[212:213]
	v_add_co_u32_e32 v154, vcc, s41, v152
	global_load_dwordx4 v[132:135], v[152:153], off
	global_load_dwordx4 v[128:131], v[152:153], off offset:1024
	v_addc_co_u32_e32 v155, vcc, 0, v153, vcc
	global_load_dwordx4 v[144:147], v[154:155], off offset:-4096
	global_load_dwordx4 v[140:143], v[152:153], off offset:2048
	v_add_co_u32_e32 v156, vcc, s39, v152
	v_mov_b32_e32 v210, v220
	s_nop 0
	v_addc_co_u32_e32 v157, vcc, 0, v153, vcc
	global_load_dwordx4 v[136:139], v[156:157], off offset:1024
	v_add_co_u32_e32 v158, vcc, s44, v152
	s_add_u32 s58, s26, s55
	s_nop 0
	v_addc_co_u32_e32 v159, vcc, 0, v153, vcc
	global_load_dwordx4 v[148:151], v[156:157], off offset:2048
	global_load_dwordx4 v[178:181], v[158:159], off offset:3072
	s_addc_u32 s59, s27, 0
	s_add_u32 s18, s28, s18
	s_addc_u32 s19, s29, s19
	s_mov_b32 s11, 0
	s_waitcnt vmcnt(6)
	v_lshlrev_b32_e32 v160, 16, v132
	s_waitcnt vmcnt(5)
	v_lshlrev_b32_e32 v164, 16, v128
	v_and_b32_e32 v165, 0xffff0000, v128
	v_and_b32_e32 v161, 0xffff0000, v132
	s_waitcnt vmcnt(4)
	v_lshlrev_b32_e32 v166, 16, v145
	v_and_b32_e32 v145, 0xffff0000, v145
	v_lshlrev_b32_e32 v167, 16, v146
	v_and_b32_e32 v146, 0xffff0000, v146
	v_lshlrev_b32_e32 v168, 16, v147
	v_and_b32_e32 v147, 0xffff0000, v147
	v_max_f32_e32 v166, v166, v166
	v_max_f32_e32 v145, v145, v145
	v_max_f32_e32 v146, v146, v146
	v_max_f32_e32 v147, v147, v147
	v_max_f32_e32 v166, 0x21800000, v166
	v_max_f32_e32 v171, 0x21800000, v145
	v_lshlrev_b32_e32 v128, 16, v144
	v_max_f32_e32 v173, 0x21800000, v146
	v_max_f32_e32 v174, 0x21800000, v147
	v_rcp_f32_e32 v146, v166
	v_rcp_f32_e32 v147, v171
	v_and_b32_e32 v144, 0xffff0000, v144
	v_max_f32_e32 v128, v128, v128
	s_waitcnt vmcnt(2)
	v_lshlrev_b32_e32 v172, 16, v137
	v_max_f32_e32 v144, v144, v144
	v_max_f32_e32 v128, 0x21800000, v128
	v_lshlrev_b32_e32 v132, 16, v133
	v_and_b32_e32 v133, 0xffff0000, v133
	v_max_f32_e32 v170, 0x21800000, v144
	v_rcp_f32_e32 v144, v128
	v_max_f32_e32 v128, v172, v172
	v_pk_mul_f32 v[132:133], v[146:147], v[132:133]
	v_max_f32_e32 v128, 0x21800000, v128
	v_pk_mul_f32 v[114:115], v[114:115], v[132:133]
	v_rcp_f32_e32 v132, v128
	v_and_b32_e32 v128, 0xffff0000, v137
	v_max_f32_e32 v128, v128, v128
	v_max_f32_e32 v128, 0x21800000, v128
	v_lshlrev_b32_e32 v169, 16, v136
	v_max_f32_e32 v168, v168, v168
	v_rcp_f32_e32 v133, v128
	v_max_f32_e32 v169, v169, v169
	v_max_f32_e32 v168, 0x21800000, v168
	v_max_f32_e32 v175, 0x21800000, v169
	v_rcp_f32_e32 v168, v168
	v_rcp_f32_e32 v169, v174
	v_lshlrev_b32_e32 v128, 16, v129
	v_and_b32_e32 v129, 0xffff0000, v129
	v_and_b32_e32 v136, 0xffff0000, v136
	v_pk_mul_f32 v[128:129], v[132:133], v[128:129]
	v_lshlrev_b32_e32 v132, 16, v138
	v_lshlrev_b32_e32 v162, 16, v134
	v_and_b32_e32 v163, 0xffff0000, v134
	v_lshlrev_b32_e32 v134, 16, v135
	v_and_b32_e32 v135, 0xffff0000, v135
	v_max_f32_e32 v136, v136, v136
	v_max_f32_e32 v132, v132, v132
	v_max_f32_e32 v167, v167, v167
	v_max_f32_e32 v136, 0x21800000, v136
	v_pk_mul_f32 v[134:135], v[168:169], v[134:135]
	v_max_f32_e32 v132, 0x21800000, v132
	v_max_f32_e32 v167, 0x21800000, v167
	v_rcp_f32_e32 v171, v136
	v_pk_mul_f32 v[118:119], v[118:119], v[134:135]
	v_rcp_f32_e32 v136, v132
	global_load_dwordx4 v[132:135], v[156:157], off offset:3072
	v_rcp_f32_e32 v145, v170
	v_rcp_f32_e32 v166, v167
	v_rcp_f32_e32 v167, v173
	v_and_b32_e32 v137, 0xffff0000, v138
	v_pk_mul_f32 v[144:145], v[144:145], v[160:161]
	v_max_f32_e32 v137, v137, v137
	v_pk_mul_f32 v[146:147], v[166:167], v[162:163]
	v_pk_mul_f32 v[112:113], v[112:113], v[144:145]
	v_pk_mul_f32 v[116:117], v[116:117], v[146:147]
	global_load_dwordx4 v[144:147], v[152:153], off offset:3072
	v_max_f32_e32 v137, 0x21800000, v137
	v_rcp_f32_e32 v137, v137
	v_pk_mul_f32 v[122:123], v[122:123], v[128:129]
	v_lshlrev_b32_e32 v128, 16, v130
	v_and_b32_e32 v129, 0xffff0000, v130
	v_lshlrev_b32_e32 v130, 16, v139
	v_max_f32_e32 v130, v130, v130
	v_max_f32_e32 v130, 0x21800000, v130
	v_pk_mul_f32 v[128:129], v[136:137], v[128:129]
	v_rcp_f32_e32 v136, v130
	v_and_b32_e32 v130, 0xffff0000, v139
	v_max_f32_e32 v130, v130, v130
	v_max_f32_e32 v130, 0x21800000, v130
	v_rcp_f32_e32 v137, v130
	v_pk_mul_f32 v[124:125], v[124:125], v[128:129]
	v_lshlrev_b32_e32 v128, 16, v131
	v_and_b32_e32 v129, 0xffff0000, v131
	s_waitcnt vmcnt(3)
	v_lshlrev_b32_e32 v130, 16, v148
	v_and_b32_e32 v131, 0xffff0000, v148
	v_max_f32_e32 v130, v130, v130
	v_max_f32_e32 v131, v131, v131
	v_max_f32_e32 v130, 0x21800000, v130
	v_max_f32_e32 v131, 0x21800000, v131
	v_rcp_f32_e32 v130, v130
	v_rcp_f32_e32 v131, v131
	v_pk_mul_f32 v[128:129], v[136:137], v[128:129]
	global_load_dwordx4 v[136:139], v[154:155], off
	v_pk_mul_f32 v[126:127], v[126:127], v[128:129]
	v_lshlrev_b32_e32 v128, 16, v140
	v_and_b32_e32 v129, 0xffff0000, v140
	v_pk_mul_f32 v[128:129], v[130:131], v[128:129]
	v_lshlrev_b32_e32 v130, 16, v149
	v_and_b32_e32 v131, 0xffff0000, v149
	v_max_f32_e32 v130, v130, v130
	v_max_f32_e32 v131, v131, v131
	v_max_f32_e32 v130, 0x21800000, v130
	v_max_f32_e32 v131, 0x21800000, v131
	v_rcp_f32_e32 v130, v130
	v_rcp_f32_e32 v131, v131
	v_rcp_f32_e32 v170, v175
	v_pk_mul_f32 v[0:1], v[0:1], v[128:129]
	v_lshlrev_b32_e32 v128, 16, v141
	v_and_b32_e32 v129, 0xffff0000, v141
	v_pk_mul_f32 v[128:129], v[130:131], v[128:129]
	v_add_co_u32_e32 v130, vcc, s42, v152
	v_pk_mul_f32 v[160:161], v[170:171], v[164:165]
	s_nop 0
	v_addc_co_u32_e32 v131, vcc, 0, v153, vcc
	v_pk_mul_f32 v[120:121], v[120:121], v[160:161]
	global_load_dwordx4 v[160:163], v[130:131], off offset:-4096
	v_pk_mul_f32 v[2:3], v[2:3], v[128:129]
	v_lshlrev_b32_e32 v128, 16, v150
	v_and_b32_e32 v129, 0xffff0000, v150
	v_max_f32_e32 v128, v128, v128
	v_max_f32_e32 v129, v129, v129
	v_max_f32_e32 v128, 0x21800000, v128
	v_max_f32_e32 v129, 0x21800000, v129
	v_rcp_f32_e32 v128, v128
	v_rcp_f32_e32 v129, v129
	v_lshlrev_b32_e32 v140, 16, v142
	v_and_b32_e32 v141, 0xffff0000, v142
	v_add_co_u32_e32 v156, vcc, s40, v152
	v_pk_mul_f32 v[128:129], v[128:129], v[140:141]
	v_lshlrev_b32_e32 v140, 16, v151
	v_and_b32_e32 v141, 0xffff0000, v151
	v_max_f32_e32 v140, v140, v140
	v_max_f32_e32 v141, v141, v141
	v_max_f32_e32 v140, 0x21800000, v140
	v_max_f32_e32 v141, 0x21800000, v141
	s_waitcnt vmcnt(3)
; DI float bf_lo(unsigned u) { return __uint_as_float(u << 16); }
; DI float bf_hi(unsigned u) { return __uint_as_float(u & 0xffff0000u); }
; DI void phase4(const Params& p, unsigned char* smem, int tid) {
;     ...
;             const unsigned char* ga = ws + OFF_G + ((size_t)(f * 64 + tt) * 8 + (te >> 6)) * 16384 + (te & 63) * 16;
;             const unsigned char* gb = ga + (size_t)4 * 64 * 8 * 16384;
; #pragma unroll
;             for (int it = 0; it < 4; ++it)
; #pragma unroll
;                 for (int jt = 0; jt < 2; ++jt)
; #pragma unroll
;                     for (int gp = 0; gp < 2; ++gp) {
;                         const u32x4 a4 = *(const u32x4*)(ga + ((it * 2 + jt) * 2 + gp) * 1024), b4 = *(const u32x4*)(gb + ((it * 2 + jt) * 2 + gp) * 1024);
; #pragma unroll
;                         for (int e = 0; e < 4; ++e) {
;                             acc[it][jt][8 * gp + 2 * e] *= bf_lo(a4[e]) * __builtin_amdgcn_rcpf(fmaxf(bf_lo(b4[e]), 8.6736174e-19f));
;                             acc[it][jt][8 * gp + 2 * e + 1] *= bf_hi(a4[e]) * __builtin_amdgcn_rcpf(fmaxf(bf_hi(b4[e]), 8.6736174e-19f));
;                         }
;                     }
	v_lshlrev_b32_e32 v148, 16, v132
	v_and_b32_e32 v132, 0xffff0000, v132
	v_rcp_f32_e32 v140, v140
	v_rcp_f32_e32 v141, v141
	v_max_f32_e32 v148, v148, v148
	v_max_f32_e32 v132, v132, v132
	v_max_f32_e32 v148, 0x21800000, v148
	v_max_f32_e32 v132, 0x21800000, v132
	v_rcp_f32_e32 v148, v148
	v_rcp_f32_e32 v149, v132
	v_pk_mul_f32 v[4:5], v[4:5], v[128:129]
	v_lshlrev_b32_e32 v128, 16, v143
	v_and_b32_e32 v129, 0xffff0000, v143
	v_pk_mul_f32 v[128:129], v[140:141], v[128:129]
	v_addc_co_u32_e32 v157, vcc, 0, v153, vcc
	v_pk_mul_f32 v[6:7], v[6:7], v[128:129]
	s_waitcnt vmcnt(2)
	v_lshlrev_b32_e32 v128, 16, v144
	v_and_b32_e32 v129, 0xffff0000, v144
	v_pk_mul_f32 v[128:129], v[148:149], v[128:129]
	global_load_dwordx4 v[148:151], v[154:155], off offset:1024
	global_load_dwordx4 v[140:143], v[156:157], off offset:1024
	global_load_dwordx4 v[164:167], v[156:157], off offset:2048
	v_lshlrev_b32_e32 v132, 16, v133
	v_and_b32_e32 v133, 0xffff0000, v133
	v_max_f32_e32 v132, v132, v132
	v_max_f32_e32 v133, v133, v133
	v_max_f32_e32 v132, 0x21800000, v132
	v_max_f32_e32 v133, 0x21800000, v133
	v_rcp_f32_e32 v132, v132
	v_rcp_f32_e32 v133, v133
	v_pk_mul_f32 v[8:9], v[8:9], v[128:129]
	v_lshlrev_b32_e32 v128, 16, v145
	v_and_b32_e32 v129, 0xffff0000, v145
	v_pk_mul_f32 v[128:129], v[132:133], v[128:129]
	v_lshlrev_b32_e32 v132, 16, v134
	v_and_b32_e32 v133, 0xffff0000, v134
	v_max_f32_e32 v132, v132, v132
	v_max_f32_e32 v133, v133, v133
	v_max_f32_e32 v132, 0x21800000, v132
	v_max_f32_e32 v133, 0x21800000, v133
	v_rcp_f32_e32 v132, v132
	v_rcp_f32_e32 v133, v133
	v_pk_mul_f32 v[10:11], v[10:11], v[128:129]
	v_lshlrev_b32_e32 v128, 16, v146
	v_and_b32_e32 v129, 0xffff0000, v146
	v_pk_mul_f32 v[128:129], v[132:133], v[128:129]
	v_lshlrev_b32_e32 v132, 16, v135
	v_and_b32_e32 v133, 0xffff0000, v135
	v_max_f32_e32 v132, v132, v132
	v_max_f32_e32 v133, v133, v133
	v_max_f32_e32 v132, 0x21800000, v132
	v_max_f32_e32 v133, 0x21800000, v133
	v_rcp_f32_e32 v132, v132
	v_rcp_f32_e32 v133, v133
	v_pk_mul_f32 v[12:13], v[12:13], v[128:129]
	v_lshlrev_b32_e32 v128, 16, v147
	v_and_b32_e32 v129, 0xffff0000, v147
	v_pk_mul_f32 v[128:129], v[132:133], v[128:129]
	s_waitcnt vmcnt(3)
	v_lshlrev_b32_e32 v144, 16, v160
	v_pk_mul_f32 v[14:15], v[14:15], v[128:129]
	v_lshlrev_b32_e32 v128, 16, v136
	v_and_b32_e32 v129, 0xffff0000, v136
	v_max_f32_e32 v128, v128, v128
	v_max_f32_e32 v129, v129, v129
	v_max_f32_e32 v128, 0x21800000, v128
	v_max_f32_e32 v129, 0x21800000, v129
	v_rcp_f32_e32 v128, v128
	v_rcp_f32_e32 v129, v129
	v_and_b32_e32 v145, 0xffff0000, v160
	v_lshlrev_b32_e32 v136, 16, v137
	v_and_b32_e32 v137, 0xffff0000, v137
	v_pk_mul_f32 v[128:129], v[128:129], v[144:145]
	global_load_dwordx4 v[144:147], v[154:155], off offset:2048
	v_max_f32_e32 v136, v136, v136
	v_max_f32_e32 v137, v137, v137
	v_max_f32_e32 v136, 0x21800000, v136
	v_max_f32_e32 v137, 0x21800000, v137
	v_rcp_f32_e32 v136, v136
	v_rcp_f32_e32 v137, v137
	v_pk_mul_f32 v[96:97], v[96:97], v[128:129]
	v_lshlrev_b32_e32 v128, 16, v161
	v_and_b32_e32 v129, 0xffff0000, v161
	v_pk_mul_f32 v[128:129], v[136:137], v[128:129]
	v_lshlrev_b32_e32 v136, 16, v138
	v_and_b32_e32 v137, 0xffff0000, v138
	v_max_f32_e32 v136, v136, v136
	v_max_f32_e32 v137, v137, v137
	v_max_f32_e32 v136, 0x21800000, v136
	v_max_f32_e32 v137, 0x21800000, v137
	v_rcp_f32_e32 v136, v136
	v_rcp_f32_e32 v137, v137
	v_pk_mul_f32 v[98:99], v[98:99], v[128:129]
	v_lshlrev_b32_e32 v128, 16, v162
	v_and_b32_e32 v129, 0xffff0000, v162
	v_pk_mul_f32 v[128:129], v[136:137], v[128:129]
	v_lshlrev_b32_e32 v136, 16, v139
	v_and_b32_e32 v137, 0xffff0000, v139
	v_max_f32_e32 v136, v136, v136
	v_max_f32_e32 v137, v137, v137
	v_max_f32_e32 v136, 0x21800000, v136
	v_max_f32_e32 v137, 0x21800000, v137
	v_rcp_f32_e32 v136, v136
	v_rcp_f32_e32 v137, v137
	v_pk_mul_f32 v[100:101], v[100:101], v[128:129]
	v_lshlrev_b32_e32 v128, 16, v163
	v_and_b32_e32 v129, 0xffff0000, v163
	v_pk_mul_f32 v[128:129], v[136:137], v[128:129]
	s_waitcnt vmcnt(3)
	v_lshlrev_b32_e32 v136, 16, v148
	v_and_b32_e32 v137, 0xffff0000, v148
	v_max_f32_e32 v136, v136, v136
	v_max_f32_e32 v137, v137, v137
	v_max_f32_e32 v136, 0x21800000, v136
	v_max_f32_e32 v137, 0x21800000, v137
	v_rcp_f32_e32 v136, v136
	v_rcp_f32_e32 v137, v137
	v_pk_mul_f32 v[102:103], v[102:103], v[128:129]
	s_waitcnt vmcnt(2)
	v_lshlrev_b32_e32 v128, 16, v140
	v_and_b32_e32 v129, 0xffff0000, v140
	v_pk_mul_f32 v[128:129], v[136:137], v[128:129]
	global_load_dwordx4 v[136:139], v[154:155], off offset:3072
	v_pk_mul_f32 v[104:105], v[104:105], v[128:129]
	global_load_dwordx4 v[154:157], v[156:157], off offset:3072
	v_lshlrev_b32_e32 v128, 16, v149
	v_and_b32_e32 v129, 0xffff0000, v149
	v_max_f32_e32 v128, v128, v128
	v_max_f32_e32 v129, v129, v129
	v_max_f32_e32 v128, 0x21800000, v128
	v_max_f32_e32 v129, 0x21800000, v129
	v_rcp_f32_e32 v128, v128
	v_rcp_f32_e32 v129, v129
	v_lshlrev_b32_e32 v140, 16, v141
	v_and_b32_e32 v141, 0xffff0000, v141
	global_load_dwordx4 v[132:135], v[130:131], off
	v_pk_mul_f32 v[128:129], v[128:129], v[140:141]
	v_lshlrev_b32_e32 v140, 16, v150
	v_and_b32_e32 v141, 0xffff0000, v150
	v_max_f32_e32 v140, v140, v140
	v_max_f32_e32 v141, v141, v141
	v_max_f32_e32 v140, 0x21800000, v140
	v_max_f32_e32 v141, 0x21800000, v141
	v_rcp_f32_e32 v140, v140
	v_rcp_f32_e32 v141, v141
	v_pk_mul_f32 v[106:107], v[106:107], v[128:129]
	v_lshlrev_b32_e32 v128, 16, v142
	v_and_b32_e32 v129, 0xffff0000, v142
	v_pk_mul_f32 v[128:129], v[140:141], v[128:129]
	v_lshlrev_b32_e32 v140, 16, v151
	v_and_b32_e32 v141, 0xffff0000, v151
	v_max_f32_e32 v140, v140, v140
	v_max_f32_e32 v141, v141, v141
	v_max_f32_e32 v140, 0x21800000, v140
	v_max_f32_e32 v141, 0x21800000, v141
	v_rcp_f32_e32 v140, v140
	v_rcp_f32_e32 v141, v141
	v_pk_mul_f32 v[108:109], v[108:109], v[128:129]
	v_lshlrev_b32_e32 v128, 16, v143
	v_and_b32_e32 v129, 0xffff0000, v143
	v_pk_mul_f32 v[128:129], v[140:141], v[128:129]
	s_waitcnt vmcnt(3)
; DI float bf_lo(unsigned u) { return __uint_as_float(u << 16); }
; DI float bf_hi(unsigned u) { return __uint_as_float(u & 0xffff0000u); }
; DI void phase4(const Params& p, unsigned char* smem, int tid) {
;     ...
;             const unsigned char* ga = ws + OFF_G + ((size_t)(f * 64 + tt) * 8 + (te >> 6)) * 16384 + (te & 63) * 16;
;             const unsigned char* gb = ga + (size_t)4 * 64 * 8 * 16384;
; #pragma unroll
;             for (int it = 0; it < 4; ++it)
; #pragma unroll
;                 for (int jt = 0; jt < 2; ++jt)
; #pragma unroll
;                     for (int gp = 0; gp < 2; ++gp) {
;                         const u32x4 a4 = *(const u32x4*)(ga + ((it * 2 + jt) * 2 + gp) * 1024), b4 = *(const u32x4*)(gb + ((it * 2 + jt) * 2 + gp) * 1024);
; #pragma unroll
;                         for (int e = 0; e < 4; ++e) {
;                             acc[it][jt][8 * gp + 2 * e] *= bf_lo(a4[e]) * __builtin_amdgcn_rcpf(fmaxf(bf_lo(b4[e]), 8.6736174e-19f));
;                             acc[it][jt][8 * gp + 2 * e + 1] *= bf_hi(a4[e]) * __builtin_amdgcn_rcpf(fmaxf(bf_hi(b4[e]), 8.6736174e-19f));
;                         }
;                     }
	v_lshlrev_b32_e32 v140, 16, v144
	v_and_b32_e32 v141, 0xffff0000, v144
	v_max_f32_e32 v140, v140, v140
	v_max_f32_e32 v141, v141, v141
	v_max_f32_e32 v140, 0x21800000, v140
	v_max_f32_e32 v141, 0x21800000, v141
	v_rcp_f32_e32 v140, v140
	v_rcp_f32_e32 v141, v141
	v_pk_mul_f32 v[110:111], v[110:111], v[128:129]
	v_lshlrev_b32_e32 v128, 16, v164
	v_and_b32_e32 v129, 0xffff0000, v164
	v_pk_mul_f32 v[128:129], v[140:141], v[128:129]
	v_lshlrev_b32_e32 v140, 16, v145
	v_and_b32_e32 v141, 0xffff0000, v145
	v_max_f32_e32 v140, v140, v140
	v_max_f32_e32 v141, v141, v141
	v_max_f32_e32 v140, 0x21800000, v140
	v_max_f32_e32 v141, 0x21800000, v141
	v_rcp_f32_e32 v140, v140
	v_rcp_f32_e32 v141, v141
	v_pk_mul_f32 v[32:33], v[32:33], v[128:129]
	v_lshlrev_b32_e32 v128, 16, v165
	v_and_b32_e32 v129, 0xffff0000, v165
	v_pk_mul_f32 v[144:145], v[140:141], v[128:129]
	v_add_co_u32_e32 v128, vcc, s45, v152
	v_lshlrev_b32_e32 v148, 16, v146
	s_nop 0
	v_addc_co_u32_e32 v129, vcc, 0, v153, vcc
	global_load_dwordx4 v[140:143], v[128:129], off offset:-4096
	v_and_b32_e32 v146, 0xffff0000, v146
	v_max_f32_e32 v146, v146, v146
	v_max_f32_e32 v148, v148, v148
	v_max_f32_e32 v146, 0x21800000, v146
	v_max_f32_e32 v148, 0x21800000, v148
	v_rcp_f32_e32 v149, v146
	v_lshlrev_b32_e32 v146, 16, v147
	v_and_b32_e32 v147, 0xffff0000, v147
	v_rcp_f32_e32 v148, v148
	v_max_f32_e32 v146, v146, v146
	v_max_f32_e32 v147, v147, v147
	v_max_f32_e32 v146, 0x21800000, v146
	v_max_f32_e32 v147, 0x21800000, v147
	v_rcp_f32_e32 v146, v146
	v_rcp_f32_e32 v147, v147
	v_pk_mul_f32 v[34:35], v[34:35], v[144:145]
	v_lshlrev_b32_e32 v144, 16, v166
	v_and_b32_e32 v145, 0xffff0000, v166
	v_pk_mul_f32 v[144:145], v[148:149], v[144:145]
	v_add_co_u32_e32 v160, vcc, s43, v152
	v_pk_mul_f32 v[36:37], v[36:37], v[144:145]
	v_lshlrev_b32_e32 v144, 16, v167
	v_and_b32_e32 v145, 0xffff0000, v167
	v_pk_mul_f32 v[144:145], v[146:147], v[144:145]
	s_waitcnt vmcnt(3)
	v_lshlrev_b32_e32 v146, 16, v136
	v_and_b32_e32 v136, 0xffff0000, v136
	v_max_f32_e32 v146, v146, v146
	v_max_f32_e32 v136, v136, v136
	v_max_f32_e32 v146, 0x21800000, v146
	v_max_f32_e32 v136, 0x21800000, v136
	v_rcp_f32_e32 v146, v146
	v_rcp_f32_e32 v147, v136
	v_lshlrev_b32_e32 v136, 16, v137
	v_and_b32_e32 v137, 0xffff0000, v137
	v_max_f32_e32 v136, v136, v136
	v_max_f32_e32 v137, v137, v137
	v_pk_mul_f32 v[38:39], v[38:39], v[144:145]
	s_waitcnt vmcnt(2)
	v_lshlrev_b32_e32 v144, 16, v154
	v_and_b32_e32 v145, 0xffff0000, v154
	v_max_f32_e32 v136, 0x21800000, v136
	v_max_f32_e32 v137, 0x21800000, v137
	v_pk_mul_f32 v[144:145], v[146:147], v[144:145]
	v_rcp_f32_e32 v136, v136
	v_rcp_f32_e32 v137, v137
	v_addc_co_u32_e32 v161, vcc, 0, v153, vcc
	v_pk_mul_f32 v[40:41], v[40:41], v[144:145]
	global_load_dwordx4 v[144:147], v[160:161], off offset:1024
	v_lshlrev_b32_e32 v148, 16, v155
	v_and_b32_e32 v149, 0xffff0000, v155
	v_pk_mul_f32 v[136:137], v[136:137], v[148:149]
	v_lshlrev_b32_e32 v148, 16, v138
	v_max_f32_e32 v148, v148, v148
	v_max_f32_e32 v148, 0x21800000, v148
	v_rcp_f32_e32 v152, v148
	global_load_dwordx4 v[148:151], v[130:131], off offset:1024
	v_and_b32_e32 v138, 0xffff0000, v138
	v_max_f32_e32 v138, v138, v138
	v_max_f32_e32 v138, 0x21800000, v138
	v_rcp_f32_e32 v153, v138
	v_lshlrev_b32_e32 v138, 16, v139
	v_and_b32_e32 v139, 0xffff0000, v139
	v_max_f32_e32 v138, v138, v138
	v_max_f32_e32 v139, v139, v139
	v_max_f32_e32 v138, 0x21800000, v138
	v_max_f32_e32 v139, 0x21800000, v139
	v_rcp_f32_e32 v138, v138
	v_rcp_f32_e32 v139, v139
	v_pk_mul_f32 v[42:43], v[42:43], v[136:137]
	v_lshlrev_b32_e32 v136, 16, v156
	v_and_b32_e32 v137, 0xffff0000, v156
	v_pk_mul_f32 v[136:137], v[152:153], v[136:137]
	s_waitcnt vmcnt(2)
	v_lshlrev_b32_e32 v154, 16, v140
	v_pk_mul_f32 v[44:45], v[44:45], v[136:137]
	v_lshlrev_b32_e32 v136, 16, v157
	v_and_b32_e32 v137, 0xffff0000, v157
	v_pk_mul_f32 v[152:153], v[138:139], v[136:137]
	v_and_b32_e32 v140, 0xffff0000, v140
	v_pk_mul_f32 v[46:47], v[46:47], v[152:153]
	v_lshlrev_b32_e32 v152, 16, v132
	v_and_b32_e32 v153, 0xffff0000, v132
	v_lshlrev_b32_e32 v132, 16, v141
	v_max_f32_e32 v140, v140, v140
	v_max_f32_e32 v132, v132, v132
	v_max_f32_e32 v140, 0x21800000, v140
	v_max_f32_e32 v132, 0x21800000, v132
	v_max_f32_e32 v154, v154, v154
	v_rcp_f32_e32 v155, v140
	v_rcp_f32_e32 v140, v132
	v_and_b32_e32 v132, 0xffff0000, v141
	v_max_f32_e32 v154, 0x21800000, v154
	v_max_f32_e32 v132, v132, v132
	v_rcp_f32_e32 v154, v154
	v_max_f32_e32 v132, 0x21800000, v132
	v_rcp_f32_e32 v141, v132
	v_lshlrev_b32_e32 v132, 16, v133
	v_pk_mul_f32 v[156:157], v[154:155], v[152:153]
	global_load_dwordx4 v[152:155], v[160:161], off offset:2048
	v_and_b32_e32 v133, 0xffff0000, v133
	v_pk_mul_f32 v[140:141], v[140:141], v[132:133]
	v_lshlrev_b32_e32 v132, 16, v142
	v_max_f32_e32 v132, v132, v132
	global_load_dwordx4 v[136:139], v[130:131], off offset:3072
	v_pk_mul_f32 v[80:81], v[80:81], v[156:157]
	v_max_f32_e32 v156, 0x21800000, v132
	global_load_dwordx4 v[130:133], v[130:131], off offset:2048
	v_and_b32_e32 v142, 0xffff0000, v142
	v_max_f32_e32 v142, v142, v142
	v_max_f32_e32 v142, 0x21800000, v142
	v_rcp_f32_e32 v156, v156
	v_rcp_f32_e32 v157, v142
	v_pk_mul_f32 v[82:83], v[82:83], v[140:141]
	v_lshlrev_b32_e32 v140, 16, v134
	v_and_b32_e32 v141, 0xffff0000, v134
	v_lshlrev_b32_e32 v134, 16, v143
	v_max_f32_e32 v134, v134, v134
	v_max_f32_e32 v134, 0x21800000, v134
	v_rcp_f32_e32 v142, v134
	v_and_b32_e32 v134, 0xffff0000, v143
	v_pk_mul_f32 v[140:141], v[156:157], v[140:141]
	v_max_f32_e32 v134, v134, v134
	v_max_f32_e32 v134, 0x21800000, v134
	v_pk_mul_f32 v[84:85], v[84:85], v[140:141]
	s_waitcnt vmcnt(4)
; DI float bf_lo(unsigned u) { return __uint_as_float(u << 16); }
; DI float bf_hi(unsigned u) { return __uint_as_float(u & 0xffff0000u); }
; DI void phase4(const Params& p, unsigned char* smem, int tid) {
;     ...
;             const unsigned char* ga = ws + OFF_G + ((size_t)(f * 64 + tt) * 8 + (te >> 6)) * 16384 + (te & 63) * 16;
;             const unsigned char* gb = ga + (size_t)4 * 64 * 8 * 16384;
; #pragma unroll
;             for (int it = 0; it < 4; ++it)
; #pragma unroll
;                 for (int jt = 0; jt < 2; ++jt)
; #pragma unroll
;                     for (int gp = 0; gp < 2; ++gp) {
;                         const u32x4 a4 = *(const u32x4*)(ga + ((it * 2 + jt) * 2 + gp) * 1024), b4 = *(const u32x4*)(gb + ((it * 2 + jt) * 2 + gp) * 1024);
; #pragma unroll
;                         for (int e = 0; e < 4; ++e) {
;                             acc[it][jt][8 * gp + 2 * e] *= bf_lo(a4[e]) * __builtin_amdgcn_rcpf(fmaxf(bf_lo(b4[e]), 8.6736174e-19f));
;                             acc[it][jt][8 * gp + 2 * e + 1] *= bf_hi(a4[e]) * __builtin_amdgcn_rcpf(fmaxf(bf_hi(b4[e]), 8.6736174e-19f));
;                         }
;                     }
	v_lshlrev_b32_e32 v140, 16, v144
	v_and_b32_e32 v141, 0xffff0000, v144
	v_rcp_f32_e32 v143, v134
	v_max_f32_e32 v140, v140, v140
	v_max_f32_e32 v141, v141, v141
	v_max_f32_e32 v140, 0x21800000, v140
	v_max_f32_e32 v141, 0x21800000, v141
	v_rcp_f32_e32 v140, v140
	v_rcp_f32_e32 v141, v141
	v_lshlrev_b32_e32 v134, 16, v135
	v_and_b32_e32 v135, 0xffff0000, v135
	v_pk_mul_f32 v[134:135], v[142:143], v[134:135]
	s_nop 0
	v_pk_mul_f32 v[86:87], v[86:87], v[134:135]
	s_waitcnt vmcnt(3)
	v_lshlrev_b32_e32 v134, 16, v148
	v_and_b32_e32 v135, 0xffff0000, v148
	v_pk_mul_f32 v[134:135], v[140:141], v[134:135]
	v_lshlrev_b32_e32 v140, 16, v145
	v_max_f32_e32 v140, v140, v140
	v_max_f32_e32 v140, 0x21800000, v140
	v_rcp_f32_e32 v144, v140
	v_and_b32_e32 v140, 0xffff0000, v145
	v_max_f32_e32 v140, v140, v140
	v_max_f32_e32 v145, 0x21800000, v140
	global_load_dwordx4 v[140:143], v[160:161], off offset:3072
	v_rcp_f32_e32 v145, v145
	v_pk_mul_f32 v[88:89], v[88:89], v[134:135]
	v_lshlrev_b32_e32 v134, 16, v149
	v_and_b32_e32 v135, 0xffff0000, v149
	v_pk_mul_f32 v[134:135], v[144:145], v[134:135]
	v_lshlrev_b32_e32 v144, 16, v146
	v_and_b32_e32 v145, 0xffff0000, v146
	v_max_f32_e32 v144, v144, v144
	v_max_f32_e32 v145, v145, v145
	v_max_f32_e32 v144, 0x21800000, v144
	v_max_f32_e32 v145, 0x21800000, v145
	v_rcp_f32_e32 v144, v144
	v_rcp_f32_e32 v145, v145
	v_pk_mul_f32 v[90:91], v[90:91], v[134:135]
	v_lshlrev_b32_e32 v134, 16, v150
	v_and_b32_e32 v135, 0xffff0000, v150
	v_pk_mul_f32 v[134:135], v[144:145], v[134:135]
	v_lshlrev_b32_e32 v144, 16, v147
	v_and_b32_e32 v145, 0xffff0000, v147
	v_max_f32_e32 v144, v144, v144
	v_max_f32_e32 v145, v145, v145
	v_max_f32_e32 v144, 0x21800000, v144
	v_max_f32_e32 v145, 0x21800000, v145
	v_rcp_f32_e32 v144, v144
	v_rcp_f32_e32 v145, v145
	v_pk_mul_f32 v[92:93], v[92:93], v[134:135]
	v_lshlrev_b32_e32 v134, 16, v151
	v_and_b32_e32 v135, 0xffff0000, v151
	v_pk_mul_f32 v[134:135], v[144:145], v[134:135]
	s_waitcnt vmcnt(3)
	v_lshlrev_b32_e32 v144, 16, v152
	v_and_b32_e32 v145, 0xffff0000, v152
	v_max_f32_e32 v144, v144, v144
	v_max_f32_e32 v145, v145, v145
	v_max_f32_e32 v144, 0x21800000, v144
	v_max_f32_e32 v145, 0x21800000, v145
	v_rcp_f32_e32 v144, v144
	v_rcp_f32_e32 v145, v145
	v_pk_mul_f32 v[94:95], v[94:95], v[134:135]
	s_waitcnt vmcnt(1)
	v_lshlrev_b32_e32 v134, 16, v130
	v_and_b32_e32 v135, 0xffff0000, v130
	v_lshlrev_b32_e32 v130, 16, v153
	v_max_f32_e32 v130, v130, v130
	v_max_f32_e32 v130, 0x21800000, v130
	v_rcp_f32_e32 v148, v130
	v_and_b32_e32 v130, 0xffff0000, v153
	v_pk_mul_f32 v[134:135], v[144:145], v[134:135]
	v_max_f32_e32 v130, v130, v130
	global_load_dwordx4 v[144:147], v[128:129], off
	v_max_f32_e32 v130, 0x21800000, v130
	v_rcp_f32_e32 v149, v130
	v_lshlrev_b32_e32 v130, 16, v131
	v_and_b32_e32 v131, 0xffff0000, v131
	v_pk_mul_f32 v[48:49], v[48:49], v[134:135]
	v_pk_mul_f32 v[130:131], v[148:149], v[130:131]
	v_lshlrev_b32_e32 v134, 16, v154
	global_load_dwordx4 v[148:151], v[158:159], off
	v_and_b32_e32 v135, 0xffff0000, v154
	v_max_f32_e32 v134, v134, v134
	v_max_f32_e32 v135, v135, v135
	v_max_f32_e32 v134, 0x21800000, v134
	v_max_f32_e32 v135, 0x21800000, v135
	v_rcp_f32_e32 v134, v134
	v_rcp_f32_e32 v135, v135
	v_pk_mul_f32 v[50:51], v[50:51], v[130:131]
	v_lshlrev_b32_e32 v130, 16, v132
	v_and_b32_e32 v131, 0xffff0000, v132
	v_lshlrev_b32_e32 v132, 16, v155
	v_max_f32_e32 v132, v132, v132
	v_max_f32_e32 v132, 0x21800000, v132
	v_pk_mul_f32 v[130:131], v[134:135], v[130:131]
	v_rcp_f32_e32 v134, v132
	v_and_b32_e32 v132, 0xffff0000, v155
	v_max_f32_e32 v132, v132, v132
	v_max_f32_e32 v132, 0x21800000, v132
	v_rcp_f32_e32 v135, v132
	v_pk_mul_f32 v[52:53], v[52:53], v[130:131]
	v_lshlrev_b32_e32 v130, 16, v133
	v_and_b32_e32 v131, 0xffff0000, v133
	v_pk_mul_f32 v[130:131], v[134:135], v[130:131]
	s_waitcnt vmcnt(2)
	v_lshlrev_b32_e32 v132, 16, v140
	v_and_b32_e32 v133, 0xffff0000, v140
	v_max_f32_e32 v132, v132, v132
	v_max_f32_e32 v133, v133, v133
	v_max_f32_e32 v132, 0x21800000, v132
	v_max_f32_e32 v133, 0x21800000, v133
	v_rcp_f32_e32 v132, v132
	v_rcp_f32_e32 v133, v133
	v_pk_mul_f32 v[54:55], v[54:55], v[130:131]
	v_lshlrev_b32_e32 v130, 16, v136
	v_and_b32_e32 v131, 0xffff0000, v136
	v_pk_mul_f32 v[134:135], v[132:133], v[130:131]
	v_lshlrev_b32_e32 v130, 16, v141
	v_max_f32_e32 v130, v130, v130
	v_max_f32_e32 v130, 0x21800000, v130
	v_rcp_f32_e32 v140, v130
	v_and_b32_e32 v130, 0xffff0000, v141
	v_max_f32_e32 v130, v130, v130
	v_max_f32_e32 v130, 0x21800000, v130
	v_rcp_f32_e32 v141, v130
	global_load_dwordx4 v[130:133], v[128:129], off offset:1024
	v_pk_mul_f32 v[56:57], v[56:57], v[134:135]
	v_lshlrev_b32_e32 v134, 16, v137
	v_and_b32_e32 v135, 0xffff0000, v137
	v_pk_mul_f32 v[140:141], v[140:141], v[134:135]
	v_lshlrev_b32_e32 v134, 16, v142
	v_max_f32_e32 v134, v134, v134
	v_max_f32_e32 v134, 0x21800000, v134
	v_rcp_f32_e32 v152, v134
	global_load_dwordx4 v[134:137], v[158:159], off offset:1024
	v_and_b32_e32 v142, 0xffff0000, v142
	v_max_f32_e32 v142, v142, v142
	v_max_f32_e32 v142, 0x21800000, v142
	v_rcp_f32_e32 v153, v142
	v_pk_mul_f32 v[58:59], v[58:59], v[140:141]
	v_lshlrev_b32_e32 v140, 16, v138
	v_and_b32_e32 v141, 0xffff0000, v138
	v_lshlrev_b32_e32 v138, 16, v143
	v_max_f32_e32 v138, v138, v138
	v_max_f32_e32 v138, 0x21800000, v138
	v_rcp_f32_e32 v142, v138
	v_and_b32_e32 v138, 0xffff0000, v143
	v_pk_mul_f32 v[140:141], v[152:153], v[140:141]
	v_max_f32_e32 v138, v138, v138
	v_max_f32_e32 v138, 0x21800000, v138
	v_pk_mul_f32 v[60:61], v[60:61], v[140:141]
	v_rcp_f32_e32 v143, v138
	v_lshlrev_b32_e32 v138, 16, v139
	s_waitcnt vmcnt(3)
; DI float bf_lo(unsigned u) { return __uint_as_float(u << 16); }
; DI float bf_hi(unsigned u) { return __uint_as_float(u & 0xffff0000u); }
; DI void phase4(const Params& p, unsigned char* smem, int tid) {
;     ...
;             const unsigned char* ga = ws + OFF_G + ((size_t)(f * 64 + tt) * 8 + (te >> 6)) * 16384 + (te & 63) * 16;
;             const unsigned char* gb = ga + (size_t)4 * 64 * 8 * 16384;
; #pragma unroll
;             for (int it = 0; it < 4; ++it)
; #pragma unroll
;                 for (int jt = 0; jt < 2; ++jt)
; #pragma unroll
;                     for (int gp = 0; gp < 2; ++gp) {
;                         const u32x4 a4 = *(const u32x4*)(ga + ((it * 2 + jt) * 2 + gp) * 1024), b4 = *(const u32x4*)(gb + ((it * 2 + jt) * 2 + gp) * 1024);
; #pragma unroll
;                         for (int e = 0; e < 4; ++e) {
;                             acc[it][jt][8 * gp + 2 * e] *= bf_lo(a4[e]) * __builtin_amdgcn_rcpf(fmaxf(bf_lo(b4[e]), 8.6736174e-19f));
;                             acc[it][jt][8 * gp + 2 * e + 1] *= bf_hi(a4[e]) * __builtin_amdgcn_rcpf(fmaxf(bf_hi(b4[e]), 8.6736174e-19f));
;                         }
;                     }
	v_lshlrev_b32_e32 v140, 16, v144
	v_and_b32_e32 v141, 0xffff0000, v144
	v_max_f32_e32 v140, v140, v140
	v_max_f32_e32 v141, v141, v141
	v_max_f32_e32 v140, 0x21800000, v140
	v_max_f32_e32 v141, 0x21800000, v141
	v_rcp_f32_e32 v140, v140
	v_rcp_f32_e32 v141, v141
	v_and_b32_e32 v139, 0xffff0000, v139
	v_pk_mul_f32 v[138:139], v[142:143], v[138:139]
	s_nop 0
	v_pk_mul_f32 v[62:63], v[62:63], v[138:139]
	s_waitcnt vmcnt(2)
	v_lshlrev_b32_e32 v138, 16, v148
	v_and_b32_e32 v139, 0xffff0000, v148
	v_pk_mul_f32 v[142:143], v[140:141], v[138:139]
	v_lshlrev_b32_e32 v138, 16, v145
	v_max_f32_e32 v138, v138, v138
	v_max_f32_e32 v138, 0x21800000, v138
	v_rcp_f32_e32 v144, v138
	v_and_b32_e32 v138, 0xffff0000, v145
	v_max_f32_e32 v138, v138, v138
	v_max_f32_e32 v145, 0x21800000, v138
	global_load_dwordx4 v[138:141], v[128:129], off offset:2048
	v_rcp_f32_e32 v145, v145
	v_pk_mul_f32 v[64:65], v[64:65], v[142:143]
	v_lshlrev_b32_e32 v142, 16, v149
	v_and_b32_e32 v143, 0xffff0000, v149
	v_pk_mul_f32 v[148:149], v[144:145], v[142:143]
	v_lshlrev_b32_e32 v142, 16, v146
	v_max_f32_e32 v142, v142, v142
	v_max_f32_e32 v152, 0x21800000, v142
	global_load_dwordx4 v[142:145], v[158:159], off offset:2048
	v_and_b32_e32 v146, 0xffff0000, v146
	v_max_f32_e32 v146, v146, v146
	v_max_f32_e32 v146, 0x21800000, v146
	v_rcp_f32_e32 v153, v146
	v_lshlrev_b32_e32 v146, 16, v147
	v_and_b32_e32 v147, 0xffff0000, v147
	v_rcp_f32_e32 v152, v152
	v_max_f32_e32 v146, v146, v146
	v_max_f32_e32 v147, v147, v147
	v_max_f32_e32 v146, 0x21800000, v146
	v_max_f32_e32 v147, 0x21800000, v147
	v_rcp_f32_e32 v146, v146
	v_rcp_f32_e32 v147, v147
	v_pk_mul_f32 v[66:67], v[66:67], v[148:149]
	v_lshlrev_b32_e32 v148, 16, v150
	v_and_b32_e32 v149, 0xffff0000, v150
	v_pk_mul_f32 v[148:149], v[152:153], v[148:149]
	s_nop 0
	v_pk_mul_f32 v[68:69], v[68:69], v[148:149]
	v_lshlrev_b32_e32 v148, 16, v151
	v_and_b32_e32 v149, 0xffff0000, v151
	v_pk_mul_f32 v[146:147], v[146:147], v[148:149]
	s_waitcnt vmcnt(3)
	v_lshlrev_b32_e32 v148, 16, v130
	v_and_b32_e32 v130, 0xffff0000, v130
	v_max_f32_e32 v148, v148, v148
	v_max_f32_e32 v130, v130, v130
	v_max_f32_e32 v148, 0x21800000, v148
	v_max_f32_e32 v130, 0x21800000, v130
	v_rcp_f32_e32 v148, v148
	v_rcp_f32_e32 v149, v130
	v_lshlrev_b32_e32 v130, 16, v131
	v_max_f32_e32 v130, v130, v130
	v_pk_mul_f32 v[70:71], v[70:71], v[146:147]
	s_waitcnt vmcnt(2)
	v_lshlrev_b32_e32 v146, 16, v134
	v_and_b32_e32 v147, 0xffff0000, v134
	v_max_f32_e32 v130, 0x21800000, v130
	v_pk_mul_f32 v[146:147], v[148:149], v[146:147]
	v_rcp_f32_e32 v148, v130
	v_and_b32_e32 v134, 0xffff0000, v131
	global_load_dwordx4 v[128:131], v[128:129], off offset:3072
	v_max_f32_e32 v134, v134, v134
	v_pk_mul_f32 v[72:73], v[72:73], v[146:147]
	v_lshlrev_b32_e32 v146, 16, v132
	v_and_b32_e32 v132, 0xffff0000, v132
	v_max_f32_e32 v134, 0x21800000, v134
	v_max_f32_e32 v132, v132, v132
	v_rcp_f32_e32 v149, v134
	v_max_f32_e32 v146, v146, v146
	v_max_f32_e32 v132, 0x21800000, v132
	v_max_f32_e32 v146, 0x21800000, v146
	v_rcp_f32_e32 v147, v132
	v_lshlrev_b32_e32 v132, 16, v133
	v_and_b32_e32 v133, 0xffff0000, v133
	v_rcp_f32_e32 v146, v146
	v_max_f32_e32 v132, v132, v132
	v_max_f32_e32 v133, v133, v133
	v_lshlrev_b32_e32 v134, 16, v135
	v_and_b32_e32 v135, 0xffff0000, v135
	v_max_f32_e32 v132, 0x21800000, v132
	v_max_f32_e32 v133, 0x21800000, v133
	v_pk_mul_f32 v[134:135], v[148:149], v[134:135]
	v_rcp_f32_e32 v132, v132
	v_rcp_f32_e32 v133, v133
	v_pk_mul_f32 v[74:75], v[74:75], v[134:135]
	v_lshlrev_b32_e32 v134, 16, v136
	v_and_b32_e32 v135, 0xffff0000, v136
	v_pk_mul_f32 v[134:135], v[146:147], v[134:135]
	s_waitcnt vmcnt(0)
	v_lshlrev_b32_e32 v152, 16, v128
	v_pk_mul_f32 v[76:77], v[76:77], v[134:135]
	v_lshlrev_b32_e32 v134, 16, v137
	v_and_b32_e32 v135, 0xffff0000, v137
	v_pk_mul_f32 v[132:133], v[132:133], v[134:135]
	v_lshlrev_b32_e32 v134, 16, v138
	v_and_b32_e32 v135, 0xffff0000, v138
	v_max_f32_e32 v134, v134, v134
	v_max_f32_e32 v135, v135, v135
	v_max_f32_e32 v134, 0x21800000, v134
	v_max_f32_e32 v135, 0x21800000, v135
	v_rcp_f32_e32 v134, v134
	v_rcp_f32_e32 v135, v135
	v_pk_mul_f32 v[78:79], v[78:79], v[132:133]
	v_lshlrev_b32_e32 v132, 16, v142
	v_and_b32_e32 v133, 0xffff0000, v142
	v_pk_mul_f32 v[132:133], v[134:135], v[132:133]
	v_lshlrev_b32_e32 v134, 16, v139
	v_and_b32_e32 v135, 0xffff0000, v139
	v_max_f32_e32 v134, v134, v134
	v_max_f32_e32 v135, v135, v135
	v_max_f32_e32 v134, 0x21800000, v134
	v_max_f32_e32 v135, 0x21800000, v135
	v_rcp_f32_e32 v134, v134
	v_rcp_f32_e32 v135, v135
	v_pk_mul_f32 v[16:17], v[16:17], v[132:133]
	v_lshlrev_b32_e32 v132, 16, v143
	v_and_b32_e32 v133, 0xffff0000, v143
	v_pk_mul_f32 v[132:133], v[134:135], v[132:133]
	v_lshlrev_b32_e32 v134, 16, v140
	v_and_b32_e32 v135, 0xffff0000, v140
	v_max_f32_e32 v134, v134, v134
	v_max_f32_e32 v135, v135, v135
	v_max_f32_e32 v134, 0x21800000, v134
	v_max_f32_e32 v135, 0x21800000, v135
	v_rcp_f32_e32 v134, v134
	v_rcp_f32_e32 v135, v135
	v_pk_mul_f32 v[18:19], v[18:19], v[132:133]
	v_lshlrev_b32_e32 v132, 16, v144
	v_and_b32_e32 v133, 0xffff0000, v144
	v_pk_mul_f32 v[132:133], v[134:135], v[132:133]
	v_lshlrev_b32_e32 v134, 16, v141
	v_and_b32_e32 v135, 0xffff0000, v141
	v_max_f32_e32 v134, v134, v134
	v_max_f32_e32 v135, v135, v135
	v_max_f32_e32 v134, 0x21800000, v134
	v_max_f32_e32 v135, 0x21800000, v135
	v_rcp_f32_e32 v134, v134
	v_rcp_f32_e32 v135, v135
	v_and_b32_e32 v128, 0xffff0000, v128
	v_max_f32_e32 v128, v128, v128
	v_ashrrev_i32_e32 v182, 2, v210
	v_max_f32_e32 v152, v152, v152
	v_max_f32_e32 v128, 0x21800000, v128
	v_pk_mul_f32 v[20:21], v[20:21], v[132:133]
	v_lshlrev_b32_e32 v132, 16, v145
; DI float bf_lo(unsigned u) { return __uint_as_float(u << 16); }
; DI float bf_hi(unsigned u) { return __uint_as_float(u & 0xffff0000u); }
; #define G_LOAD(pr, qr, kt_) if (MODE != 1) { _Pragma("unroll") for (int r = 0; r < NP; ++r) pr[r] = *(const u32x4*)(pp + (size_t)(r * 128) * ldp + (kt_) * BK); \
;                               _Pragma("unroll") for (int r = 0; r < NQ; ++r) qr[r] = *(const u32x4*)(qp + (size_t)(r * 128) * ldq + (kt_) * BK); }
;     ...
;     const bf16_t* pp = P + (size_t)lrow * ldp + lch * 8;
;     const bf16_t* qp = Q + (size_t)lrow * ldq + lch * 8;
;     unsigned char* wP = lds + lrow * LROW + lch * 16;
;     const unsigned char* rP = lds + (wi * WI * 32 + (lane & 31)) * LROW + (lane >> 5) * 16;
;     const unsigned char* rQ = lds + BI * LROW + (wj * 64 + (lane & 31)) * LROW + (lane >> 5) * 16;
;     u32x4 p0[NP], q0[NQ], p1[NP], q1[NQ], p2[NP], q2[NQ];
;     bf16x8 fa0[WI], fb0[2], fb1[2];
;     if (ZERO) {
; #pragma unroll
;         for (int it = 0; it < WI; ++it)
; #pragma unroll
;             for (int jt = 0; jt < 2; ++jt)
; #pragma unroll
;                 for (int r = 0; r < 16; ++r) acc[it][jt][r] = 0.f;
;     }
;     const int nk = K / BK;
;     ...
;     if (MODE == 1) {
; #pragma unroll
;         for (int r = 0; r < NP; ++r) { p0[r] = *(const u32x4*)(pp + (size_t)(r * 128) * ldp); p1[r] = p0[r]; p2[r] = p0[r]; }
; #pragma unroll
;         for (int r = 0; r < NQ; ++r) { q0[r] = *(const u32x4*)(qp + (size_t)(r * 128) * ldq); q1[r] = q0[r]; q2[r] = q0[r]; }
;     }
;     G_LOAD(p0, q0, 0)
;     G_LOAD(p1, q1, 1)
;     G_LOAD(p2, q2, 2)
;     G_STORE(p0, q0, 0)
;     G_LOAD(p0, q0, 3)
;     G_STORE(p1, q1, STAGE)
;     __syncthreads();
;     F_LOAD(fa0, fb0, 0, 0)
; DI void phase4(const Params& p, unsigned char* smem, int tid) {
;     ...
;                             acc[it][jt][8 * gp + 2 * e] *= bf_lo(a4[e]) * __builtin_amdgcn_rcpf(fmaxf(bf_lo(b4[e]), 8.6736174e-19f));
;                             acc[it][jt][8 * gp + 2 * e + 1] *= bf_hi(a4[e]) * __builtin_amdgcn_rcpf(fmaxf(bf_hi(b4[e]), 8.6736174e-19f));
;                         }
;                     }
	v_and_b32_e32 v133, 0xffff0000, v145
	v_ashrrev_i32_e32 v183, 31, v182
	v_max_f32_e32 v152, 0x21800000, v152
	v_rcp_f32_e32 v153, v128
	v_lshlrev_b32_e32 v128, 16, v129
	v_and_b32_e32 v129, 0xffff0000, v129
	v_pk_mul_f32 v[148:149], v[134:135], v[132:133]
	v_lshlrev_b64 v[190:191], 11, v[182:183]
	v_lshlrev_b32_e32 v134, 4, v210
	v_rcp_f32_e32 v152, v152
	v_max_f32_e32 v128, v128, v128
	v_max_f32_e32 v129, v129, v129
	v_lshl_add_u64 v[132:133], s[58:59], 0, v[190:191]
	s_mov_b64 s[98:99], s[58:59]
	v_and_b32_e32 v212, 48, v134
	v_max_f32_e32 v128, 0x21800000, v128
	v_max_f32_e32 v129, 0x21800000, v129
	v_lshl_add_u64 v[184:185], v[132:133], 0, v[212:213]
	v_add_u32_e32 v250, v190, v212
	v_add_u32_e32 v251, 0x40000, v250
	v_rcp_f32_e32 v128, v128
	v_rcp_f32_e32 v129, v129
	v_lshl_add_u64 v[140:141], s[18:19], 0, v[190:191]
	s_mov_b64 s[100:101], s[18:19]
	v_add_co_u32_e32 v150, vcc, s34, v184
	v_pk_mul_f32 v[22:23], v[22:23], v[148:149]
	v_lshlrev_b32_e32 v148, 16, v178
	v_and_b32_e32 v149, 0xffff0000, v178
	v_addc_co_u32_e32 v151, vcc, 0, v185, vcc
	v_lshl_add_u64 v[186:187], v[140:141], 0, v[212:213]
	v_pk_mul_f32 v[148:149], v[152:153], v[148:149]
	v_add_co_u32_e32 v188, vcc, s34, v186
	v_pk_mul_f32 v[24:25], v[24:25], v[148:149]
	v_lshlrev_b32_e32 v148, 16, v179
	v_and_b32_e32 v149, 0xffff0000, v179
	v_addc_co_u32_e32 v189, vcc, 0, v187, vcc
	v_pk_mul_f32 v[128:129], v[128:129], v[148:149]
	v_lshlrev_b32_e32 v148, 16, v130
	global_load_dwordx4 v[132:135], v[184:185], off
	global_load_dwordx4 v[136:139], v[150:151], off
	global_load_dwordx4 v[140:143], v[186:187], off
	global_load_dwordx4 v[144:147], v[188:189], off
	global_load_dwordx4 v[192:195], v[184:185], off offset:64
	global_load_dwordx4 v[196:199], v[150:151], off offset:64
	global_load_dwordx4 v[200:203], v[186:187], off offset:64
	v_max_f32_e32 v148, v148, v148
	global_load_dwordx4 v[204:207], v[188:189], off offset:64
	v_max_f32_e32 v148, 0x21800000, v148
	v_rcp_f32_e32 v208, v148
	global_load_dwordx4 v[176:179], v[184:185], off offset:128
	global_load_dwordx4 v[160:163], v[184:185], off offset:192
	global_load_dwordx4 v[172:175], v[150:151], off offset:128
	global_load_dwordx4 v[156:159], v[150:151], off offset:192
	global_load_dwordx4 v[168:171], v[186:187], off offset:128
	global_load_dwordx4 v[152:155], v[186:187], off offset:192
	global_load_dwordx4 v[164:167], v[188:189], off offset:128
	s_nop 0
	global_load_dwordx4 v[148:151], v[188:189], off offset:192
	v_and_b32_e32 v130, 0xffff0000, v130
	v_max_f32_e32 v130, v130, v130
	v_max_f32_e32 v130, 0x21800000, v130
	v_rcp_f32_e32 v209, v130
	v_lshlrev_b32_e32 v130, 16, v131
	v_and_b32_e32 v131, 0xffff0000, v131
	v_max_f32_e32 v130, v130, v130
	v_max_f32_e32 v131, v131, v131
	v_max_f32_e32 v130, 0x21800000, v130
	v_max_f32_e32 v131, 0x21800000, v131
	v_rcp_f32_e32 v130, v130
	v_rcp_f32_e32 v131, v131
	v_pk_mul_f32 v[26:27], v[26:27], v[128:129]
	v_lshlrev_b32_e32 v128, 16, v180
	v_and_b32_e32 v129, 0xffff0000, v180
	v_pk_mul_f32 v[128:129], v[208:209], v[128:129]
	v_lshrrev_b32_e32 v180, 1, v210
	v_pk_mul_f32 v[28:29], v[28:29], v[128:129]
	v_lshlrev_b32_e32 v128, 16, v181
	v_and_b32_e32 v129, 0xffff0000, v181
	v_pk_mul_f32 v[128:129], v[130:131], v[128:129]
	v_and_b32_e32 v131, 31, v210
	v_pk_mul_f32 v[30:31], v[30:31], v[128:129]
	v_ashrrev_i32_e32 v128, 6, v210
	v_lshrrev_b32_e32 v129, 30, v128
	v_add_u32_e32 v129, v128, v129
	v_and_b32_e32 v130, 0x3ffffc, v129
	v_lshlrev_b32_e32 v129, 5, v129
	v_sub_u32_e32 v128, v128, v130
	v_mul_lo_u32 v130, v182, s31
	v_and_or_b32 v129, v129, s33, v131
	v_mul_lo_u32 v129, v129, s31
	v_and_b32_e32 v180, 16, v180
	v_add3_u32 v209, 0, v130, v212
	v_lshl_or_b32 v128, v128, 6, v131
	v_add3_u32 v208, 0, v129, v180
	s_waitcnt vmcnt(15)
	ds_write_b128 v209, v[132:135] offset:2048
	s_waitcnt vmcnt(14)
	ds_write_b128 v209, v[136:139] offset:12288
	s_waitcnt vmcnt(13)
	ds_write_b128 v209, v[140:143] offset:22528
	s_waitcnt vmcnt(12)
	ds_write_b128 v209, v[144:147] offset:32768
	s_waitcnt vmcnt(11)
	ds_write_b128 v209, v[192:195] offset:43008
	s_waitcnt vmcnt(10)
	ds_write_b128 v209, v[196:199] offset:53248
	s_waitcnt vmcnt(9)
	ds_write_b128 v209, v[200:203] offset:63488
	v_add_u32_e32 v193, 0x12000, v209
	v_mul_lo_u32 v128, v128, s31
	s_waitcnt vmcnt(8)
	ds_write_b128 v193, v[204:207]
	s_waitcnt lgkmcnt(0)
	s_barrier
	ds_read_b128 v[144:147], v208 offset:2048
	ds_read_b128 v[140:143], v208 offset:4608
	ds_read_b128 v[136:139], v208 offset:7168
	ds_read_b128 v[132:135], v208 offset:9728
	v_add3_u32 v211, 0, v128, v180
	ds_read_b128 v[180:183], v211 offset:22528
	ds_read_b128 v[128:131], v211 offset:25088
	s_add_u32 s18, s56, s54
	s_addc_u32 s19, s57, 0
	s_add_u32 s12, s56, s12
	s_addc_u32 s13, s57, s13
	v_add_u32_e32 v210, 0x5800, v211
	v_add_u32_e32 v192, 0x19800, v209
	v_add_u32_e32 v195, 0x14800, v209
	v_add_u32_e32 v197, 0x14800, v208
	v_add_u32_e32 v198, 0x19800, v211
	v_add_u32_e32 v194, 0x17000, v209
	v_add_u32_e32 v196, 0x1c000, v209
	v_add_u32_e32 v199, 0x1a200, v211
	v_add_u32_e32 v200, 0x15200, v208
	v_add_u32_e32 v201, 0x15c00, v208
	v_add_u32_e32 v202, 0x16600, v208
	v_add_u32_e32 v203, 0x19820, v211
	v_add_u32_e32 v204, 0x14820, v208
	v_add_u32_e32 v205, 0x1a220, v211
	v_add_u32_e32 v206, 0x15220, v208
	v_add_u32_e32 v207, 0x15c20, v208
	v_add_u32_e32 v214, 0x16620, v208
	v_lshl_add_u64 v[188:189], s[18:19], 0, v[190:191]
	v_lshl_add_u64 v[190:191], s[12:13], 0, v[190:191]
; #define G_LOAD(pr, qr, kt_) if (MODE != 1) { _Pragma("unroll") for (int r = 0; r < NP; ++r) pr[r] = *(const u32x4*)(pp + (size_t)(r * 128) * ldp + (kt_) * BK); \
;                               _Pragma("unroll") for (int r = 0; r < NQ; ++r) qr[r] = *(const u32x4*)(qp + (size_t)(r * 128) * ldq + (kt_) * BK); }
; #define G_STORE(pr, qr, so_) { unsigned char* w_ = wP + (so_); \
;                               _Pragma("unroll") for (int r = 0; r < NP; ++r) *(u32x4*)(w_ + r * 128 * LROW) = pr[r]; \
;                               _Pragma("unroll") for (int r = 0; r < NQ; ++r) *(u32x4*)(w_ + BI * LROW + r * 128 * LROW) = qr[r]; }
; #define F_LOAD(fa, fb, so_, ks_) { _Pragma("unroll") for (int it = 0; it < WI; ++it) fa[it] = *(const bf16x8*)(rP + (so_) + it * 32 * LROW + (ks_) * 32); \
;                                   _Pragma("unroll") for (int jt = 0; jt < 2; ++jt) fb[jt] = *(const bf16x8*)(rQ + (so_) + jt * 32 * LROW + (ks_) * 32); }
; #define G_LOAD(pr, qr, kt_) if (MODE != 1) { _Pragma("unroll") for (int r = 0; r < NP; ++r) pr[r] = *(const u32x4*)(pp + (size_t)(r * 128) * ldp + (kt_) * BK); \
;                               _Pragma("unroll") for (int r = 0; r < NQ; ++r) qr[r] = *(const u32x4*)(qp + (size_t)(r * 128) * ldq + (kt_) * BK); }
; #define G_STORE(pr, qr, so_) { unsigned char* w_ = wP + (so_); \
;                               _Pragma("unroll") for (int r = 0; r < NP; ++r) *(u32x4*)(w_ + r * 128 * LROW) = pr[r]; \
;                               _Pragma("unroll") for (int r = 0; r < NQ; ++r) *(u32x4*)(w_ + BI * LROW + r * 128 * LROW) = qr[r]; }
;     ...
;     if (MODE == 1) {
; #pragma unroll
;         for (int r = 0; r < NP; ++r) { p0[r] = *(const u32x4*)(pp + (size_t)(r * 128) * ldp); p1[r] = p0[r]; p2[r] = p0[r]; }
; #pragma unroll
;         for (int r = 0; r < NQ; ++r) { q0[r] = *(const u32x4*)(qp + (size_t)(r * 128) * ldq); q1[r] = q0[r]; q2[r] = q0[r]; }
;     }
;     G_LOAD(p0, q0, 0)
;     G_LOAD(p1, q1, 1)
;     G_LOAD(p2, q2, 2)
;     G_STORE(p0, q0, 0)
;     G_LOAD(p0, q0, 3)
;     G_STORE(p1, q1, STAGE)
;     __syncthreads();
;     F_LOAD(fa0, fb0, 0, 0)
;     int cur = 0, nxt = STAGE, wr = 2 * STAGE;
;     int kt = 0;
; #pragma unroll 1
;     for (; kt + 3 <= nk; kt += 3) {
;         G_HALF(p1, q1, p2, q2, kt)
;         G_HALF(p2, q2, p0, q0, kt + 1)
;         G_HALF(p0, q0, p1, q1, kt + 2)
;     }
.LBB0_995:
	s_waitcnt lgkmcnt(1)
	v_mfma_f32_32x32x16_bf16 v[112:127], v[144:147], v[180:183], v[112:127]
	ds_read_b128 v[216:219], v211 offset:22560
	s_waitcnt vmcnt(7)
	ds_write_b128 v195, v[176:179]
	s_waitcnt lgkmcnt(2)
	v_mfma_f32_32x32x16_bf16 v[0:15], v[144:147], v[128:131], v[0:15]
	ds_read_b128 v[176:179], v208 offset:2080
	global_load_dwordx4 v[144:147], v250, s[98:99] offset:256
	v_mfma_f32_32x32x16_bf16 v[96:111], v[140:143], v[180:183], v[96:111]
	ds_read_b128 v[222:225], v211 offset:25120
	s_waitcnt vmcnt(6)
	ds_write_b128 v194, v[172:175]
	v_mfma_f32_32x32x16_bf16 v[32:47], v[140:143], v[128:131], v[32:47]
	ds_read_b128 v[172:175], v208 offset:4640
	global_load_dwordx4 v[140:143], v251, s[98:99] offset:256
	v_mfma_f32_32x32x16_bf16 v[80:95], v[136:139], v[180:183], v[80:95]
	s_waitcnt vmcnt(5)
	ds_write_b128 v192, v[168:171]
	v_mfma_f32_32x32x16_bf16 v[48:63], v[136:139], v[128:131], v[48:63]
	ds_read_b128 v[168:171], v208 offset:7200
	global_load_dwordx4 v[136:139], v250, s[100:101] offset:256
	v_mfma_f32_32x32x16_bf16 v[64:79], v[132:135], v[180:183], v[64:79]
	s_waitcnt vmcnt(4)
	ds_write_b128 v196, v[164:167]
	v_mfma_f32_32x32x16_bf16 v[16:31], v[132:135], v[128:131], v[16:31]
	ds_read_b128 v[132:135], v208 offset:9760
	global_load_dwordx4 v[128:131], v251, s[100:101] offset:256
	s_waitcnt lgkmcnt(7)
	v_mfma_f32_32x32x16_bf16 v[112:127], v[176:179], v[216:219], v[112:127]
	ds_read_b128 v[164:167], v211 offset:63488
	s_waitcnt lgkmcnt(7)
	v_mfma_f32_32x32x16_bf16 v[0:15], v[176:179], v[222:225], v[0:15]
	ds_read_b128 v[176:179], v208 offset:43008
	s_waitcnt lgkmcnt(6)
	v_mfma_f32_32x32x16_bf16 v[96:111], v[172:175], v[216:219], v[96:111]
	ds_read_b128 v[180:183], v210 offset:43520
	v_mfma_f32_32x32x16_bf16 v[32:47], v[172:175], v[222:225], v[32:47]
	ds_read_b128 v[172:175], v208 offset:45568
	s_waitcnt lgkmcnt(6)
	v_mfma_f32_32x32x16_bf16 v[80:95], v[168:171], v[216:219], v[80:95]
	v_mfma_f32_32x32x16_bf16 v[48:63], v[168:171], v[222:225], v[48:63]
	ds_read_b128 v[168:171], v208 offset:48128
	s_waitcnt lgkmcnt(5)
	v_mfma_f32_32x32x16_bf16 v[64:79], v[132:135], v[216:219], v[64:79]
	v_mfma_f32_32x32x16_bf16 v[16:31], v[132:135], v[222:225], v[16:31]
	ds_read_b128 v[132:135], v208 offset:50688
	s_barrier
	s_min_u32 s6, s11, 26
	s_waitcnt lgkmcnt(4)
	v_mfma_f32_32x32x16_bf16 v[112:127], v[176:179], v[164:167], v[112:127]
	ds_read_b128 v[216:219], v211 offset:63520
	ds_write_b128 v209, v[160:163] offset:2048
	s_waitcnt lgkmcnt(5)
	v_mfma_f32_32x32x16_bf16 v[0:15], v[176:179], v[180:183], v[0:15]
	global_load_dwordx4 v[176:179], v250, s[98:99] offset:320
	ds_read_b128 v[160:163], v208 offset:43040
	s_waitcnt lgkmcnt(5)
	v_mfma_f32_32x32x16_bf16 v[96:111], v[172:175], v[164:167], v[96:111]
	ds_read_b128 v[222:225], v210 offset:43552
	ds_write_b128 v209, v[156:159] offset:12288
	v_mfma_f32_32x32x16_bf16 v[32:47], v[172:175], v[180:183], v[32:47]
	global_load_dwordx4 v[172:175], v251, s[98:99] offset:320
	ds_read_b128 v[156:159], v208 offset:45600
	s_waitcnt lgkmcnt(7)
	v_mfma_f32_32x32x16_bf16 v[80:95], v[168:171], v[164:167], v[80:95]
	ds_write_b128 v209, v[152:155] offset:22528
	v_mfma_f32_32x32x16_bf16 v[48:63], v[168:171], v[180:183], v[48:63]
	global_load_dwordx4 v[168:171], v250, s[100:101] offset:320
	ds_read_b128 v[152:155], v208 offset:48160
	s_waitcnt lgkmcnt(8)
	v_mfma_f32_32x32x16_bf16 v[64:79], v[132:135], v[164:167], v[64:79]
	s_waitcnt vmcnt(7)
	ds_write_b128 v209, v[148:151] offset:32768
	v_mfma_f32_32x32x16_bf16 v[16:31], v[132:135], v[180:183], v[16:31]
	global_load_dwordx4 v[164:167], v251, s[100:101] offset:320
	ds_read_b128 v[132:135], v208 offset:50720
	s_waitcnt lgkmcnt(7)
	v_mfma_f32_32x32x16_bf16 v[112:127], v[160:163], v[216:219], v[112:127]
	ds_read_b128 v[148:151], v198
	s_waitcnt lgkmcnt(7)
	v_mfma_f32_32x32x16_bf16 v[0:15], v[160:163], v[222:225], v[0:15]
	ds_read_b128 v[160:163], v197
	s_waitcnt lgkmcnt(6)
	v_mfma_f32_32x32x16_bf16 v[96:111], v[156:159], v[216:219], v[96:111]
	ds_read_b128 v[180:183], v199
	v_mfma_f32_32x32x16_bf16 v[32:47], v[156:159], v[222:225], v[32:47]
	ds_read_b128 v[156:159], v200
	s_waitcnt lgkmcnt(6)
	v_mfma_f32_32x32x16_bf16 v[80:95], v[152:155], v[216:219], v[80:95]
	v_mfma_f32_32x32x16_bf16 v[48:63], v[152:155], v[222:225], v[48:63]
	ds_read_b128 v[152:155], v201
	s_waitcnt lgkmcnt(5)
	v_mfma_f32_32x32x16_bf16 v[64:79], v[132:135], v[216:219], v[64:79]
	v_mfma_f32_32x32x16_bf16 v[16:31], v[132:135], v[222:225], v[16:31]
	ds_read_b128 v[132:135], v202
	s_barrier
; #define G_LOAD(pr, qr, kt_) if (MODE != 1) { _Pragma("unroll") for (int r = 0; r < NP; ++r) pr[r] = *(const u32x4*)(pp + (size_t)(r * 128) * ldp + (kt_) * BK); \
;                               _Pragma("unroll") for (int r = 0; r < NQ; ++r) qr[r] = *(const u32x4*)(qp + (size_t)(r * 128) * ldq + (kt_) * BK); }
; #define G_STORE(pr, qr, so_) { unsigned char* w_ = wP + (so_); \
;                               _Pragma("unroll") for (int r = 0; r < NP; ++r) *(u32x4*)(w_ + r * 128 * LROW) = pr[r]; \
;                               _Pragma("unroll") for (int r = 0; r < NQ; ++r) *(u32x4*)(w_ + BI * LROW + r * 128 * LROW) = qr[r]; }
; #define F_LOAD(fa, fb, so_, ks_) { _Pragma("unroll") for (int it = 0; it < WI; ++it) fa[it] = *(const bf16x8*)(rP + (so_) + it * 32 * LROW + (ks_) * 32); \
;                                   _Pragma("unroll") for (int jt = 0; jt < 2; ++jt) fb[jt] = *(const bf16x8*)(rQ + (so_) + jt * 32 * LROW + (ks_) * 32); }
; #define G_LOAD(pr, qr, kt_) if (MODE != 1) { _Pragma("unroll") for (int r = 0; r < NP; ++r) pr[r] = *(const u32x4*)(pp + (size_t)(r * 128) * ldp + (kt_) * BK); \
;                               _Pragma("unroll") for (int r = 0; r < NQ; ++r) qr[r] = *(const u32x4*)(qp + (size_t)(r * 128) * ldq + (kt_) * BK); }
;     ...
;     if (MODE == 1) {
; #pragma unroll
;         for (int r = 0; r < NP; ++r) { p0[r] = *(const u32x4*)(pp + (size_t)(r * 128) * ldp); p1[r] = p0[r]; p2[r] = p0[r]; }
; #pragma unroll
;         for (int r = 0; r < NQ; ++r) { q0[r] = *(const u32x4*)(qp + (size_t)(r * 128) * ldq); q1[r] = q0[r]; q2[r] = q0[r]; }
;     }
;     G_LOAD(p0, q0, 0)
;     G_LOAD(p1, q1, 1)
;     G_LOAD(p2, q2, 2)
;     G_STORE(p0, q0, 0)
;     G_LOAD(p0, q0, 3)
;     G_STORE(p1, q1, STAGE)
;     __syncthreads();
;     F_LOAD(fa0, fb0, 0, 0)
;     int cur = 0, nxt = STAGE, wr = 2 * STAGE;
;     int kt = 0;
; #pragma unroll 1
;     for (; kt + 3 <= nk; kt += 3) {
;         G_HALF(p1, q1, p2, q2, kt)
;         G_HALF(p2, q2, p0, q0, kt + 1)
;         G_HALF(p0, q0, p1, q1, kt + 2)
;     }
;     if (kt < nk) G_HALF(p1, q1, p2, q2, kt)
;     if (kt + 1 < nk) G_HALF(p2, q2, p0, q0, kt + 1)
	s_min_u32 s6, s11, 25
	s_waitcnt lgkmcnt(4)
	v_mfma_f32_32x32x16_bf16 v[112:127], v[160:163], v[148:151], v[112:127]
	ds_read_b128 v[216:219], v203
	s_waitcnt vmcnt(7)
	ds_write_b128 v209, v[144:147] offset:43008
	s_waitcnt lgkmcnt(5)
	v_mfma_f32_32x32x16_bf16 v[0:15], v[160:163], v[180:183], v[0:15]
	global_load_dwordx4 v[160:163], v250, s[98:99] offset:384
	ds_read_b128 v[144:147], v204
	s_waitcnt lgkmcnt(5)
	v_mfma_f32_32x32x16_bf16 v[96:111], v[156:159], v[148:151], v[96:111]
	ds_read_b128 v[222:225], v205
	s_waitcnt vmcnt(7)
	ds_write_b128 v209, v[140:143] offset:53248
	v_mfma_f32_32x32x16_bf16 v[32:47], v[156:159], v[180:183], v[32:47]
	global_load_dwordx4 v[156:159], v251, s[98:99] offset:384
	ds_read_b128 v[140:143], v206
	s_waitcnt lgkmcnt(7)
	v_mfma_f32_32x32x16_bf16 v[80:95], v[152:155], v[148:151], v[80:95]
	s_waitcnt vmcnt(7)
	ds_write_b128 v209, v[136:139] offset:63488
	v_mfma_f32_32x32x16_bf16 v[48:63], v[152:155], v[180:183], v[48:63]
	global_load_dwordx4 v[152:155], v250, s[100:101] offset:384
	ds_read_b128 v[136:139], v207
	s_waitcnt lgkmcnt(8)
	v_mfma_f32_32x32x16_bf16 v[64:79], v[132:135], v[148:151], v[64:79]
	s_waitcnt vmcnt(7)
	ds_write_b128 v193, v[128:131]
	v_mfma_f32_32x32x16_bf16 v[16:31], v[132:135], v[180:183], v[16:31]
	ds_read_b128 v[132:135], v214
	global_load_dwordx4 v[148:151], v251, s[100:101] offset:384
	s_waitcnt lgkmcnt(7)
	v_mfma_f32_32x32x16_bf16 v[112:127], v[144:147], v[216:219], v[112:127]
	ds_read_b128 v[180:183], v211 offset:22528
	s_waitcnt lgkmcnt(7)
	v_mfma_f32_32x32x16_bf16 v[0:15], v[144:147], v[222:225], v[0:15]
	ds_read_b128 v[144:147], v208 offset:2048
	s_waitcnt lgkmcnt(6)
	v_mfma_f32_32x32x16_bf16 v[96:111], v[140:143], v[216:219], v[96:111]
	ds_read_b128 v[128:131], v211 offset:25088
	v_mfma_f32_32x32x16_bf16 v[32:47], v[140:143], v[222:225], v[32:47]
	ds_read_b128 v[140:143], v208 offset:4608
	s_waitcnt lgkmcnt(6)
	v_mfma_f32_32x32x16_bf16 v[80:95], v[136:139], v[216:219], v[80:95]
	v_mfma_f32_32x32x16_bf16 v[48:63], v[136:139], v[222:225], v[48:63]
	ds_read_b128 v[136:139], v208 offset:7168
	s_waitcnt lgkmcnt(5)
	v_mfma_f32_32x32x16_bf16 v[64:79], v[132:135], v[216:219], v[64:79]
	v_mfma_f32_32x32x16_bf16 v[16:31], v[132:135], v[222:225], v[16:31]
	ds_read_b128 v[132:135], v208 offset:9728
	s_add_i32 s11, s11, 3
	v_add_u32_e32 v250, 0xc0, v250
	s_cmp_lt_u32 s11, 30
	v_add_u32_e32 v251, 0xc0, v251
	s_waitcnt lgkmcnt(0)
	s_barrier
	s_cbranch_scc1 .LBB0_995
	v_mfma_f32_32x32x16_bf16 v[112:127], v[144:147], v[180:183], v[112:127]
	ds_read_b128 v[214:217], v211 offset:22560
	s_waitcnt vmcnt(7)
	ds_write_b128 v195, v[176:179]
	ds_read_b128 v[200:203], v208 offset:2080
	v_mfma_f32_32x32x16_bf16 v[96:111], v[140:143], v[180:183], v[96:111]
	ds_read_b128 v[188:191], v211 offset:25120
	s_waitcnt vmcnt(6)
	ds_write_b128 v194, v[172:175]
	ds_read_b128 v[204:207], v208 offset:4640
	v_mfma_f32_32x32x16_bf16 v[80:95], v[136:139], v[180:183], v[80:95]
	s_waitcnt vmcnt(5)
	ds_write_b128 v192, v[168:171]
	ds_read_b128 v[192:195], v208 offset:7200
	v_mfma_f32_32x32x16_bf16 v[64:79], v[132:135], v[180:183], v[64:79]
	s_waitcnt vmcnt(4)
	ds_write_b128 v196, v[164:167]
	ds_read_b128 v[196:199], v208 offset:9760
	s_waitcnt lgkmcnt(7)
	v_mfma_f32_32x32x16_bf16 v[112:127], v[200:203], v[214:217], v[112:127]
	ds_read_b128 v[222:225], v211 offset:63488
	ds_read_b128 v[184:187], v208 offset:43008
	s_waitcnt lgkmcnt(6)
	v_mfma_f32_32x32x16_bf16 v[96:111], v[204:207], v[214:217], v[96:111]
	ds_read_b128 v[164:167], v210 offset:43520
	ds_read_b128 v[176:179], v208 offset:45568
	s_waitcnt lgkmcnt(6)
	v_mfma_f32_32x32x16_bf16 v[80:95], v[192:195], v[214:217], v[80:95]
	ds_read_b128 v[172:175], v208 offset:48128
	s_waitcnt lgkmcnt(5)
	v_mfma_f32_32x32x16_bf16 v[64:79], v[196:199], v[214:217], v[64:79]
	ds_read_b128 v[168:171], v208 offset:50688
	s_waitcnt lgkmcnt(0)
	s_barrier
	v_mfma_f32_32x32x16_bf16 v[112:127], v[184:187], v[222:225], v[112:127]
	ds_read_b128 v[214:217], v211 offset:63520
	s_waitcnt vmcnt(3)
	ds_write_b128 v209, v[160:163] offset:2048
	ds_read_b128 v[180:183], v208 offset:43040
	v_mfma_f32_32x32x16_bf16 v[96:111], v[176:179], v[222:225], v[96:111]
	ds_read_b128 v[160:163], v210 offset:43552
	s_waitcnt vmcnt(2)
	ds_write_b128 v209, v[156:159] offset:12288
	ds_read_b128 v[156:159], v208 offset:45600
	v_mfma_f32_32x32x16_bf16 v[80:95], v[172:175], v[222:225], v[80:95]
	s_waitcnt vmcnt(1)
	ds_write_b128 v209, v[152:155] offset:22528
	ds_read_b128 v[152:155], v208 offset:48160
	v_mfma_f32_32x32x16_bf16 v[64:79], v[168:171], v[222:225], v[64:79]
	s_waitcnt vmcnt(0)
	ds_write_b128 v209, v[148:151] offset:32768
	ds_read_b128 v[148:151], v208 offset:50720
	s_waitcnt lgkmcnt(7)
	v_mfma_f32_32x32x16_bf16 v[112:127], v[180:183], v[214:217], v[112:127]
	s_waitcnt lgkmcnt(4)
	v_mfma_f32_32x32x16_bf16 v[96:111], v[156:159], v[214:217], v[96:111]
	s_waitcnt lgkmcnt(2)
	v_mfma_f32_32x32x16_bf16 v[80:95], v[152:155], v[214:217], v[80:95]
	s_waitcnt lgkmcnt(0)
	v_mfma_f32_32x32x16_bf16 v[64:79], v[148:151], v[214:217], v[64:79]
	s_add_i32 s12, s14, 0x100
	v_mov_b32_e32 v221, v220
	s_ashr_i32 s13, s12, 31
	s_barrier
; DI u32x2 pk4(float a, float b, float c, float d) { u32x2 r; r.x = pk2(a, b); r.y = pk2(c, d); return r; }
; DI float bf_lo(unsigned u) { return __uint_as_float(u << 16); }
; DI float bf_hi(unsigned u) { return __uint_as_float(u & 0xffff0000u); }
; template <int WI, int WGJ, class GetF, class FinF>
; DI void staged_rows(unsigned char* lds, int tid, GetF get, FinF fin) {
;     ...
;     for (int jt = 0; jt < 2; ++jt) {
;         unsigned char* wrow = lds + (wj * 32 + ln) * RS + (wi * WI * 32 + 4 * h) * 2;
; #pragma unroll
;         for (int it = 0; it < WI; ++it)
; #pragma unroll
;             for (int g = 0; g < 4; ++g) *(u32x2*)(wrow + (it * 32 + 8 * g) * 2) = get(it, jt, g);
; DI void phase4(const Params& p, unsigned char* smem, int tid) {
;     ...
;         {
;             int te = tid; asm volatile("" : "+v"(te));
;             const unsigned char* gb = ws + OFF_G + ((size_t)((4 + f) * 64 + tt) * 8 + (te >> 6)) * 16384 + (te & 63) * 16;
;             staged_rows<4, 4>(lds, te,
;                 [&](int it, int jt, int g) { const u32x4 b4 = *(const u32x4*)(gb + ((it * 2 + jt) * 2 + (g >> 1)) * 1024); const int e0 = (g & 1) * 2;
;                     const float g0 = fmaxf(bf_lo(b4[e0]), 8.6736174e-19f), g1 = fmaxf(bf_hi(b4[e0]), 8.6736174e-19f);
;                     const float g2 = fmaxf(bf_lo(b4[e0 + 1]), 8.6736174e-19f), g3 = fmaxf(bf_hi(b4[e0 + 1]), 8.6736174e-19f);
;                     return pk4(acc[it][jt][4 * g] * g0, acc[it][jt][4 * g + 1] * g1, acc[it][jt][4 * g + 2] * g2, acc[it][jt][4 * g + 3] * g3); },
;                 [&](int row, int col, u32x4 v) { __builtin_nontemporal_store(v, (u32x4*)(mx + (size_t)(r0 + row) * 1024 + f * 256 + col)); });
	s_lshl_b64 s[12:13], s[12:13], 17
	v_ashrrev_i32_e32 v208, 6, v221
	v_ashrrev_i32_e32 v209, 31, v208
	s_add_u32 s12, s24, s12
	v_lshlrev_b64 v[210:211], 14, v[208:209]
	s_addc_u32 s13, s25, s13
	v_lshlrev_b32_e32 v209, 4, v221
	v_lshl_add_u64 v[210:211], s[12:13], 0, v[210:211]
	v_and_b32_e32 v212, 0x3f0, v209
	v_lshl_add_u64 v[216:217], v[210:211], 0, v[212:213]
	global_load_dwordx4 v[222:225], v[216:217], off
	global_load_dwordx4 v[226:229], v[216:217], off offset:1024
	v_add_co_u32_e32 v214, vcc, s42, v216
	v_lshrrev_b32_e32 v210, 2, v221
	s_nop 0
	v_addc_co_u32_e32 v215, vcc, 0, v217, vcc
	global_load_dwordx4 v[230:233], v[214:215], off offset:-4096
	v_lshrrev_b32_e32 v211, 30, v208
	v_and_b32_e32 v212, 8, v210
	v_add_u32_e32 v210, v208, v211
	v_and_b32_e32 v211, 0x7ffffc, v210
	v_and_b32_e32 v209, 31, v221
	v_sub_u32_e32 v208, v208, v211
	v_lshlrev_b32_e32 v210, 6, v210
	v_lshl_or_b32 v208, v208, 5, v209
	v_add_co_u32_e32 v218, vcc, s40, v216
	v_and_b32_e32 v234, 0xffffff00, v210
	s_nop 0
	v_addc_co_u32_e32 v219, vcc, 0, v217, vcc
	v_mul_lo_u32 v235, v208, s50
	global_load_dwordx4 v[208:211], v[218:219], off offset:1024
	v_add3_u32 v234, 0, v235, v234
	v_add_u32_e32 v212, v234, v212
	v_add_u32_e32 v212, 0x800, v212
	s_lshl_b32 s11, s53, 9
	s_add_u32 s12, s3, s11
	s_mov_b32 s6, 0
	s_addc_u32 s13, s16, 0
	s_waitcnt vmcnt(3)
	v_lshlrev_b32_e32 v234, 16, v222
	v_and_b32_e32 v222, 0xffff0000, v222
	v_lshlrev_b32_e32 v235, 16, v223
	v_and_b32_e32 v223, 0xffff0000, v223
	v_lshlrev_b32_e32 v236, 16, v224
	v_and_b32_e32 v224, 0xffff0000, v224
	v_lshlrev_b32_e32 v237, 16, v225
	v_and_b32_e32 v225, 0xffff0000, v225
	s_waitcnt vmcnt(2)
	v_lshlrev_b32_e32 v238, 16, v226
	v_and_b32_e32 v226, 0xffff0000, v226
	v_lshlrev_b32_e32 v239, 16, v227
	v_and_b32_e32 v227, 0xffff0000, v227
	v_max_f32_e32 v234, v234, v234
	v_max_f32_e32 v241, v222, v222
	v_max_f32_e32 v235, v235, v235
	v_max_f32_e32 v242, v223, v223
	v_max_f32_e32 v236, v236, v236
	v_max_f32_e32 v243, v224, v224
	v_max_f32_e32 v237, v237, v237
	v_max_f32_e32 v244, v225, v225
	v_max_f32_e32 v245, v226, v226
	v_max_f32_e32 v246, v227, v227
	v_max_f32_e32 v222, 0x21800000, v234
	v_max_f32_e32 v223, 0x21800000, v241
	v_max_f32_e32 v224, 0x21800000, v235
	v_max_f32_e32 v225, 0x21800000, v242
	v_max_f32_e32 v226, 0x21800000, v236
	v_max_f32_e32 v227, 0x21800000, v243
	v_max_f32_e32 v234, 0x21800000, v237
	v_max_f32_e32 v235, 0x21800000, v244
	v_pk_mul_f32 v[112:113], v[112:113], v[222:223]
	v_pk_mul_f32 v[114:115], v[114:115], v[224:225]
	v_pk_mul_f32 v[116:117], v[116:117], v[226:227]
	v_pk_mul_f32 v[118:119], v[118:119], v[234:235]
	v_lshlrev_b32_e32 v240, 16, v228
	v_cvt_pk_bf16_f32 v112, v112, v113
	v_cvt_pk_bf16_f32 v113, v114, v115
	v_cvt_pk_bf16_f32 v114, v116, v117
	v_cvt_pk_bf16_f32 v115, v118, v119
	ds_write2_b64 v212, v[112:113], v[114:115] offset1:2
	v_max_f32_e32 v112, v240, v240
	v_max_f32_e32 v118, 0x21800000, v112
	v_and_b32_e32 v112, 0xffff0000, v228
	v_max_f32_e32 v238, v238, v238
	v_max_f32_e32 v112, v112, v112
	v_max_f32_e32 v236, 0x21800000, v238
	v_max_f32_e32 v237, 0x21800000, v245
	v_max_f32_e32 v119, 0x21800000, v112
	v_lshlrev_b32_e32 v112, 16, v229
	v_pk_mul_f32 v[120:121], v[120:121], v[236:237]
	v_max_f32_e32 v112, v112, v112
	v_cvt_pk_bf16_f32 v116, v120, v121
	v_max_f32_e32 v120, 0x21800000, v112
	v_and_b32_e32 v112, 0xffff0000, v229
	v_max_f32_e32 v121, v112, v112
	global_load_dwordx4 v[112:115], v[214:215], off
	v_max_f32_e32 v239, v239, v239
	v_max_f32_e32 v238, 0x21800000, v239
	v_max_f32_e32 v239, 0x21800000, v246
	v_max_f32_e32 v121, 0x21800000, v121
	v_pk_mul_f32 v[122:123], v[122:123], v[238:239]
	v_pk_mul_f32 v[118:119], v[124:125], v[118:119]
	v_pk_mul_f32 v[120:121], v[126:127], v[120:121]
	v_cvt_pk_bf16_f32 v117, v122, v123
	v_cvt_pk_bf16_f32 v118, v118, v119
	v_cvt_pk_bf16_f32 v119, v120, v121
	ds_write2_b64 v212, v[116:117], v[118:119] offset0:4 offset1:6
	s_waitcnt vmcnt(2)
	v_lshlrev_b32_e32 v116, 16, v230
	v_and_b32_e32 v117, 0xffff0000, v230
	v_lshlrev_b32_e32 v118, 16, v231
	v_and_b32_e32 v119, 0xffff0000, v231
	v_max_f32_e32 v116, v116, v116
	v_max_f32_e32 v117, v117, v117
	v_max_f32_e32 v118, v118, v118
	v_max_f32_e32 v119, v119, v119
	v_max_f32_e32 v116, 0x21800000, v116
	v_max_f32_e32 v117, 0x21800000, v117
	v_max_f32_e32 v118, 0x21800000, v118
	v_max_f32_e32 v119, 0x21800000, v119
	v_pk_mul_f32 v[96:97], v[96:97], v[116:117]
	v_pk_mul_f32 v[98:99], v[98:99], v[118:119]
	v_cvt_pk_bf16_f32 v96, v96, v97
	v_cvt_pk_bf16_f32 v97, v98, v99
	v_lshlrev_b32_e32 v98, 16, v232
	v_and_b32_e32 v99, 0xffff0000, v232
	v_lshlrev_b32_e32 v116, 16, v233
	v_and_b32_e32 v121, 0xffff0000, v233
	v_max_f32_e32 v98, v98, v98
	v_max_f32_e32 v99, v99, v99
	v_max_f32_e32 v116, v116, v116
	v_max_f32_e32 v121, v121, v121
	v_max_f32_e32 v98, 0x21800000, v98
	v_max_f32_e32 v99, 0x21800000, v99
	v_max_f32_e32 v120, 0x21800000, v116
	v_max_f32_e32 v121, 0x21800000, v121
	v_pk_mul_f32 v[98:99], v[100:101], v[98:99]
	v_pk_mul_f32 v[100:101], v[102:103], v[120:121]
	v_cvt_pk_bf16_f32 v98, v98, v99
	v_cvt_pk_bf16_f32 v99, v100, v101
	global_load_dwordx4 v[116:119], v[214:215], off offset:1024
	ds_write2_b64 v212, v[96:97], v[98:99] offset0:8 offset1:10
	s_waitcnt vmcnt(2)
; DI u32x2 pk4(float a, float b, float c, float d) { u32x2 r; r.x = pk2(a, b); r.y = pk2(c, d); return r; }
; DI float bf_lo(unsigned u) { return __uint_as_float(u << 16); }
; DI float bf_hi(unsigned u) { return __uint_as_float(u & 0xffff0000u); }
; template <int WI, int WGJ, class GetF, class FinF>
; DI void staged_rows(unsigned char* lds, int tid, GetF get, FinF fin) {
;     ...
;     for (int jt = 0; jt < 2; ++jt) {
;         unsigned char* wrow = lds + (wj * 32 + ln) * RS + (wi * WI * 32 + 4 * h) * 2;
; #pragma unroll
;         for (int it = 0; it < WI; ++it)
; #pragma unroll
;             for (int g = 0; g < 4; ++g) *(u32x2*)(wrow + (it * 32 + 8 * g) * 2) = get(it, jt, g);
;         __syncthreads();
; DI void phase4(const Params& p, unsigned char* smem, int tid) {
;     ...
;                 [&](int it, int jt, int g) { const u32x4 b4 = *(const u32x4*)(gb + ((it * 2 + jt) * 2 + (g >> 1)) * 1024); const int e0 = (g & 1) * 2;
;                     const float g0 = fmaxf(bf_lo(b4[e0]), 8.6736174e-19f), g1 = fmaxf(bf_hi(b4[e0]), 8.6736174e-19f);
;                     const float g2 = fmaxf(bf_lo(b4[e0 + 1]), 8.6736174e-19f), g3 = fmaxf(bf_hi(b4[e0 + 1]), 8.6736174e-19f);
;                     return pk4(acc[it][jt][4 * g] * g0, acc[it][jt][4 * g + 1] * g1, acc[it][jt][4 * g + 2] * g2, acc[it][jt][4 * g + 3] * g3); },
	v_lshlrev_b32_e32 v96, 16, v208
	v_and_b32_e32 v97, 0xffff0000, v208
	v_max_f32_e32 v96, v96, v96
	v_max_f32_e32 v97, v97, v97
	v_max_f32_e32 v96, 0x21800000, v96
	v_max_f32_e32 v97, 0x21800000, v97
	v_pk_mul_f32 v[96:97], v[104:105], v[96:97]
	v_lshlrev_b32_e32 v98, 16, v209
	v_and_b32_e32 v99, 0xffff0000, v209
	v_cvt_pk_bf16_f32 v102, v96, v97
	v_lshlrev_b32_e32 v96, 16, v210
	v_max_f32_e32 v98, v98, v98
	v_max_f32_e32 v99, v99, v99
	v_max_f32_e32 v96, v96, v96
	v_max_f32_e32 v98, 0x21800000, v98
	v_max_f32_e32 v99, 0x21800000, v99
	v_max_f32_e32 v104, 0x21800000, v96
	v_and_b32_e32 v96, 0xffff0000, v210
	v_pk_mul_f32 v[98:99], v[106:107], v[98:99]
	v_max_f32_e32 v105, v96, v96
	v_add_co_u32_e32 v96, vcc, s44, v216
	v_lshlrev_b32_e32 v106, 16, v211
	v_and_b32_e32 v107, 0xffff0000, v211
	v_addc_co_u32_e32 v97, vcc, 0, v217, vcc
	v_max_f32_e32 v106, v106, v106
	v_max_f32_e32 v107, v107, v107
	v_cvt_pk_bf16_f32 v103, v98, v99
	global_load_dwordx4 v[98:101], v[96:97], off
	v_max_f32_e32 v105, 0x21800000, v105
	v_max_f32_e32 v106, 0x21800000, v106
	v_max_f32_e32 v107, 0x21800000, v107
	v_pk_mul_f32 v[104:105], v[108:109], v[104:105]
	v_pk_mul_f32 v[106:107], v[110:111], v[106:107]
	v_cvt_pk_bf16_f32 v104, v104, v105
	v_cvt_pk_bf16_f32 v105, v106, v107
	ds_write2_b64 v212, v[102:103], v[104:105] offset0:12 offset1:14
	s_waitcnt vmcnt(2)
	v_lshlrev_b32_e32 v102, 16, v112
	v_and_b32_e32 v103, 0xffff0000, v112
	v_max_f32_e32 v102, v102, v102
	v_max_f32_e32 v103, v103, v103
	v_max_f32_e32 v102, 0x21800000, v102
	v_max_f32_e32 v103, 0x21800000, v103
	v_lshlrev_b32_e32 v104, 16, v113
	v_and_b32_e32 v105, 0xffff0000, v113
	v_max_f32_e32 v104, v104, v104
	v_max_f32_e32 v105, v105, v105
	v_pk_mul_f32 v[80:81], v[80:81], v[102:103]
	v_max_f32_e32 v104, 0x21800000, v104
	v_max_f32_e32 v105, 0x21800000, v105
	v_cvt_pk_bf16_f32 v102, v80, v81
	v_lshlrev_b32_e32 v80, 16, v114
	v_pk_mul_f32 v[82:83], v[82:83], v[104:105]
	v_max_f32_e32 v80, v80, v80
	v_cvt_pk_bf16_f32 v103, v82, v83
	v_max_f32_e32 v104, 0x21800000, v80
	global_load_dwordx4 v[80:83], v[96:97], off offset:1024
	v_and_b32_e32 v105, 0xffff0000, v114
	v_lshlrev_b32_e32 v106, 16, v115
	v_and_b32_e32 v107, 0xffff0000, v115
	v_max_f32_e32 v105, v105, v105
	v_max_f32_e32 v106, v106, v106
	v_max_f32_e32 v107, v107, v107
	v_max_f32_e32 v105, 0x21800000, v105
	v_max_f32_e32 v106, 0x21800000, v106
	v_max_f32_e32 v107, 0x21800000, v107
	v_pk_mul_f32 v[84:85], v[84:85], v[104:105]
	v_pk_mul_f32 v[86:87], v[86:87], v[106:107]
	v_cvt_pk_bf16_f32 v84, v84, v85
	v_cvt_pk_bf16_f32 v85, v86, v87
	ds_write2_b64 v212, v[102:103], v[84:85] offset0:16 offset1:18
	s_waitcnt vmcnt(2)
	v_lshlrev_b32_e32 v84, 16, v116
	v_and_b32_e32 v85, 0xffff0000, v116
	v_lshlrev_b32_e32 v86, 16, v117
	v_and_b32_e32 v87, 0xffff0000, v117
	v_max_f32_e32 v84, v84, v84
	v_max_f32_e32 v85, v85, v85
	v_max_f32_e32 v86, v86, v86
	v_max_f32_e32 v87, v87, v87
	v_max_f32_e32 v84, 0x21800000, v84
	v_max_f32_e32 v85, 0x21800000, v85
	v_max_f32_e32 v86, 0x21800000, v86
	v_max_f32_e32 v87, 0x21800000, v87
	v_pk_mul_f32 v[84:85], v[88:89], v[84:85]
	v_pk_mul_f32 v[86:87], v[90:91], v[86:87]
	v_cvt_pk_bf16_f32 v84, v84, v85
	v_cvt_pk_bf16_f32 v85, v86, v87
	v_lshlrev_b32_e32 v86, 16, v118
	v_and_b32_e32 v87, 0xffff0000, v118
	v_lshlrev_b32_e32 v88, 16, v119
	v_and_b32_e32 v89, 0xffff0000, v119
	v_max_f32_e32 v86, v86, v86
	v_max_f32_e32 v87, v87, v87
	v_max_f32_e32 v88, v88, v88
	v_max_f32_e32 v89, v89, v89
	v_max_f32_e32 v86, 0x21800000, v86
	v_max_f32_e32 v87, 0x21800000, v87
	v_max_f32_e32 v88, 0x21800000, v88
	v_max_f32_e32 v89, 0x21800000, v89
	v_pk_mul_f32 v[86:87], v[92:93], v[86:87]
	v_pk_mul_f32 v[88:89], v[94:95], v[88:89]
	v_cvt_pk_bf16_f32 v86, v86, v87
	v_cvt_pk_bf16_f32 v87, v88, v89
	ds_write2_b64 v212, v[84:85], v[86:87] offset0:20 offset1:22
	s_waitcnt vmcnt(1)
	v_lshlrev_b32_e32 v84, 16, v98
	v_and_b32_e32 v85, 0xffff0000, v98
	v_lshlrev_b32_e32 v86, 16, v99
	v_and_b32_e32 v87, 0xffff0000, v99
	v_max_f32_e32 v84, v84, v84
	v_max_f32_e32 v85, v85, v85
	v_max_f32_e32 v86, v86, v86
	v_max_f32_e32 v87, v87, v87
	v_max_f32_e32 v84, 0x21800000, v84
	v_max_f32_e32 v85, 0x21800000, v85
	v_max_f32_e32 v86, 0x21800000, v86
	v_max_f32_e32 v87, 0x21800000, v87
	v_pk_mul_f32 v[64:65], v[64:65], v[84:85]
	v_pk_mul_f32 v[66:67], v[66:67], v[86:87]
	v_cvt_pk_bf16_f32 v64, v64, v65
	v_cvt_pk_bf16_f32 v65, v66, v67
	v_lshlrev_b32_e32 v66, 16, v100
	v_and_b32_e32 v67, 0xffff0000, v100
	v_lshlrev_b32_e32 v84, 16, v101
	v_and_b32_e32 v85, 0xffff0000, v101
	v_max_f32_e32 v66, v66, v66
	v_max_f32_e32 v67, v67, v67
	v_max_f32_e32 v84, v84, v84
	v_max_f32_e32 v85, v85, v85
	v_max_f32_e32 v66, 0x21800000, v66
	v_max_f32_e32 v67, 0x21800000, v67
	v_max_f32_e32 v84, 0x21800000, v84
	v_max_f32_e32 v85, 0x21800000, v85
	v_pk_mul_f32 v[66:67], v[68:69], v[66:67]
	v_pk_mul_f32 v[68:69], v[70:71], v[84:85]
	v_cvt_pk_bf16_f32 v66, v66, v67
	v_cvt_pk_bf16_f32 v67, v68, v69
	ds_write2_b64 v212, v[64:65], v[66:67] offset0:24 offset1:26
	s_waitcnt vmcnt(0)
	v_lshlrev_b32_e32 v64, 16, v80
	v_and_b32_e32 v65, 0xffff0000, v80
	v_lshlrev_b32_e32 v66, 16, v81
	v_and_b32_e32 v67, 0xffff0000, v81
	v_max_f32_e32 v64, v64, v64
	v_max_f32_e32 v65, v65, v65
	v_max_f32_e32 v66, v66, v66
	v_max_f32_e32 v67, v67, v67
	v_max_f32_e32 v64, 0x21800000, v64
	v_max_f32_e32 v65, 0x21800000, v65
	v_max_f32_e32 v66, 0x21800000, v66
	v_max_f32_e32 v67, 0x21800000, v67
	v_pk_mul_f32 v[64:65], v[72:73], v[64:65]
	v_pk_mul_f32 v[66:67], v[74:75], v[66:67]
	v_cvt_pk_bf16_f32 v64, v64, v65
	v_cvt_pk_bf16_f32 v65, v66, v67
	v_lshlrev_b32_e32 v66, 16, v82
	v_and_b32_e32 v67, 0xffff0000, v82
	v_lshlrev_b32_e32 v68, 16, v83
	v_and_b32_e32 v69, 0xffff0000, v83
	v_max_f32_e32 v66, v66, v66
	v_max_f32_e32 v67, v67, v67
	v_max_f32_e32 v68, v68, v68
	v_max_f32_e32 v69, v69, v69
	v_max_f32_e32 v66, 0x21800000, v66
	v_max_f32_e32 v67, 0x21800000, v67
	v_max_f32_e32 v68, 0x21800000, v68
	v_max_f32_e32 v69, 0x21800000, v69
	v_pk_mul_f32 v[66:67], v[76:77], v[66:67]
	v_pk_mul_f32 v[68:69], v[78:79], v[68:69]
	v_cvt_pk_bf16_f32 v66, v66, v67
	v_cvt_pk_bf16_f32 v67, v68, v69
	ds_write2_b64 v212, v[64:65], v[66:67] offset0:28 offset1:30
	s_waitcnt lgkmcnt(0)
	s_barrier

; #define G_LOAD(pr, qr, kt_) if (MODE != 1) { _Pragma("unroll") for (int r = 0; r < NP; ++r) pr[r] = *(const u32x4*)(pp + (size_t)(r * 128) * ldp + (kt_) * BK); \
;                               _Pragma("unroll") for (int r = 0; r < NQ; ++r) qr[r] = *(const u32x4*)(qp + (size_t)(r * 128) * ldq + (kt_) * BK); }
; #define G_STORE(pr, qr, so_) { unsigned char* w_ = wP + (so_); \
;                               _Pragma("unroll") for (int r = 0; r < NP; ++r) *(u32x4*)(w_ + r * 128 * LROW) = pr[r]; \
;                               _Pragma("unroll") for (int r = 0; r < NQ; ++r) *(u32x4*)(w_ + BI * LROW + r * 128 * LROW) = qr[r]; }
; #define F_LOAD(fa, fb, so_, ks_) { _Pragma("unroll") for (int it = 0; it < WI; ++it) fa[it] = *(const bf16x8*)(rP + (so_) + it * 32 * LROW + (ks_) * 32); \
;                                   _Pragma("unroll") for (int jt = 0; jt < 2; ++jt) fb[jt] = *(const bf16x8*)(rQ + (so_) + jt * 32 * LROW + (ks_) * 32); }
; #define G_LOAD(pr, qr, kt_) if (MODE != 1) { _Pragma("unroll") for (int r = 0; r < NP; ++r) pr[r] = *(const u32x4*)(pp + (size_t)(r * 128) * ldp + (kt_) * BK); \
;                               _Pragma("unroll") for (int r = 0; r < NQ; ++r) qr[r] = *(const u32x4*)(qp + (size_t)(r * 128) * ldq + (kt_) * BK); }
; #define G_STORE(pr, qr, so_) { unsigned char* w_ = wP + (so_); \
;                               _Pragma("unroll") for (int r = 0; r < NP; ++r) *(u32x4*)(w_ + r * 128 * LROW) = pr[r]; \
;                               _Pragma("unroll") for (int r = 0; r < NQ; ++r) *(u32x4*)(w_ + BI * LROW + r * 128 * LROW) = qr[r]; }
;     ...
;     if (MODE == 1) {
; #pragma unroll
;         for (int r = 0; r < NP; ++r) { p0[r] = *(const u32x4*)(pp + (size_t)(r * 128) * ldp); p1[r] = p0[r]; p2[r] = p0[r]; }
; #pragma unroll
;         for (int r = 0; r < NQ; ++r) { q0[r] = *(const u32x4*)(qp + (size_t)(r * 128) * ldq); q1[r] = q0[r]; q2[r] = q0[r]; }
;     }
;     G_LOAD(p0, q0, 0)
;     G_LOAD(p1, q1, 1)
;     G_LOAD(p2, q2, 2)
;     G_STORE(p0, q0, 0)
;     G_LOAD(p0, q0, 3)
;     G_STORE(p1, q1, STAGE)
;     __syncthreads();
;     F_LOAD(fa0, fb0, 0, 0)
;     int cur = 0, nxt = STAGE, wr = 2 * STAGE;
;     int kt = 0;
; #pragma unroll 1
;     for (; kt + 3 <= nk; kt += 3) {
;         G_HALF(p1, q1, p2, q2, kt)
;         G_HALF(p2, q2, p0, q0, kt + 1)
;         G_HALF(p0, q0, p1, q1, kt + 2)
;     }
.LBB0_1060:
	s_waitcnt lgkmcnt(1)
	s_nop 0
	v_mfma_f32_32x32x16_bf16 v[112:127], v[180:183], v[160:163], v[112:127]
	ds_read_b128 v[218:221], v200 offset:22560
	s_waitcnt vmcnt(7)
	ds_write_b128 v205, v[156:159]
	s_waitcnt lgkmcnt(2)
	v_mfma_f32_32x32x16_bf16 v[48:63], v[180:183], v[164:167], v[48:63]
	global_load_dwordx4 v[180:183], v250, s[98:99] offset:256
	ds_read_b128 v[156:159], v198 offset:2080
	v_mfma_f32_32x32x16_bf16 v[96:111], v[176:179], v[160:163], v[96:111]
	ds_read_b128 v[222:225], v200 offset:25120
	s_waitcnt vmcnt(6)
	ds_write_b128 v204, v[152:155]
	v_mfma_f32_32x32x16_bf16 v[32:47], v[176:179], v[164:167], v[32:47]
	global_load_dwordx4 v[176:179], v251, s[98:99] offset:256
	ds_read_b128 v[152:155], v198 offset:4640
	v_mfma_f32_32x32x16_bf16 v[80:95], v[172:175], v[160:163], v[80:95]
	s_waitcnt vmcnt(5)
	ds_write_b128 v201, v[148:151]
	v_mfma_f32_32x32x16_bf16 v[16:31], v[172:175], v[164:167], v[16:31]
	global_load_dwordx4 v[172:175], v250, s[100:101] offset:256
	ds_read_b128 v[148:151], v198 offset:7200
	v_mfma_f32_32x32x16_bf16 v[64:79], v[168:171], v[160:163], v[64:79]
	s_waitcnt vmcnt(4)
	ds_write_b128 v203, v[144:147]
	v_mfma_f32_32x32x16_bf16 v[0:15], v[168:171], v[164:167], v[0:15]
	global_load_dwordx4 v[160:163], v251, s[100:101] offset:256
	ds_read_b128 v[144:147], v198 offset:9760
	s_waitcnt lgkmcnt(7)
	v_mfma_f32_32x32x16_bf16 v[112:127], v[156:159], v[218:221], v[112:127]
	ds_read_b128 v[164:167], v200 offset:63488
	s_waitcnt lgkmcnt(7)
	v_mfma_f32_32x32x16_bf16 v[48:63], v[156:159], v[222:225], v[48:63]
	ds_read_b128 v[156:159], v198 offset:43008
	s_waitcnt lgkmcnt(6)
	v_mfma_f32_32x32x16_bf16 v[96:111], v[152:155], v[218:221], v[96:111]
	ds_read_b128 v[168:171], v199 offset:43520
	v_mfma_f32_32x32x16_bf16 v[32:47], v[152:155], v[222:225], v[32:47]
	ds_read_b128 v[152:155], v198 offset:45568
	s_waitcnt lgkmcnt(6)
	v_mfma_f32_32x32x16_bf16 v[80:95], v[148:151], v[218:221], v[80:95]
	v_mfma_f32_32x32x16_bf16 v[16:31], v[148:151], v[222:225], v[16:31]
	ds_read_b128 v[148:151], v198 offset:48128
	s_waitcnt lgkmcnt(5)
	v_mfma_f32_32x32x16_bf16 v[64:79], v[144:147], v[218:221], v[64:79]
	v_mfma_f32_32x32x16_bf16 v[0:15], v[144:147], v[222:225], v[0:15]
	ds_read_b128 v[144:147], v198 offset:50688
	s_barrier
	s_waitcnt lgkmcnt(4)
	v_mfma_f32_32x32x16_bf16 v[112:127], v[156:159], v[164:167], v[112:127]
	ds_read_b128 v[218:221], v200 offset:63520
	ds_write_b128 v197, v[140:143] offset:2048
	s_waitcnt lgkmcnt(5)
	v_mfma_f32_32x32x16_bf16 v[48:63], v[156:159], v[168:171], v[48:63]
	global_load_dwordx4 v[156:159], v250, s[98:99] offset:320
	ds_read_b128 v[140:143], v198 offset:43040
	s_waitcnt lgkmcnt(5)
	v_mfma_f32_32x32x16_bf16 v[96:111], v[152:155], v[164:167], v[96:111]
	ds_read_b128 v[222:225], v199 offset:43552
	ds_write_b128 v197, v[136:139] offset:12288
	v_mfma_f32_32x32x16_bf16 v[32:47], v[152:155], v[168:171], v[32:47]
	global_load_dwordx4 v[152:155], v251, s[98:99] offset:320
	ds_read_b128 v[136:139], v198 offset:45600
	s_waitcnt lgkmcnt(7)
	v_mfma_f32_32x32x16_bf16 v[80:95], v[148:151], v[164:167], v[80:95]
	ds_write_b128 v197, v[132:135] offset:22528
	v_mfma_f32_32x32x16_bf16 v[16:31], v[148:151], v[168:171], v[16:31]
	global_load_dwordx4 v[148:151], v250, s[100:101] offset:320
	ds_read_b128 v[132:135], v198 offset:48160
	s_waitcnt lgkmcnt(8)
	v_mfma_f32_32x32x16_bf16 v[64:79], v[144:147], v[164:167], v[64:79]
	s_waitcnt vmcnt(7)
	ds_write_b128 v197, v[128:131] offset:32768
	v_mfma_f32_32x32x16_bf16 v[0:15], v[144:147], v[168:171], v[0:15]
	global_load_dwordx4 v[144:147], v251, s[100:101] offset:320
	ds_read_b128 v[128:131], v198 offset:50720
	s_waitcnt lgkmcnt(7)
	v_mfma_f32_32x32x16_bf16 v[112:127], v[140:143], v[218:221], v[112:127]
	ds_read_b128 v[164:167], v207
	s_waitcnt lgkmcnt(7)
	v_mfma_f32_32x32x16_bf16 v[48:63], v[140:143], v[222:225], v[48:63]
	ds_read_b128 v[140:143], v206
	s_waitcnt lgkmcnt(6)
	v_mfma_f32_32x32x16_bf16 v[96:111], v[136:139], v[218:221], v[96:111]
	ds_read_b128 v[168:171], v208
	v_mfma_f32_32x32x16_bf16 v[32:47], v[136:139], v[222:225], v[32:47]
	ds_read_b128 v[136:139], v209
	s_waitcnt lgkmcnt(6)
	v_mfma_f32_32x32x16_bf16 v[80:95], v[132:135], v[218:221], v[80:95]
	v_mfma_f32_32x32x16_bf16 v[16:31], v[132:135], v[222:225], v[16:31]
	ds_read_b128 v[132:135], v210
	s_waitcnt lgkmcnt(5)
	v_mfma_f32_32x32x16_bf16 v[64:79], v[128:131], v[218:221], v[64:79]
	v_mfma_f32_32x32x16_bf16 v[0:15], v[128:131], v[222:225], v[0:15]
	ds_read_b128 v[128:131], v211
	s_barrier
; #define G_LOAD(pr, qr, kt_) if (MODE != 1) { _Pragma("unroll") for (int r = 0; r < NP; ++r) pr[r] = *(const u32x4*)(pp + (size_t)(r * 128) * ldp + (kt_) * BK); \
;                               _Pragma("unroll") for (int r = 0; r < NQ; ++r) qr[r] = *(const u32x4*)(qp + (size_t)(r * 128) * ldq + (kt_) * BK); }
; #define G_STORE(pr, qr, so_) { unsigned char* w_ = wP + (so_); \
;                               _Pragma("unroll") for (int r = 0; r < NP; ++r) *(u32x4*)(w_ + r * 128 * LROW) = pr[r]; \
;                               _Pragma("unroll") for (int r = 0; r < NQ; ++r) *(u32x4*)(w_ + BI * LROW + r * 128 * LROW) = qr[r]; }
; #define F_LOAD(fa, fb, so_, ks_) { _Pragma("unroll") for (int it = 0; it < WI; ++it) fa[it] = *(const bf16x8*)(rP + (so_) + it * 32 * LROW + (ks_) * 32); \
;                                   _Pragma("unroll") for (int jt = 0; jt < 2; ++jt) fb[jt] = *(const bf16x8*)(rQ + (so_) + jt * 32 * LROW + (ks_) * 32); }
; #define G_LOAD(pr, qr, kt_) if (MODE != 1) { _Pragma("unroll") for (int r = 0; r < NP; ++r) pr[r] = *(const u32x4*)(pp + (size_t)(r * 128) * ldp + (kt_) * BK); \
;                               _Pragma("unroll") for (int r = 0; r < NQ; ++r) qr[r] = *(const u32x4*)(qp + (size_t)(r * 128) * ldq + (kt_) * BK); }
;     ...
;     if (MODE == 1) {
; #pragma unroll
;         for (int r = 0; r < NP; ++r) { p0[r] = *(const u32x4*)(pp + (size_t)(r * 128) * ldp); p1[r] = p0[r]; p2[r] = p0[r]; }
; #pragma unroll
;         for (int r = 0; r < NQ; ++r) { q0[r] = *(const u32x4*)(qp + (size_t)(r * 128) * ldq); q1[r] = q0[r]; q2[r] = q0[r]; }
;     }
;     G_LOAD(p0, q0, 0)
;     G_LOAD(p1, q1, 1)
;     G_LOAD(p2, q2, 2)
;     G_STORE(p0, q0, 0)
;     G_LOAD(p0, q0, 3)
;     G_STORE(p1, q1, STAGE)
;     __syncthreads();
;     F_LOAD(fa0, fb0, 0, 0)
;     int cur = 0, nxt = STAGE, wr = 2 * STAGE;
;     int kt = 0;
; #pragma unroll 1
;     for (; kt + 3 <= nk; kt += 3) {
;         G_HALF(p1, q1, p2, q2, kt)
;         G_HALF(p2, q2, p0, q0, kt + 1)
;         G_HALF(p0, q0, p1, q1, kt + 2)
;     }
;     if (kt < nk) G_HALF(p1, q1, p2, q2, kt)
;     if (kt + 1 < nk) G_HALF(p2, q2, p0, q0, kt + 1)
	s_waitcnt lgkmcnt(4)
	v_mfma_f32_32x32x16_bf16 v[112:127], v[140:143], v[164:167], v[112:127]
	ds_read_b128 v[218:221], v212
	s_waitcnt vmcnt(7)
	ds_write_b128 v197, v[180:183] offset:43008
	s_waitcnt lgkmcnt(5)
	v_mfma_f32_32x32x16_bf16 v[48:63], v[140:143], v[168:171], v[48:63]
	global_load_dwordx4 v[140:143], v250, s[98:99] offset:384
	ds_read_b128 v[180:183], v213
	s_waitcnt lgkmcnt(5)
	v_mfma_f32_32x32x16_bf16 v[96:111], v[136:139], v[164:167], v[96:111]
	ds_read_b128 v[222:225], v214
	s_waitcnt vmcnt(7)
	ds_write_b128 v197, v[176:179] offset:53248
	v_mfma_f32_32x32x16_bf16 v[32:47], v[136:139], v[168:171], v[32:47]
	ds_read_b128 v[176:179], v215
	global_load_dwordx4 v[136:139], v251, s[98:99] offset:384
	s_waitcnt lgkmcnt(7)
	v_mfma_f32_32x32x16_bf16 v[80:95], v[132:135], v[164:167], v[80:95]
	s_waitcnt vmcnt(7)
	ds_write_b128 v197, v[172:175] offset:63488
	v_mfma_f32_32x32x16_bf16 v[16:31], v[132:135], v[168:171], v[16:31]
	global_load_dwordx4 v[132:135], v250, s[100:101] offset:384
	ds_read_b128 v[172:175], v216
	s_waitcnt lgkmcnt(8)
	v_mfma_f32_32x32x16_bf16 v[64:79], v[128:131], v[164:167], v[64:79]
	s_waitcnt vmcnt(7)
	ds_write_b128 v202, v[160:163]
	v_mfma_f32_32x32x16_bf16 v[0:15], v[128:131], v[168:171], v[0:15]
	ds_read_b128 v[168:171], v217
	global_load_dwordx4 v[128:131], v251, s[100:101] offset:384
	s_waitcnt lgkmcnt(7)
	v_mfma_f32_32x32x16_bf16 v[112:127], v[180:183], v[218:221], v[112:127]
	ds_read_b128 v[160:163], v200 offset:22528
	s_waitcnt lgkmcnt(7)
	v_mfma_f32_32x32x16_bf16 v[48:63], v[180:183], v[222:225], v[48:63]
	ds_read_b128 v[180:183], v198 offset:2048
	s_waitcnt lgkmcnt(6)
	v_mfma_f32_32x32x16_bf16 v[96:111], v[176:179], v[218:221], v[96:111]
	ds_read_b128 v[164:167], v200 offset:25088
	v_mfma_f32_32x32x16_bf16 v[32:47], v[176:179], v[222:225], v[32:47]
	ds_read_b128 v[176:179], v198 offset:4608
	s_waitcnt lgkmcnt(6)
	v_mfma_f32_32x32x16_bf16 v[80:95], v[172:175], v[218:221], v[80:95]
	v_mfma_f32_32x32x16_bf16 v[16:31], v[172:175], v[222:225], v[16:31]
	ds_read_b128 v[172:175], v198 offset:7168
	s_waitcnt lgkmcnt(5)
	v_mfma_f32_32x32x16_bf16 v[64:79], v[168:171], v[218:221], v[64:79]
	v_mfma_f32_32x32x16_bf16 v[0:15], v[168:171], v[222:225], v[0:15]
	ds_read_b128 v[168:171], v198 offset:9728
	s_add_i32 s5, s5, 3
	v_add_u32_e32 v250, 0xc0, v250
	s_cmp_lt_u32 s5, 30
	v_add_u32_e32 v251, 0xc0, v251
	s_waitcnt lgkmcnt(0)
	s_barrier
	s_cbranch_scc1 .LBB0_1060
	v_mfma_f32_32x32x16_bf16 v[112:127], v[180:183], v[160:163], v[112:127]
	ds_read_b128 v[186:189], v200 offset:22560
	s_waitcnt vmcnt(7)
	ds_write_b128 v205, v[156:159]
	v_mfma_f32_32x32x16_bf16 v[48:63], v[180:183], v[164:167], v[48:63]
	ds_read_b128 v[156:159], v198 offset:2080
	v_mfma_f32_32x32x16_bf16 v[96:111], v[176:179], v[160:163], v[96:111]
	ds_read_b128 v[180:183], v200 offset:25120
	s_waitcnt vmcnt(6)
	ds_write_b128 v204, v[152:155]
	v_mfma_f32_32x32x16_bf16 v[32:47], v[176:179], v[164:167], v[32:47]
	ds_read_b128 v[152:155], v198 offset:4640
	v_mfma_f32_32x32x16_bf16 v[80:95], v[172:175], v[160:163], v[80:95]
	s_waitcnt vmcnt(5)
	ds_write_b128 v201, v[148:151]
	v_mfma_f32_32x32x16_bf16 v[16:31], v[172:175], v[164:167], v[16:31]
	ds_read_b128 v[148:151], v198 offset:7200
	v_mfma_f32_32x32x16_bf16 v[64:79], v[168:171], v[160:163], v[64:79]
	s_waitcnt vmcnt(4)
	ds_write_b128 v203, v[144:147]
	v_mfma_f32_32x32x16_bf16 v[0:15], v[168:171], v[164:167], v[0:15]
	ds_read_b128 v[144:147], v198 offset:9760
	s_waitcnt lgkmcnt(7)
	v_mfma_f32_32x32x16_bf16 v[112:127], v[156:159], v[186:189], v[112:127]
	ds_read_b128 v[160:163], v200 offset:63488
	s_waitcnt lgkmcnt(7)
	v_mfma_f32_32x32x16_bf16 v[48:63], v[156:159], v[180:183], v[48:63]
	ds_read_b128 v[156:159], v198 offset:43008
	s_waitcnt lgkmcnt(6)
	v_mfma_f32_32x32x16_bf16 v[96:111], v[152:155], v[186:189], v[96:111]
	ds_read_b128 v[164:167], v199 offset:43520
	v_mfma_f32_32x32x16_bf16 v[32:47], v[152:155], v[180:183], v[32:47]
	ds_read_b128 v[152:155], v198 offset:45568
	s_waitcnt lgkmcnt(6)
	v_mfma_f32_32x32x16_bf16 v[80:95], v[148:151], v[186:189], v[80:95]
	v_mfma_f32_32x32x16_bf16 v[16:31], v[148:151], v[180:183], v[16:31]
	ds_read_b128 v[148:151], v198 offset:48128
	s_waitcnt lgkmcnt(5)
	v_mfma_f32_32x32x16_bf16 v[64:79], v[144:147], v[186:189], v[64:79]
	v_mfma_f32_32x32x16_bf16 v[0:15], v[144:147], v[180:183], v[0:15]
	ds_read_b128 v[144:147], v198 offset:50688
	s_waitcnt lgkmcnt(0)
	s_barrier
; #define G_HALF(pl, ql, ps, qs, kt_) { const int k4_ = min((kt_) + 4, nk - 1); \
;         SB G_LOAD(pl, ql, k4_) F_LOAD(fa1, fb1, cur, 1) SB G_MFMA(fa0, fb0) SB G_STORE(ps, qs, wr) F_LOAD(fa0, fb0, nxt, 0) SB G_MFMA(fa1, fb1) SB \
;         __syncthreads(); { const int t_ = cur; cur = nxt; nxt = wr; wr = t_; } }
; #define G_HALF(pl, ql, ps, qs, kt_) { const int k4_ = min((kt_) + 4, nk - 1); \
;         SB R_BURST1(fb0, fb1, cur, 1, pl, ql, k4_, ps, qs, wr) R_BURST2(fb1, fb0, nxt, 0, ps, qs, wr) \
;         __syncthreads(); { const int t_ = cur; cur = nxt; nxt = wr; wr = t_; } }
; #define G_HALF(pl, ql, ps, qs, kt_) { const int k4_ = min((kt_) + 4, nk - 1); \
;         SB R_BURST1(fb0, fb1, cur, 1, pl, ql, k4_, ps, qs, wr) R_BURST2(fb1, fb0, nxt, 0, ps, qs, wr) \
;         __syncthreads(); { const int t_ = cur; cur = nxt; nxt = wr; wr = t_; } }
;     ...
;     if (kt < nk) G_HALF(p1, q1, p2, q2, kt)
;     if (kt + 1 < nk) G_HALF(p2, q2, p0, q0, kt + 1)
; DI void phase5(const Params& p, unsigned char* smem, int tid, bool coop) {
;     ...
; #pragma unroll
;         for (int jt = 0; jt < 2; ++jt) {
;             const int tr = tt * 256 + wj * 64 + jt * 32 + ln;
;             float sq = 0.f;
; #pragma unroll
;             for (int it = 0; it < 4; ++it)
; #pragma unroll
;                 for (int r = 0; r < 16; ++r) sq += acc[it][jt][r] * acc[it][jt][r];
;             { const auto sw = __builtin_amdgcn_permlane32_swap(__float_as_uint(sq), __float_as_uint(sq), false, false);
;               sq = __uint_as_float(sw[0]) + __uint_as_float(sw[1]); }
;             if (h == 0) atomicAdd(ssq + tr, sq);
;         }
	v_mfma_f32_32x32x16_bf16 v[112:127], v[156:159], v[160:163], v[112:127]
	ds_read_b128 v[168:171], v200 offset:63520
	s_waitcnt vmcnt(3)
	ds_write_b128 v197, v[140:143] offset:2048
	v_mfma_f32_32x32x16_bf16 v[48:63], v[156:159], v[164:167], v[48:63]
	ds_read_b128 v[140:143], v198 offset:43040
	v_mfma_f32_32x32x16_bf16 v[96:111], v[152:155], v[160:163], v[96:111]
	ds_read_b128 v[156:159], v199 offset:43552
	s_waitcnt vmcnt(2)
	ds_write_b128 v197, v[136:139] offset:12288
	v_mfma_f32_32x32x16_bf16 v[32:47], v[152:155], v[164:167], v[32:47]
	ds_read_b128 v[136:139], v198 offset:45600
	v_mfma_f32_32x32x16_bf16 v[80:95], v[148:151], v[160:163], v[80:95]
	s_waitcnt vmcnt(1)
	ds_write_b128 v197, v[132:135] offset:22528
	v_mfma_f32_32x32x16_bf16 v[16:31], v[148:151], v[164:167], v[16:31]
	ds_read_b128 v[132:135], v198 offset:48160
	v_mfma_f32_32x32x16_bf16 v[64:79], v[144:147], v[160:163], v[64:79]
	s_waitcnt vmcnt(0)
	ds_write_b128 v197, v[128:131] offset:32768
	v_mfma_f32_32x32x16_bf16 v[0:15], v[144:147], v[164:167], v[0:15]
	ds_read_b128 v[128:131], v198 offset:50720
	s_waitcnt lgkmcnt(7)
	v_mfma_f32_32x32x16_bf16 v[112:127], v[140:143], v[168:171], v[112:127]
	s_waitcnt lgkmcnt(6)
	v_mfma_f32_32x32x16_bf16 v[48:63], v[140:143], v[156:159], v[48:63]
	s_waitcnt lgkmcnt(4)
	v_mfma_f32_32x32x16_bf16 v[96:111], v[136:139], v[168:171], v[96:111]
	v_mfma_f32_32x32x16_bf16 v[32:47], v[136:139], v[156:159], v[32:47]
	s_waitcnt lgkmcnt(2)
	v_mfma_f32_32x32x16_bf16 v[80:95], v[132:135], v[168:171], v[80:95]
	v_mfma_f32_32x32x16_bf16 v[16:31], v[132:135], v[156:159], v[16:31]
	s_waitcnt lgkmcnt(0)
	v_mfma_f32_32x32x16_bf16 v[64:79], v[128:131], v[168:171], v[64:79]
	v_mfma_f32_32x32x16_bf16 v[0:15], v[128:131], v[156:159], v[0:15]
	v_readfirstlane_b32 s98, v194
	v_ashrrev_i32_e32 v252, 8, v194
	v_bfe_u32 v253, v194, 5, 1
	v_lshlrev_b32_e32 v252, 9, v252
	v_lshl_add_u32 v252, v253, 4, v252
	s_lshl_b32 s99, s53, 10
	s_add_u32 s36, s8, s99
	s_addc_u32 s37, s9, 0
	s_add_u32 s100, s26, s99
	s_addc_u32 s101, s27, 0
	global_load_dwordx4 v[146:149], v252, s[36:37]
	global_load_dwordx4 v[150:153], v252, s[36:37] offset:32
	global_load_dwordx4 v[154:157], v252, s[36:37] offset:64
	global_load_dwordx4 v[158:161], v252, s[36:37] offset:96
	global_load_dwordx4 v[162:165], v252, s[36:37] offset:128
	global_load_dwordx4 v[166:169], v252, s[36:37] offset:160
	global_load_dwordx4 v[170:173], v252, s[36:37] offset:192
	global_load_dwordx4 v[174:177], v252, s[36:37] offset:224
	global_load_dwordx4 v[178:181], v252, s[36:37] offset:256
	global_load_dwordx4 v[186:189], v252, s[36:37] offset:288
	global_load_dwordx4 v[190:193], v252, s[36:37] offset:320
	global_load_dwordx4 v[198:201], v252, s[36:37] offset:352
	global_load_dwordx4 v[202:205], v252, s[36:37] offset:384
	global_load_dwordx4 v[206:209], v252, s[36:37] offset:416
	global_load_dwordx4 v[210:213], v252, s[36:37] offset:448
	global_load_dwordx4 v[214:217], v252, s[36:37] offset:480
	v_lshrrev_b32_e32 v254, 7, v194
	v_lshlrev_b32_e32 v254, 18, v254
	v_bfe_u32 v253, v194, 6, 1
	v_lshl_add_u32 v254, v253, 16, v254
	v_and_b32_e32 v253, 63, v194
	v_lshl_add_u32 v254, v253, 4, v254
	s_lshl_b32 s99, s30, 12
	v_add_u32_e32 v254, s99, v254
	v_lshrrev_b32_e32 v246, 6, v194
	v_mul_u32_u24_e32 v246, 0x2100, v246
	v_lshl_add_u32 v246, v253, 3, v246
	s_nop 0
	v_mul_f32_e32 v128, v113, v113
	v_fmac_f32_e32 v128, v112, v112
	v_fmac_f32_e32 v128, v114, v114
	v_fmac_f32_e32 v128, v115, v115
	v_fmac_f32_e32 v128, v116, v116
	v_fmac_f32_e32 v128, v117, v117
	v_fmac_f32_e32 v128, v118, v118
	v_fmac_f32_e32 v128, v119, v119
	v_fmac_f32_e32 v128, v120, v120
	v_fmac_f32_e32 v128, v121, v121
	v_fmac_f32_e32 v128, v122, v122
	v_fmac_f32_e32 v128, v123, v123
	v_fmac_f32_e32 v128, v124, v124
	v_fmac_f32_e32 v128, v125, v125
	v_fmac_f32_e32 v128, v126, v126
	v_fmac_f32_e32 v128, v127, v127
	v_fmac_f32_e32 v128, v96, v96
	v_fmac_f32_e32 v128, v97, v97
	v_fmac_f32_e32 v128, v98, v98
	v_fmac_f32_e32 v128, v99, v99
	v_fmac_f32_e32 v128, v100, v100
	v_fmac_f32_e32 v128, v101, v101
	v_fmac_f32_e32 v128, v102, v102
	v_fmac_f32_e32 v128, v103, v103
	v_fmac_f32_e32 v128, v104, v104
	v_fmac_f32_e32 v128, v105, v105
	v_fmac_f32_e32 v128, v106, v106
	v_fmac_f32_e32 v128, v107, v107
	v_fmac_f32_e32 v128, v108, v108
	v_fmac_f32_e32 v128, v109, v109
	v_fmac_f32_e32 v128, v110, v110
	v_fmac_f32_e32 v128, v111, v111
	v_fmac_f32_e32 v128, v80, v80
	v_fmac_f32_e32 v128, v81, v81
	v_fmac_f32_e32 v128, v82, v82
	v_fmac_f32_e32 v128, v83, v83
	v_fmac_f32_e32 v128, v84, v84
	v_fmac_f32_e32 v128, v85, v85
	v_fmac_f32_e32 v128, v86, v86
	v_fmac_f32_e32 v128, v87, v87
	v_fmac_f32_e32 v128, v88, v88
	v_fmac_f32_e32 v128, v89, v89
	v_fmac_f32_e32 v128, v90, v90
	v_fmac_f32_e32 v128, v91, v91
	v_fmac_f32_e32 v128, v92, v92
	v_fmac_f32_e32 v128, v93, v93
	v_fmac_f32_e32 v128, v94, v94
	v_fmac_f32_e32 v128, v95, v95
	v_fmac_f32_e32 v128, v64, v64
	v_fmac_f32_e32 v128, v65, v65
	v_fmac_f32_e32 v128, v66, v66
	v_fmac_f32_e32 v128, v67, v67
	v_fmac_f32_e32 v128, v68, v68
	v_fmac_f32_e32 v128, v69, v69
	v_fmac_f32_e32 v128, v70, v70
	v_fmac_f32_e32 v128, v71, v71
	v_fmac_f32_e32 v128, v72, v72
	v_fmac_f32_e32 v128, v73, v73
	v_fmac_f32_e32 v128, v74, v74
	v_fmac_f32_e32 v128, v75, v75
	v_fmac_f32_e32 v128, v76, v76
	v_fmac_f32_e32 v128, v77, v77
	v_mov_b32_e32 v142, v194
	v_fmac_f32_e32 v128, v78, v78
	s_barrier
	v_fmac_f32_e32 v128, v79, v79
	v_and_b32_e32 v134, 0xc0, v142
	v_and_b32_e32 v143, 31, v142
	v_bfe_u32 v129, v142, 5, 1
	v_or3_b32 v130, v134, s30, v143
	v_mov_b32_e32 v132, v128
	v_cmp_eq_u32_e32 vcc, 0, v129
	s_nop 0
	v_permlane32_swap_b32_e32 v128, v132
	v_ashrrev_i32_e32 v131, 31, v130
	s_and_saveexec_b64 s[6:7], vcc
	s_cbranch_execz .LBB0_1063
	v_add_f32_e32 v128, v128, v132
	v_lshl_add_u64 v[132:133], v[130:131], 2, s[18:19]
	global_atomic_add_f32 v[132:133], v128, off
